# GEMM K-loops: LDS-DMA pieces per load segment 2/4/4/6 instead of 2/6/2/6 (two A pieces staged one segment later)
# speedup vs baseline: 1.0062x; 1.0062x over previous
; #define PG8_STAGE(bufoff, gbase, voff) do { _Pragma("unroll") for (int _i = 0; _i < 2; ++_i) \
;         __builtin_amdgcn_global_load_lds((const unsigned*)((const char*)(gbase) + (voff)[_i]), (PG8_LAS unsigned*)(lds + (bufoff) + ldsw + _i * 8192), 16, 0, 0); } while (0)
; #define PG8_LDA(dst, b, h) do { _Pragma("unroll") for (int m = 0; m < 4; ++m) _Pragma("unroll") for (int k = 0; k < 2; ++k) dst[m][k] = *(const PG8_LAS bf16x8*)(lds + PG8_SA(b, h) + aoff + m * 2048 + k * 1024); } while (0)
; #define PG8_LDB(dst, b, h) do { _Pragma("unroll") for (int n = 0; n < 2; ++n) _Pragma("unroll") for (int k = 0; k < 2; ++k) dst[n][k] = *(const PG8_LAS bf16x8*)(lds + PG8_SB(b, h) + boff + n * 2048 + k * 1024); } while (0)
; #define PG8_MMA(ai, bj, At, Bt) do { __builtin_amdgcn_s_setprio(1); _Pragma("unroll") for (int m = 0; m < 4; ++m) _Pragma("unroll") for (int n = 0; n < 2; ++n) _Pragma("unroll") for (int k = 0; k < 2; ++k) \
;         acc[ai][bj][m][n] = __builtin_amdgcn_mfma_f32_16x16x32_bf16(Bt[n][k], At[m][k], acc[ai][bj][m][n], 0, 0, 0); __builtin_amdgcn_s_setprio(0); } while (0)
; #define PG8_BAR __builtin_amdgcn_s_barrier()
; template <class Epi, class Sched, bool ALIGN_EPI = false, bool SP2 = false>
; __device__ __forceinline__ void gemm_phase(PG8_LAS unsigned char* lds, const Gemm g, const Sched& S, const Epi& E, const int tid_in) {
;     ...
;             PG8_LDB(B0, 0, 0); PG8_LDB(B1, 0, 1); PG8_SCHED; PG8_LDA(At, 0, 0); PG8_STAGE(PG8_SA(1, 1), a1 + hstepA, voffA);
;             PG8_WAIT_V(8); PG8_WAIT_L(0); PG8_BAR; PG8_MMA(0, 0, At, B0); PG8_MMA(0, 1, At, B1); PG8_BAR; PG8_SCHED;
;             PG8_LDA(At, 0, 1); PG8_STAGE(PG8_SB(0, 0), b2, voffB); PG8_STAGE(PG8_SB(0, 1), b2 + hstepB, voffB); PG8_STAGE(PG8_SA(0, 0), a2, voffA);
;             PG8_WAIT_V(8); PG8_WAIT_L(0); PG8_BAR; PG8_MMA(1, 0, At, B0); PG8_MMA(1, 1, At, B1); PG8_BAR; PG8_SCHED;
;             PG8_LDB(B0, 1, 0); PG8_LDB(B1, 1, 1); PG8_SCHED; PG8_LDA(At, 1, 0); PG8_STAGE(PG8_SA(0, 1), a2 + hstepA, voffA);
;             PG8_WAIT_V(8); PG8_WAIT_L(0); PG8_BAR; PG8_MMA(0, 0, At, B0); PG8_MMA(0, 1, At, B1); PG8_BAR; PG8_SCHED;
;             PG8_LDA(At, 1, 1); PG8_STAGE(PG8_SB(1, 0), b3, voffB); PG8_STAGE(PG8_SB(1, 1), b3 + hstepB, voffB); PG8_STAGE(PG8_SA(1, 0), a3, voffA);
;             PG8_WAIT_V(8); PG8_WAIT_L(0); PG8_BAR; PG8_MMA(1, 0, At, B0); PG8_MMA(1, 1, At, B1); PG8_BAR; PG8_SCHED;
.LBB0_145:
	s_add_u32 s28, s22, 0xfffc0080
	s_addc_u32 s29, s23, -1
	s_add_i32 s46, 0, 0x10000
	s_cmp_eq_u32 s72, 12
	s_cselect_b32 s31, s13, s29
	s_cselect_b32 s30, s19, s28
	v_add_u32_e32 v142, s46, v144
	s_cselect_b32 s29, s11, s71
	s_cselect_b32 s28, s60, s70
	s_add_i32 s73, 0, 0x14000
	ds_read_b128 v[154:157], v142
	ds_read_b128 v[158:161], v142 offset:1024
	ds_read_b128 v[162:165], v142 offset:2048
	ds_read_b128 v[166:169], v142 offset:3072
	v_add_u32_e32 v142, s73, v144
	ds_read_b128 v[170:173], v142
	ds_read_b128 v[174:177], v142 offset:1024
	ds_read_b128 v[178:181], v142 offset:2048
	ds_read_b128 v[182:185], v142 offset:3072
	v_lshl_add_u64 v[142:143], s[22:23], 0, v[138:139]
	s_add_i32 m0, s21, 0xc000
	ds_read_b128 v[186:189], v153
	ds_read_b128 v[202:205], v153 offset:1024
	ds_read_b128 v[206:209], v153 offset:2048
	ds_read_b128 v[210:213], v153 offset:3072
	ds_read_b128 v[214:217], v153 offset:4096
	ds_read_b128 v[218:221], v153 offset:5120
	ds_read_b128 v[222:225], v153 offset:6144
	ds_read_b128 v[226:229], v153 offset:7168
	global_load_lds_dwordx4 v[142:143], off
	v_lshl_add_u64 v[142:143], s[22:23], 0, v[140:141]
	s_add_i32 m0, s21, 0xe000
	s_nop 0
	global_load_lds_dwordx4 v[142:143], off
	s_waitcnt vmcnt(8)
	s_waitcnt lgkmcnt(0)
	s_barrier
	s_setprio 1
	s_waitcnt lgkmcnt(0)
	v_mfma_f32_16x16x32_bf16 v[126:129], v[154:157], v[186:189], v[126:129]
	v_mfma_f32_16x16x32_bf16 v[122:125], v[162:165], v[186:189], v[122:125]
	v_mfma_f32_16x16x32_bf16 v[114:117], v[154:157], v[206:209], v[114:117]
	v_mfma_f32_16x16x32_bf16 v[106:109], v[162:165], v[206:209], v[106:109]
	v_mfma_f32_16x16x32_bf16 v[98:101], v[154:157], v[214:217], v[98:101]
	v_mfma_f32_16x16x32_bf16 v[88:91], v[162:165], v[214:217], v[88:91]
	v_mfma_f32_16x16x32_bf16 v[80:83], v[154:157], v[222:225], v[80:83]
	v_mfma_f32_16x16x32_bf16 v[72:75], v[162:165], v[222:225], v[72:75]
	v_mfma_f32_16x16x32_bf16 v[126:129], v[158:161], v[202:205], v[126:129]
	v_mfma_f32_16x16x32_bf16 v[122:125], v[166:169], v[202:205], v[122:125]
	v_mfma_f32_16x16x32_bf16 v[114:117], v[158:161], v[210:213], v[114:117]
	v_mfma_f32_16x16x32_bf16 v[106:109], v[166:169], v[210:213], v[106:109]
	v_mfma_f32_16x16x32_bf16 v[98:101], v[158:161], v[218:221], v[98:101]
	v_mfma_f32_16x16x32_bf16 v[88:91], v[166:169], v[218:221], v[88:91]
	v_mfma_f32_16x16x32_bf16 v[80:83], v[158:161], v[226:229], v[80:83]
	v_mfma_f32_16x16x32_bf16 v[72:75], v[166:169], v[226:229], v[72:75]
	s_setprio 0
	s_setprio 1
	v_mfma_f32_16x16x32_bf16 v[118:121], v[170:173], v[186:189], v[118:121]
	v_mfma_f32_16x16x32_bf16 v[110:113], v[178:181], v[186:189], v[110:113]
	v_mfma_f32_16x16x32_bf16 v[102:105], v[170:173], v[206:209], v[102:105]
	v_mfma_f32_16x16x32_bf16 v[92:95], v[178:181], v[206:209], v[92:95]
	v_mfma_f32_16x16x32_bf16 v[84:87], v[170:173], v[214:217], v[84:87]
	v_mfma_f32_16x16x32_bf16 v[76:79], v[178:181], v[214:217], v[76:79]
	v_mfma_f32_16x16x32_bf16 v[68:71], v[170:173], v[222:225], v[68:71]
	v_mfma_f32_16x16x32_bf16 v[64:67], v[178:181], v[222:225], v[64:67]
	v_mfma_f32_16x16x32_bf16 v[118:121], v[174:177], v[202:205], v[118:121]
	v_mfma_f32_16x16x32_bf16 v[110:113], v[182:185], v[202:205], v[110:113]
	v_mfma_f32_16x16x32_bf16 v[102:105], v[174:177], v[210:213], v[102:105]
	v_mfma_f32_16x16x32_bf16 v[92:95], v[182:185], v[210:213], v[92:95]
	v_mfma_f32_16x16x32_bf16 v[84:87], v[174:177], v[218:221], v[84:87]
	v_mfma_f32_16x16x32_bf16 v[76:79], v[182:185], v[218:221], v[76:79]
	v_mfma_f32_16x16x32_bf16 v[68:71], v[174:177], v[226:229], v[68:71]
	v_mfma_f32_16x16x32_bf16 v[64:67], v[182:185], v[226:229], v[64:67]
	s_setprio 0
	s_barrier
	s_add_i32 s46, s46, s42
	v_lshl_add_u64 v[142:143], s[28:29], 0, v[132:133]
	s_mov_b32 m0, s46
	ds_read_b128 v[186:189], v153 offset:16384
	ds_read_b128 v[202:205], v153 offset:17408
	ds_read_b128 v[206:209], v153 offset:18432
	ds_read_b128 v[210:213], v153 offset:19456
	ds_read_b128 v[214:217], v153 offset:20480
	ds_read_b128 v[218:221], v153 offset:21504
	ds_read_b128 v[222:225], v153 offset:22528
	ds_read_b128 v[226:229], v153 offset:23552
	global_load_lds_dwordx4 v[142:143], off
	s_add_i32 m0, s46, 0x2000
	s_add_u32 s74, s28, 0x40000
	v_lshl_add_u64 v[146:147], s[28:29], 0, v[136:137]
	s_addc_u32 s75, s29, 0
	s_add_i32 s46, s73, s42
	global_load_lds_dwordx4 v[146:147], off
	v_lshl_add_u64 v[148:149], s[74:75], 0, v[132:133]
	s_mov_b32 m0, s46
	global_load_lds_dwordx4 v[148:149], off
	v_lshl_add_u64 v[148:149], s[74:75], 0, v[136:137]
	s_add_i32 m0, s46, 0x2000
	s_nop 0
	global_load_lds_dwordx4 v[148:149], off
	s_waitcnt vmcnt(6)
	s_waitcnt lgkmcnt(0)
	s_barrier
; #define PG8_STAGE(bufoff, gbase, voff) do { _Pragma("unroll") for (int _i = 0; _i < 2; ++_i) \
;         __builtin_amdgcn_global_load_lds((const unsigned*)((const char*)(gbase) + (voff)[_i]), (PG8_LAS unsigned*)(lds + (bufoff) + ldsw + _i * 8192), 16, 0, 0); } while (0)
; #define PG8_LDA(dst, b, h) do { _Pragma("unroll") for (int m = 0; m < 4; ++m) _Pragma("unroll") for (int k = 0; k < 2; ++k) dst[m][k] = *(const PG8_LAS bf16x8*)(lds + PG8_SA(b, h) + aoff + m * 2048 + k * 1024); } while (0)
; #define PG8_LDB(dst, b, h) do { _Pragma("unroll") for (int n = 0; n < 2; ++n) _Pragma("unroll") for (int k = 0; k < 2; ++k) dst[n][k] = *(const PG8_LAS bf16x8*)(lds + PG8_SB(b, h) + boff + n * 2048 + k * 1024); } while (0)
; #define PG8_MMA(ai, bj, At, Bt) do { __builtin_amdgcn_s_setprio(1); _Pragma("unroll") for (int m = 0; m < 4; ++m) _Pragma("unroll") for (int n = 0; n < 2; ++n) _Pragma("unroll") for (int k = 0; k < 2; ++k) \
;         acc[ai][bj][m][n] = __builtin_amdgcn_mfma_f32_16x16x32_bf16(Bt[n][k], At[m][k], acc[ai][bj][m][n], 0, 0, 0); __builtin_amdgcn_s_setprio(0); } while (0)
; #define PG8_BAR __builtin_amdgcn_s_barrier()
; template <class Epi, class Sched, bool ALIGN_EPI = false, bool SP2 = false>
; __device__ __forceinline__ void gemm_phase(PG8_LAS unsigned char* lds, const Gemm g, const Sched& S, const Epi& E, const int tid_in) {
;     ...
;             PG8_LDB(B0, 0, 0); PG8_LDB(B1, 0, 1); PG8_SCHED; PG8_LDA(At, 0, 0); PG8_STAGE(PG8_SA(1, 1), a1 + hstepA, voffA);
;             PG8_WAIT_V(8); PG8_WAIT_L(0); PG8_BAR; PG8_MMA(0, 0, At, B0); PG8_MMA(0, 1, At, B1); PG8_BAR; PG8_SCHED;
;             PG8_LDA(At, 0, 1); PG8_STAGE(PG8_SB(0, 0), b2, voffB); PG8_STAGE(PG8_SB(0, 1), b2 + hstepB, voffB); PG8_STAGE(PG8_SA(0, 0), a2, voffA);
;             PG8_WAIT_V(8); PG8_WAIT_L(0); PG8_BAR; PG8_MMA(1, 0, At, B0); PG8_MMA(1, 1, At, B1); PG8_BAR; PG8_SCHED;
;             PG8_LDB(B0, 1, 0); PG8_LDB(B1, 1, 1); PG8_SCHED; PG8_LDA(At, 1, 0); PG8_STAGE(PG8_SA(0, 1), a2 + hstepA, voffA);
;             PG8_WAIT_V(8); PG8_WAIT_L(0); PG8_BAR; PG8_MMA(0, 0, At, B0); PG8_MMA(0, 1, At, B1); PG8_BAR; PG8_SCHED;
;             PG8_LDA(At, 1, 1); PG8_STAGE(PG8_SB(1, 0), b3, voffB); PG8_STAGE(PG8_SB(1, 1), b3 + hstepB, voffB); PG8_STAGE(PG8_SA(1, 0), a3, voffA);
;             PG8_WAIT_V(8); PG8_WAIT_L(0); PG8_BAR; PG8_MMA(1, 0, At, B0); PG8_MMA(1, 1, At, B1); PG8_BAR; PG8_SCHED;
	s_setprio 1
	s_waitcnt lgkmcnt(0)
	v_mfma_f32_16x16x32_bf16 v[60:63], v[154:157], v[186:189], v[60:63]
	v_mfma_f32_16x16x32_bf16 v[56:59], v[162:165], v[186:189], v[56:59]
	v_mfma_f32_16x16x32_bf16 v[48:51], v[154:157], v[206:209], v[48:51]
	v_mfma_f32_16x16x32_bf16 v[40:43], v[162:165], v[206:209], v[40:43]
	v_mfma_f32_16x16x32_bf16 v[32:35], v[154:157], v[214:217], v[32:35]
	v_mfma_f32_16x16x32_bf16 v[24:27], v[162:165], v[214:217], v[24:27]
	v_mfma_f32_16x16x32_bf16 v[16:19], v[154:157], v[222:225], v[16:19]
	v_mfma_f32_16x16x32_bf16 v[8:11], v[162:165], v[222:225], v[8:11]
	v_mfma_f32_16x16x32_bf16 v[60:63], v[158:161], v[202:205], v[60:63]
	v_mfma_f32_16x16x32_bf16 v[56:59], v[166:169], v[202:205], v[56:59]
	v_mfma_f32_16x16x32_bf16 v[48:51], v[158:161], v[210:213], v[48:51]
	v_mfma_f32_16x16x32_bf16 v[40:43], v[166:169], v[210:213], v[40:43]
	v_mfma_f32_16x16x32_bf16 v[32:35], v[158:161], v[218:221], v[32:35]
	v_mfma_f32_16x16x32_bf16 v[24:27], v[166:169], v[218:221], v[24:27]
	v_mfma_f32_16x16x32_bf16 v[16:19], v[158:161], v[226:229], v[16:19]
	v_mfma_f32_16x16x32_bf16 v[8:11], v[166:169], v[226:229], v[8:11]
	s_setprio 0
	s_setprio 1
	v_mfma_f32_16x16x32_bf16 v[52:55], v[170:173], v[186:189], v[52:55]
	v_mfma_f32_16x16x32_bf16 v[44:47], v[178:181], v[186:189], v[44:47]
	v_mfma_f32_16x16x32_bf16 v[36:39], v[170:173], v[206:209], v[36:39]
	v_mfma_f32_16x16x32_bf16 v[28:31], v[178:181], v[206:209], v[28:31]
	v_mfma_f32_16x16x32_bf16 v[20:23], v[170:173], v[214:217], v[20:23]
	v_mfma_f32_16x16x32_bf16 v[12:15], v[178:181], v[214:217], v[12:15]
	v_mfma_f32_16x16x32_bf16 v[4:7], v[170:173], v[222:225], v[4:7]
	v_mfma_f32_16x16x32_bf16 v[0:3], v[178:181], v[222:225], v[0:3]
	v_mfma_f32_16x16x32_bf16 v[52:55], v[174:177], v[202:205], v[52:55]
	v_mfma_f32_16x16x32_bf16 v[44:47], v[182:185], v[202:205], v[44:47]
	v_mfma_f32_16x16x32_bf16 v[36:39], v[174:177], v[210:213], v[36:39]
	v_mfma_f32_16x16x32_bf16 v[28:31], v[182:185], v[210:213], v[28:31]
	v_mfma_f32_16x16x32_bf16 v[20:23], v[174:177], v[218:221], v[20:23]
	v_mfma_f32_16x16x32_bf16 v[12:15], v[182:185], v[218:221], v[12:15]
	v_mfma_f32_16x16x32_bf16 v[4:7], v[174:177], v[226:229], v[4:7]
	v_mfma_f32_16x16x32_bf16 v[0:3], v[182:185], v[226:229], v[0:3]
	s_setprio 0
	s_barrier
	v_lshl_add_u64 v[148:149], s[30:31], 0, v[130:131]
	v_lshl_add_u64 v[230:231], s[30:31], 0, v[134:135]
	s_mov_b32 m0, s21
	s_nop 0
	global_load_lds_dwordx4 v[148:149], off
	s_mov_b32 m0, s43
	s_nop 0
	global_load_lds_dwordx4 v[230:231], off
	s_add_i32 s46, 0, 0x18000
	s_add_i32 s73, 0, 0x1c000
	v_add_u32_e32 v166, s46, v144
	v_add_u32_e32 v182, s73, v144
	ds_read_b128 v[154:157], v166
	ds_read_b128 v[158:161], v166 offset:1024
	ds_read_b128 v[162:165], v166 offset:2048
	ds_read_b128 v[166:169], v166 offset:3072
	ds_read_b128 v[170:173], v182
	ds_read_b128 v[174:177], v182 offset:1024
	ds_read_b128 v[178:181], v182 offset:2048
	ds_read_b128 v[182:185], v182 offset:3072
	s_add_u32 s30, s30, 0x40000
	s_addc_u32 s31, s31, 0
	s_mov_b32 m0, s44
	v_lshl_add_u64 v[232:233], s[30:31], 0, v[130:131]
	ds_read_b128 v[186:189], v153 offset:32768
	ds_read_b128 v[202:205], v153 offset:33792
	ds_read_b128 v[206:209], v153 offset:34816
	ds_read_b128 v[210:213], v153 offset:35840
	ds_read_b128 v[214:217], v153 offset:36864
	ds_read_b128 v[218:221], v153 offset:37888
	ds_read_b128 v[222:225], v153 offset:38912
	ds_read_b128 v[226:229], v153 offset:39936
	global_load_lds_dwordx4 v[232:233], off
	v_lshl_add_u64 v[232:233], s[30:31], 0, v[134:135]
	s_mov_b32 m0, s45
	s_nop 0
	global_load_lds_dwordx4 v[232:233], off
	s_waitcnt vmcnt(8)
	s_waitcnt lgkmcnt(0)
	s_barrier
	s_setprio 1
	s_waitcnt lgkmcnt(0)
	v_mfma_f32_16x16x32_bf16 v[126:129], v[154:157], v[186:189], v[126:129]
	v_mfma_f32_16x16x32_bf16 v[122:125], v[162:165], v[186:189], v[122:125]
	v_mfma_f32_16x16x32_bf16 v[114:117], v[154:157], v[206:209], v[114:117]
	v_mfma_f32_16x16x32_bf16 v[106:109], v[162:165], v[206:209], v[106:109]
	v_mfma_f32_16x16x32_bf16 v[98:101], v[154:157], v[214:217], v[98:101]
	v_mfma_f32_16x16x32_bf16 v[88:91], v[162:165], v[214:217], v[88:91]
	v_mfma_f32_16x16x32_bf16 v[80:83], v[154:157], v[222:225], v[80:83]
	v_mfma_f32_16x16x32_bf16 v[72:75], v[162:165], v[222:225], v[72:75]
	v_mfma_f32_16x16x32_bf16 v[126:129], v[158:161], v[202:205], v[126:129]
	v_mfma_f32_16x16x32_bf16 v[122:125], v[166:169], v[202:205], v[122:125]
	v_mfma_f32_16x16x32_bf16 v[114:117], v[158:161], v[210:213], v[114:117]
	v_mfma_f32_16x16x32_bf16 v[106:109], v[166:169], v[210:213], v[106:109]
	v_mfma_f32_16x16x32_bf16 v[98:101], v[158:161], v[218:221], v[98:101]
	v_mfma_f32_16x16x32_bf16 v[88:91], v[166:169], v[218:221], v[88:91]
	v_mfma_f32_16x16x32_bf16 v[80:83], v[158:161], v[226:229], v[80:83]
	v_mfma_f32_16x16x32_bf16 v[72:75], v[166:169], v[226:229], v[72:75]
	s_setprio 0
	s_setprio 1
	v_mfma_f32_16x16x32_bf16 v[118:121], v[170:173], v[186:189], v[118:121]
	v_mfma_f32_16x16x32_bf16 v[110:113], v[178:181], v[186:189], v[110:113]
	v_mfma_f32_16x16x32_bf16 v[102:105], v[170:173], v[206:209], v[102:105]
	v_mfma_f32_16x16x32_bf16 v[92:95], v[178:181], v[206:209], v[92:95]
	v_mfma_f32_16x16x32_bf16 v[84:87], v[170:173], v[214:217], v[84:87]
	v_mfma_f32_16x16x32_bf16 v[76:79], v[178:181], v[214:217], v[76:79]
	v_mfma_f32_16x16x32_bf16 v[68:71], v[170:173], v[222:225], v[68:71]
	v_mfma_f32_16x16x32_bf16 v[64:67], v[178:181], v[222:225], v[64:67]
	v_mfma_f32_16x16x32_bf16 v[118:121], v[174:177], v[202:205], v[118:121]
	v_mfma_f32_16x16x32_bf16 v[110:113], v[182:185], v[202:205], v[110:113]
	v_mfma_f32_16x16x32_bf16 v[102:105], v[174:177], v[210:213], v[102:105]
	v_mfma_f32_16x16x32_bf16 v[92:95], v[182:185], v[210:213], v[92:95]
	v_mfma_f32_16x16x32_bf16 v[84:87], v[174:177], v[218:221], v[84:87]
	v_mfma_f32_16x16x32_bf16 v[76:79], v[182:185], v[218:221], v[76:79]
	v_mfma_f32_16x16x32_bf16 v[68:71], v[174:177], v[226:229], v[68:71]
	v_mfma_f32_16x16x32_bf16 v[64:67], v[182:185], v[226:229], v[64:67]
	s_setprio 0
	s_barrier
; #define PG8_STAGE(bufoff, gbase, voff) do { _Pragma("unroll") for (int _i = 0; _i < 2; ++_i) \
;         __builtin_amdgcn_global_load_lds((const unsigned*)((const char*)(gbase) + (voff)[_i]), (PG8_LAS unsigned*)(lds + (bufoff) + ldsw + _i * 8192), 16, 0, 0); } while (0)
; #define PG8_LDA(dst, b, h) do { _Pragma("unroll") for (int m = 0; m < 4; ++m) _Pragma("unroll") for (int k = 0; k < 2; ++k) dst[m][k] = *(const PG8_LAS bf16x8*)(lds + PG8_SA(b, h) + aoff + m * 2048 + k * 1024); } while (0)
; #define PG8_LDB(dst, b, h) do { _Pragma("unroll") for (int n = 0; n < 2; ++n) _Pragma("unroll") for (int k = 0; k < 2; ++k) dst[n][k] = *(const PG8_LAS bf16x8*)(lds + PG8_SB(b, h) + boff + n * 2048 + k * 1024); } while (0)
; #define PG8_MMA(ai, bj, At, Bt) do { __builtin_amdgcn_s_setprio(1); _Pragma("unroll") for (int m = 0; m < 4; ++m) _Pragma("unroll") for (int n = 0; n < 2; ++n) _Pragma("unroll") for (int k = 0; k < 2; ++k) \
;         acc[ai][bj][m][n] = __builtin_amdgcn_mfma_f32_16x16x32_bf16(Bt[n][k], At[m][k], acc[ai][bj][m][n], 0, 0, 0); __builtin_amdgcn_s_setprio(0); } while (0)
; #define PG8_BAR __builtin_amdgcn_s_barrier()
; template <class Epi, class Sched, bool ALIGN_EPI = false, bool SP2 = false>
; __device__ __forceinline__ void gemm_phase(PG8_LAS unsigned char* lds, const Gemm g, const Sched& S, const Epi& E, const int tid_in) {
;     ...
;             PG8_LDB(B0, 0, 0); PG8_LDB(B1, 0, 1); PG8_SCHED; PG8_LDA(At, 0, 0); PG8_STAGE(PG8_SA(1, 1), a1 + hstepA, voffA);
;             PG8_WAIT_V(8); PG8_WAIT_L(0); PG8_BAR; PG8_MMA(0, 0, At, B0); PG8_MMA(0, 1, At, B1); PG8_BAR; PG8_SCHED;
;             PG8_LDA(At, 0, 1); PG8_STAGE(PG8_SB(0, 0), b2, voffB); PG8_STAGE(PG8_SB(0, 1), b2 + hstepB, voffB); PG8_STAGE(PG8_SA(0, 0), a2, voffA);
;             PG8_WAIT_V(8); PG8_WAIT_L(0); PG8_BAR; PG8_MMA(1, 0, At, B0); PG8_MMA(1, 1, At, B1); PG8_BAR; PG8_SCHED;
;             PG8_LDB(B0, 1, 0); PG8_LDB(B1, 1, 1); PG8_SCHED; PG8_LDA(At, 1, 0); PG8_STAGE(PG8_SA(0, 1), a2 + hstepA, voffA);
;             PG8_WAIT_V(8); PG8_WAIT_L(0); PG8_BAR; PG8_MMA(0, 0, At, B0); PG8_MMA(0, 1, At, B1); PG8_BAR; PG8_SCHED;
;             PG8_LDA(At, 1, 1); PG8_STAGE(PG8_SB(1, 0), b3, voffB); PG8_STAGE(PG8_SB(1, 1), b3 + hstepB, voffB); PG8_STAGE(PG8_SA(1, 0), a3, voffA);
;             PG8_WAIT_V(8); PG8_WAIT_L(0); PG8_BAR; PG8_MMA(1, 0, At, B0); PG8_MMA(1, 1, At, B1); PG8_BAR; PG8_SCHED;
	s_add_i32 s30, s46, s42
	v_lshl_add_u64 v[142:143], v[142:143], 0, s[68:69]
	s_mov_b32 m0, s30
	ds_read_b128 v[186:189], v153 offset:49152
	ds_read_b128 v[202:205], v153 offset:50176
	ds_read_b128 v[206:209], v153 offset:51200
	ds_read_b128 v[210:213], v153 offset:52224
	ds_read_b128 v[214:217], v153 offset:53248
	ds_read_b128 v[218:221], v153 offset:54272
	ds_read_b128 v[222:225], v153 offset:55296
	ds_read_b128 v[226:229], v153 offset:56320
	global_load_lds_dwordx4 v[142:143], off
	s_add_i32 m0, s30, 0x2000
	s_add_u32 s28, s28, 0x40080
	v_lshl_add_u64 v[142:143], v[146:147], 0, s[68:69]
	s_addc_u32 s29, s29, 0
	s_add_i32 s30, s73, s42
	global_load_lds_dwordx4 v[142:143], off
	v_lshl_add_u64 v[142:143], s[28:29], 0, v[132:133]
	s_mov_b32 m0, s30
	s_nop 0
	global_load_lds_dwordx4 v[142:143], off
	v_lshl_add_u64 v[142:143], s[28:29], 0, v[136:137]
	s_add_i32 m0, s30, 0x2000
	s_nop 0
	global_load_lds_dwordx4 v[142:143], off
	v_lshl_add_u64 v[142:143], v[148:149], 0, s[68:69]
	s_mov_b32 m0, s52
	s_nop 0
	global_load_lds_dwordx4 v[142:143], off
	v_lshl_add_u64 v[142:143], v[230:231], 0, s[68:69]
	s_mov_b32 m0, s53
	s_nop 0
	global_load_lds_dwordx4 v[142:143], off
	s_waitcnt vmcnt(8)
	s_waitcnt lgkmcnt(0)
	s_barrier
	s_setprio 1
	s_waitcnt lgkmcnt(0)
	v_mfma_f32_16x16x32_bf16 v[60:63], v[154:157], v[186:189], v[60:63]
	v_mfma_f32_16x16x32_bf16 v[56:59], v[162:165], v[186:189], v[56:59]
	v_mfma_f32_16x16x32_bf16 v[48:51], v[154:157], v[206:209], v[48:51]
	v_mfma_f32_16x16x32_bf16 v[40:43], v[162:165], v[206:209], v[40:43]
	v_mfma_f32_16x16x32_bf16 v[32:35], v[154:157], v[214:217], v[32:35]
	v_mfma_f32_16x16x32_bf16 v[24:27], v[162:165], v[214:217], v[24:27]
	v_mfma_f32_16x16x32_bf16 v[16:19], v[154:157], v[222:225], v[16:19]
	v_mfma_f32_16x16x32_bf16 v[8:11], v[162:165], v[222:225], v[8:11]
	v_mfma_f32_16x16x32_bf16 v[60:63], v[158:161], v[202:205], v[60:63]
	v_mfma_f32_16x16x32_bf16 v[56:59], v[166:169], v[202:205], v[56:59]
	v_mfma_f32_16x16x32_bf16 v[48:51], v[158:161], v[210:213], v[48:51]
	v_mfma_f32_16x16x32_bf16 v[40:43], v[166:169], v[210:213], v[40:43]
	v_mfma_f32_16x16x32_bf16 v[32:35], v[158:161], v[218:221], v[32:35]
	v_mfma_f32_16x16x32_bf16 v[24:27], v[166:169], v[218:221], v[24:27]
	v_mfma_f32_16x16x32_bf16 v[16:19], v[158:161], v[226:229], v[16:19]
	v_mfma_f32_16x16x32_bf16 v[8:11], v[166:169], v[226:229], v[8:11]
	s_setprio 0
	s_setprio 1
	v_mfma_f32_16x16x32_bf16 v[52:55], v[170:173], v[186:189], v[52:55]
	v_mfma_f32_16x16x32_bf16 v[44:47], v[178:181], v[186:189], v[44:47]
	v_mfma_f32_16x16x32_bf16 v[36:39], v[170:173], v[206:209], v[36:39]
	v_mfma_f32_16x16x32_bf16 v[28:31], v[178:181], v[206:209], v[28:31]
	v_mfma_f32_16x16x32_bf16 v[20:23], v[170:173], v[214:217], v[20:23]
	v_mfma_f32_16x16x32_bf16 v[12:15], v[178:181], v[214:217], v[12:15]
	v_mfma_f32_16x16x32_bf16 v[4:7], v[170:173], v[222:225], v[4:7]
	v_mfma_f32_16x16x32_bf16 v[0:3], v[178:181], v[222:225], v[0:3]
	v_mfma_f32_16x16x32_bf16 v[52:55], v[174:177], v[202:205], v[52:55]
	v_mfma_f32_16x16x32_bf16 v[44:47], v[182:185], v[202:205], v[44:47]
	v_mfma_f32_16x16x32_bf16 v[36:39], v[174:177], v[210:213], v[36:39]
	v_mfma_f32_16x16x32_bf16 v[28:31], v[182:185], v[210:213], v[28:31]
	v_mfma_f32_16x16x32_bf16 v[20:23], v[174:177], v[218:221], v[20:23]
	v_mfma_f32_16x16x32_bf16 v[12:15], v[182:185], v[218:221], v[12:15]
	v_mfma_f32_16x16x32_bf16 v[4:7], v[174:177], v[226:229], v[4:7]
	v_mfma_f32_16x16x32_bf16 v[0:3], v[182:185], v[226:229], v[0:3]
	s_setprio 0
	s_barrier
	s_add_i32 s72, s72, 2
	s_add_u32 s22, s22, 0x100
	s_addc_u32 s23, s23, 0
	s_add_u32 s70, s70, 0x100
	s_addc_u32 s71, s71, 0
	s_cmp_gt_u32 s72, 13
	s_cbranch_scc0 .LBB0_145
	s_and_b64 vcc, exec, s[8:9]
	s_cbranch_vccz .LBB0_148
	s_barrier

; #define PG8_STAGE(bufoff, gbase, voff) do { _Pragma("unroll") for (int _i = 0; _i < 2; ++_i) \
;         __builtin_amdgcn_global_load_lds((const unsigned*)((const char*)(gbase) + (voff)[_i]), (PG8_LAS unsigned*)(lds + (bufoff) + ldsw + _i * 8192), 16, 0, 0); } while (0)
; #define PG8_LDA(dst, b, h) do { _Pragma("unroll") for (int m = 0; m < 4; ++m) _Pragma("unroll") for (int k = 0; k < 2; ++k) dst[m][k] = *(const PG8_LAS bf16x8*)(lds + PG8_SA(b, h) + aoff + m * 2048 + k * 1024); } while (0)
; #define PG8_LDB(dst, b, h) do { _Pragma("unroll") for (int n = 0; n < 2; ++n) _Pragma("unroll") for (int k = 0; k < 2; ++k) dst[n][k] = *(const PG8_LAS bf16x8*)(lds + PG8_SB(b, h) + boff + n * 2048 + k * 1024); } while (0)
; #define PG8_MMA(ai, bj, At, Bt) do { __builtin_amdgcn_s_setprio(1); _Pragma("unroll") for (int m = 0; m < 4; ++m) _Pragma("unroll") for (int n = 0; n < 2; ++n) _Pragma("unroll") for (int k = 0; k < 2; ++k) \
;         acc[ai][bj][m][n] = __builtin_amdgcn_mfma_f32_16x16x32_bf16(Bt[n][k], At[m][k], acc[ai][bj][m][n], 0, 0, 0); __builtin_amdgcn_s_setprio(0); } while (0)
; #define PG8_BAR __builtin_amdgcn_s_barrier()
; template <class Epi, class Sched, bool ALIGN_EPI = false, bool SP2 = false>
; __device__ __forceinline__ void gemm_phase(PG8_LAS unsigned char* lds, const Gemm g, const Sched& S, const Epi& E, const int tid_in) {
;     ...
;             PG8_LDB(B0, 0, 0); PG8_LDB(B1, 0, 1); PG8_SCHED; PG8_LDA(At, 0, 0); PG8_STAGE(PG8_SA(1, 1), a1 + hstepA, voffA);
;             PG8_WAIT_V(8); PG8_WAIT_L(0); PG8_BAR; PG8_MMA(0, 0, At, B0); PG8_MMA(0, 1, At, B1); PG8_BAR; PG8_SCHED;
;             PG8_LDA(At, 0, 1); PG8_STAGE(PG8_SB(0, 0), b2, voffB); PG8_STAGE(PG8_SB(0, 1), b2 + hstepB, voffB); PG8_STAGE(PG8_SA(0, 0), a2, voffA);
;             PG8_WAIT_V(8); PG8_WAIT_L(0); PG8_BAR; PG8_MMA(1, 0, At, B0); PG8_MMA(1, 1, At, B1); PG8_BAR; PG8_SCHED;
;             PG8_LDB(B0, 1, 0); PG8_LDB(B1, 1, 1); PG8_SCHED; PG8_LDA(At, 1, 0); PG8_STAGE(PG8_SA(0, 1), a2 + hstepA, voffA);
;             PG8_WAIT_V(8); PG8_WAIT_L(0); PG8_BAR; PG8_MMA(0, 0, At, B0); PG8_MMA(0, 1, At, B1); PG8_BAR; PG8_SCHED;
;             PG8_LDA(At, 1, 1); PG8_STAGE(PG8_SB(1, 0), b3, voffB); PG8_STAGE(PG8_SB(1, 1), b3 + hstepB, voffB); PG8_STAGE(PG8_SA(1, 0), a3, voffA);
;             PG8_WAIT_V(8); PG8_WAIT_L(0); PG8_BAR; PG8_MMA(1, 0, At, B0); PG8_MMA(1, 1, At, B1); PG8_BAR; PG8_SCHED;
.LBB0_213:
	s_add_u32 s22, s20, 0xfffc0080
	s_addc_u32 s23, s21, -1
	s_add_i32 s46, 0, 0x10000
	s_cmp_eq_u32 s70, 12
	s_cselect_b32 s29, s13, s23
	s_cselect_b32 s28, s54, s22
	v_add_u32_e32 v145, s46, v142
	s_cselect_b32 s23, s11, s60
	s_cselect_b32 s22, s55, s56
	s_add_i32 s71, 0, 0x14000
	ds_read_b128 v[146:149], v145
	ds_read_b128 v[150:153], v145 offset:1024
	ds_read_b128 v[154:157], v145 offset:2048
	ds_read_b128 v[158:161], v145 offset:3072
	v_add_u32_e32 v145, s71, v142
	ds_read_b128 v[162:165], v145
	ds_read_b128 v[166:169], v145 offset:1024
	ds_read_b128 v[170:173], v145 offset:2048
	ds_read_b128 v[174:177], v145 offset:3072
	v_lshl_add_u64 v[190:191], s[20:21], 0, v[138:139]
	s_add_i32 m0, s40, 0xc000
	ds_read_b128 v[178:181], v144
	ds_read_b128 v[182:185], v144 offset:1024
	ds_read_b128 v[186:189], v144 offset:2048
	ds_read_b128 v[202:205], v144 offset:3072
	ds_read_b128 v[206:209], v144 offset:4096
	ds_read_b128 v[210:213], v144 offset:5120
	ds_read_b128 v[214:217], v144 offset:6144
	ds_read_b128 v[218:221], v144 offset:7168
	global_load_lds_dwordx4 v[190:191], off
	v_lshl_add_u64 v[190:191], s[20:21], 0, v[140:141]
	s_add_i32 m0, s40, 0xe000
	s_nop 0
	global_load_lds_dwordx4 v[190:191], off
	s_waitcnt vmcnt(8)
	s_waitcnt lgkmcnt(0)
	s_barrier
	s_setprio 1
	s_waitcnt lgkmcnt(0)
	v_mfma_f32_16x16x32_bf16 v[126:129], v[146:149], v[178:181], v[126:129]
	v_mfma_f32_16x16x32_bf16 v[118:121], v[154:157], v[178:181], v[118:121]
	v_mfma_f32_16x16x32_bf16 v[110:113], v[146:149], v[186:189], v[110:113]
	v_mfma_f32_16x16x32_bf16 v[102:105], v[154:157], v[186:189], v[102:105]
	v_mfma_f32_16x16x32_bf16 v[92:95], v[146:149], v[206:209], v[92:95]
	v_mfma_f32_16x16x32_bf16 v[84:87], v[154:157], v[206:209], v[84:87]
	v_mfma_f32_16x16x32_bf16 v[76:79], v[146:149], v[214:217], v[76:79]
	v_mfma_f32_16x16x32_bf16 v[68:71], v[154:157], v[214:217], v[68:71]
	v_mfma_f32_16x16x32_bf16 v[126:129], v[150:153], v[182:185], v[126:129]
	v_mfma_f32_16x16x32_bf16 v[118:121], v[158:161], v[182:185], v[118:121]
	v_mfma_f32_16x16x32_bf16 v[110:113], v[150:153], v[202:205], v[110:113]
	v_mfma_f32_16x16x32_bf16 v[102:105], v[158:161], v[202:205], v[102:105]
	v_mfma_f32_16x16x32_bf16 v[92:95], v[150:153], v[210:213], v[92:95]
	v_mfma_f32_16x16x32_bf16 v[84:87], v[158:161], v[210:213], v[84:87]
	v_mfma_f32_16x16x32_bf16 v[76:79], v[150:153], v[218:221], v[76:79]
	v_mfma_f32_16x16x32_bf16 v[68:71], v[158:161], v[218:221], v[68:71]
	s_setprio 0
	s_setprio 1
	v_mfma_f32_16x16x32_bf16 v[122:125], v[162:165], v[178:181], v[122:125]
	v_mfma_f32_16x16x32_bf16 v[114:117], v[170:173], v[178:181], v[114:117]
	v_mfma_f32_16x16x32_bf16 v[106:109], v[162:165], v[186:189], v[106:109]
	v_mfma_f32_16x16x32_bf16 v[98:101], v[170:173], v[186:189], v[98:101]
	v_mfma_f32_16x16x32_bf16 v[88:91], v[162:165], v[206:209], v[88:91]
	v_mfma_f32_16x16x32_bf16 v[80:83], v[170:173], v[206:209], v[80:83]
	v_mfma_f32_16x16x32_bf16 v[72:75], v[162:165], v[214:217], v[72:75]
	v_mfma_f32_16x16x32_bf16 v[64:67], v[170:173], v[214:217], v[64:67]
	v_mfma_f32_16x16x32_bf16 v[122:125], v[166:169], v[182:185], v[122:125]
	v_mfma_f32_16x16x32_bf16 v[114:117], v[174:177], v[182:185], v[114:117]
	v_mfma_f32_16x16x32_bf16 v[106:109], v[166:169], v[202:205], v[106:109]
	v_mfma_f32_16x16x32_bf16 v[98:101], v[174:177], v[202:205], v[98:101]
	v_mfma_f32_16x16x32_bf16 v[88:91], v[166:169], v[210:213], v[88:91]
	v_mfma_f32_16x16x32_bf16 v[80:83], v[174:177], v[210:213], v[80:83]
	v_mfma_f32_16x16x32_bf16 v[72:75], v[166:169], v[218:221], v[72:75]
	v_mfma_f32_16x16x32_bf16 v[64:67], v[174:177], v[218:221], v[64:67]
	s_setprio 0
	s_barrier
	s_add_i32 s46, s46, s39
	v_lshl_add_u64 v[190:191], s[22:23], 0, v[132:133]
	s_mov_b32 m0, s46
	ds_read_b128 v[178:181], v144 offset:16384
	ds_read_b128 v[182:185], v144 offset:17408
	ds_read_b128 v[186:189], v144 offset:18432
	ds_read_b128 v[202:205], v144 offset:19456
	ds_read_b128 v[206:209], v144 offset:20480
	ds_read_b128 v[210:213], v144 offset:21504
	ds_read_b128 v[214:217], v144 offset:22528
	ds_read_b128 v[218:221], v144 offset:23552
	global_load_lds_dwordx4 v[190:191], off
	s_add_i32 m0, s46, 0x2000
	s_add_u32 s72, s22, 0x40000
	v_lshl_add_u64 v[192:193], s[22:23], 0, v[136:137]
	s_addc_u32 s73, s23, 0
	s_add_i32 s46, s71, s39
	global_load_lds_dwordx4 v[192:193], off
	v_lshl_add_u64 v[198:199], s[72:73], 0, v[132:133]
	s_mov_b32 m0, s46
	global_load_lds_dwordx4 v[198:199], off
	v_lshl_add_u64 v[198:199], s[72:73], 0, v[136:137]
	s_add_i32 m0, s46, 0x2000
	s_nop 0
	global_load_lds_dwordx4 v[198:199], off
	s_waitcnt vmcnt(6)
	s_waitcnt lgkmcnt(0)
	s_barrier
; #define PG8_STAGE(bufoff, gbase, voff) do { _Pragma("unroll") for (int _i = 0; _i < 2; ++_i) \
;         __builtin_amdgcn_global_load_lds((const unsigned*)((const char*)(gbase) + (voff)[_i]), (PG8_LAS unsigned*)(lds + (bufoff) + ldsw + _i * 8192), 16, 0, 0); } while (0)
; #define PG8_LDA(dst, b, h) do { _Pragma("unroll") for (int m = 0; m < 4; ++m) _Pragma("unroll") for (int k = 0; k < 2; ++k) dst[m][k] = *(const PG8_LAS bf16x8*)(lds + PG8_SA(b, h) + aoff + m * 2048 + k * 1024); } while (0)
; #define PG8_LDB(dst, b, h) do { _Pragma("unroll") for (int n = 0; n < 2; ++n) _Pragma("unroll") for (int k = 0; k < 2; ++k) dst[n][k] = *(const PG8_LAS bf16x8*)(lds + PG8_SB(b, h) + boff + n * 2048 + k * 1024); } while (0)
; #define PG8_MMA(ai, bj, At, Bt) do { __builtin_amdgcn_s_setprio(1); _Pragma("unroll") for (int m = 0; m < 4; ++m) _Pragma("unroll") for (int n = 0; n < 2; ++n) _Pragma("unroll") for (int k = 0; k < 2; ++k) \
;         acc[ai][bj][m][n] = __builtin_amdgcn_mfma_f32_16x16x32_bf16(Bt[n][k], At[m][k], acc[ai][bj][m][n], 0, 0, 0); __builtin_amdgcn_s_setprio(0); } while (0)
; #define PG8_BAR __builtin_amdgcn_s_barrier()
; template <class Epi, class Sched, bool ALIGN_EPI = false, bool SP2 = false>
; __device__ __forceinline__ void gemm_phase(PG8_LAS unsigned char* lds, const Gemm g, const Sched& S, const Epi& E, const int tid_in) {
;     ...
;             PG8_LDB(B0, 0, 0); PG8_LDB(B1, 0, 1); PG8_SCHED; PG8_LDA(At, 0, 0); PG8_STAGE(PG8_SA(1, 1), a1 + hstepA, voffA);
;             PG8_WAIT_V(8); PG8_WAIT_L(0); PG8_BAR; PG8_MMA(0, 0, At, B0); PG8_MMA(0, 1, At, B1); PG8_BAR; PG8_SCHED;
;             PG8_LDA(At, 0, 1); PG8_STAGE(PG8_SB(0, 0), b2, voffB); PG8_STAGE(PG8_SB(0, 1), b2 + hstepB, voffB); PG8_STAGE(PG8_SA(0, 0), a2, voffA);
;             PG8_WAIT_V(8); PG8_WAIT_L(0); PG8_BAR; PG8_MMA(1, 0, At, B0); PG8_MMA(1, 1, At, B1); PG8_BAR; PG8_SCHED;
;             PG8_LDB(B0, 1, 0); PG8_LDB(B1, 1, 1); PG8_SCHED; PG8_LDA(At, 1, 0); PG8_STAGE(PG8_SA(0, 1), a2 + hstepA, voffA);
;             PG8_WAIT_V(8); PG8_WAIT_L(0); PG8_BAR; PG8_MMA(0, 0, At, B0); PG8_MMA(0, 1, At, B1); PG8_BAR; PG8_SCHED;
;             PG8_LDA(At, 1, 1); PG8_STAGE(PG8_SB(1, 0), b3, voffB); PG8_STAGE(PG8_SB(1, 1), b3 + hstepB, voffB); PG8_STAGE(PG8_SA(1, 0), a3, voffA);
;             PG8_WAIT_V(8); PG8_WAIT_L(0); PG8_BAR; PG8_MMA(1, 0, At, B0); PG8_MMA(1, 1, At, B1); PG8_BAR; PG8_SCHED;
	s_setprio 1
	s_waitcnt lgkmcnt(0)
	v_mfma_f32_16x16x32_bf16 v[60:63], v[146:149], v[178:181], v[60:63]
	v_mfma_f32_16x16x32_bf16 v[52:55], v[154:157], v[178:181], v[52:55]
	v_mfma_f32_16x16x32_bf16 v[44:47], v[146:149], v[186:189], v[44:47]
	v_mfma_f32_16x16x32_bf16 v[36:39], v[154:157], v[186:189], v[36:39]
	v_mfma_f32_16x16x32_bf16 v[28:31], v[146:149], v[206:209], v[28:31]
	v_mfma_f32_16x16x32_bf16 v[20:23], v[154:157], v[206:209], v[20:23]
	v_mfma_f32_16x16x32_bf16 v[12:15], v[146:149], v[214:217], v[12:15]
	v_mfma_f32_16x16x32_bf16 v[4:7], v[154:157], v[214:217], v[4:7]
	v_mfma_f32_16x16x32_bf16 v[60:63], v[150:153], v[182:185], v[60:63]
	v_mfma_f32_16x16x32_bf16 v[52:55], v[158:161], v[182:185], v[52:55]
	v_mfma_f32_16x16x32_bf16 v[44:47], v[150:153], v[202:205], v[44:47]
	v_mfma_f32_16x16x32_bf16 v[36:39], v[158:161], v[202:205], v[36:39]
	v_mfma_f32_16x16x32_bf16 v[28:31], v[150:153], v[210:213], v[28:31]
	v_mfma_f32_16x16x32_bf16 v[20:23], v[158:161], v[210:213], v[20:23]
	v_mfma_f32_16x16x32_bf16 v[12:15], v[150:153], v[218:221], v[12:15]
	v_mfma_f32_16x16x32_bf16 v[4:7], v[158:161], v[218:221], v[4:7]
	s_setprio 0
	s_setprio 1
	v_mfma_f32_16x16x32_bf16 v[56:59], v[162:165], v[178:181], v[56:59]
	v_mfma_f32_16x16x32_bf16 v[48:51], v[170:173], v[178:181], v[48:51]
	v_mfma_f32_16x16x32_bf16 v[40:43], v[162:165], v[186:189], v[40:43]
	v_mfma_f32_16x16x32_bf16 v[32:35], v[170:173], v[186:189], v[32:35]
	v_mfma_f32_16x16x32_bf16 v[24:27], v[162:165], v[206:209], v[24:27]
	v_mfma_f32_16x16x32_bf16 v[16:19], v[170:173], v[206:209], v[16:19]
	v_mfma_f32_16x16x32_bf16 v[8:11], v[162:165], v[214:217], v[8:11]
	v_mfma_f32_16x16x32_bf16 v[0:3], v[170:173], v[214:217], v[0:3]
	v_mfma_f32_16x16x32_bf16 v[56:59], v[166:169], v[182:185], v[56:59]
	v_mfma_f32_16x16x32_bf16 v[48:51], v[174:177], v[182:185], v[48:51]
	v_mfma_f32_16x16x32_bf16 v[40:43], v[166:169], v[202:205], v[40:43]
	v_mfma_f32_16x16x32_bf16 v[32:35], v[174:177], v[202:205], v[32:35]
	v_mfma_f32_16x16x32_bf16 v[24:27], v[166:169], v[210:213], v[24:27]
	v_mfma_f32_16x16x32_bf16 v[16:19], v[174:177], v[210:213], v[16:19]
	v_mfma_f32_16x16x32_bf16 v[8:11], v[166:169], v[218:221], v[8:11]
	v_mfma_f32_16x16x32_bf16 v[0:3], v[174:177], v[218:221], v[0:3]
	s_setprio 0
	s_barrier
	v_lshl_add_u64 v[198:199], s[28:29], 0, v[130:131]
	v_lshl_add_u64 v[200:201], s[28:29], 0, v[134:135]
	s_mov_b32 m0, s40
	s_nop 0
	global_load_lds_dwordx4 v[198:199], off
	s_mov_b32 m0, s41
	s_nop 0
	global_load_lds_dwordx4 v[200:201], off
	s_add_i32 s46, 0, 0x18000
	v_add_u32_e32 v145, s46, v142
	s_add_i32 s71, 0, 0x1c000
	ds_read_b128 v[146:149], v145
	ds_read_b128 v[150:153], v145 offset:1024
	ds_read_b128 v[154:157], v145 offset:2048
	ds_read_b128 v[158:161], v145 offset:3072
	v_add_u32_e32 v145, s71, v142
	ds_read_b128 v[162:165], v145
	ds_read_b128 v[166:169], v145 offset:1024
	ds_read_b128 v[170:173], v145 offset:2048
	ds_read_b128 v[174:177], v145 offset:3072
	s_add_u32 s28, s28, 0x40000
	s_addc_u32 s29, s29, 0
	s_mov_b32 m0, s42
	v_lshl_add_u64 v[222:223], s[28:29], 0, v[130:131]
	ds_read_b128 v[178:181], v144 offset:32768
	ds_read_b128 v[182:185], v144 offset:33792
	ds_read_b128 v[186:189], v144 offset:34816
	ds_read_b128 v[202:205], v144 offset:35840
	ds_read_b128 v[206:209], v144 offset:36864
	ds_read_b128 v[210:213], v144 offset:37888
	ds_read_b128 v[214:217], v144 offset:38912
	ds_read_b128 v[218:221], v144 offset:39936
	global_load_lds_dwordx4 v[222:223], off
	v_lshl_add_u64 v[222:223], s[28:29], 0, v[134:135]
	s_mov_b32 m0, s43
	s_nop 0
	global_load_lds_dwordx4 v[222:223], off
	s_waitcnt vmcnt(8)
	s_waitcnt lgkmcnt(0)
	s_barrier
	s_setprio 1
	s_waitcnt lgkmcnt(0)
	v_mfma_f32_16x16x32_bf16 v[126:129], v[146:149], v[178:181], v[126:129]
	v_mfma_f32_16x16x32_bf16 v[118:121], v[154:157], v[178:181], v[118:121]
	v_mfma_f32_16x16x32_bf16 v[110:113], v[146:149], v[186:189], v[110:113]
	v_mfma_f32_16x16x32_bf16 v[102:105], v[154:157], v[186:189], v[102:105]
	v_mfma_f32_16x16x32_bf16 v[92:95], v[146:149], v[206:209], v[92:95]
	v_mfma_f32_16x16x32_bf16 v[84:87], v[154:157], v[206:209], v[84:87]
	v_mfma_f32_16x16x32_bf16 v[76:79], v[146:149], v[214:217], v[76:79]
	v_mfma_f32_16x16x32_bf16 v[68:71], v[154:157], v[214:217], v[68:71]
	v_mfma_f32_16x16x32_bf16 v[126:129], v[150:153], v[182:185], v[126:129]
	v_mfma_f32_16x16x32_bf16 v[118:121], v[158:161], v[182:185], v[118:121]
	v_mfma_f32_16x16x32_bf16 v[110:113], v[150:153], v[202:205], v[110:113]
	v_mfma_f32_16x16x32_bf16 v[102:105], v[158:161], v[202:205], v[102:105]
	v_mfma_f32_16x16x32_bf16 v[92:95], v[150:153], v[210:213], v[92:95]
	v_mfma_f32_16x16x32_bf16 v[84:87], v[158:161], v[210:213], v[84:87]
	v_mfma_f32_16x16x32_bf16 v[76:79], v[150:153], v[218:221], v[76:79]
	v_mfma_f32_16x16x32_bf16 v[68:71], v[158:161], v[218:221], v[68:71]
	s_setprio 0
	s_setprio 1
	v_mfma_f32_16x16x32_bf16 v[122:125], v[162:165], v[178:181], v[122:125]
	v_mfma_f32_16x16x32_bf16 v[114:117], v[170:173], v[178:181], v[114:117]
	v_mfma_f32_16x16x32_bf16 v[106:109], v[162:165], v[186:189], v[106:109]
	v_mfma_f32_16x16x32_bf16 v[98:101], v[170:173], v[186:189], v[98:101]
	v_mfma_f32_16x16x32_bf16 v[88:91], v[162:165], v[206:209], v[88:91]
	v_mfma_f32_16x16x32_bf16 v[80:83], v[170:173], v[206:209], v[80:83]
	v_mfma_f32_16x16x32_bf16 v[72:75], v[162:165], v[214:217], v[72:75]
	v_mfma_f32_16x16x32_bf16 v[64:67], v[170:173], v[214:217], v[64:67]
	v_mfma_f32_16x16x32_bf16 v[122:125], v[166:169], v[182:185], v[122:125]
	v_mfma_f32_16x16x32_bf16 v[114:117], v[174:177], v[182:185], v[114:117]
	v_mfma_f32_16x16x32_bf16 v[106:109], v[166:169], v[202:205], v[106:109]
	v_mfma_f32_16x16x32_bf16 v[98:101], v[174:177], v[202:205], v[98:101]
	v_mfma_f32_16x16x32_bf16 v[88:91], v[166:169], v[210:213], v[88:91]
	v_mfma_f32_16x16x32_bf16 v[80:83], v[174:177], v[210:213], v[80:83]
	v_mfma_f32_16x16x32_bf16 v[72:75], v[166:169], v[218:221], v[72:75]
	v_mfma_f32_16x16x32_bf16 v[64:67], v[174:177], v[218:221], v[64:67]
	s_setprio 0
	s_barrier
; #define PG8_STAGE(bufoff, gbase, voff) do { _Pragma("unroll") for (int _i = 0; _i < 2; ++_i) \
;         __builtin_amdgcn_global_load_lds((const unsigned*)((const char*)(gbase) + (voff)[_i]), (PG8_LAS unsigned*)(lds + (bufoff) + ldsw + _i * 8192), 16, 0, 0); } while (0)
; #define PG8_LDA(dst, b, h) do { _Pragma("unroll") for (int m = 0; m < 4; ++m) _Pragma("unroll") for (int k = 0; k < 2; ++k) dst[m][k] = *(const PG8_LAS bf16x8*)(lds + PG8_SA(b, h) + aoff + m * 2048 + k * 1024); } while (0)
; #define PG8_LDB(dst, b, h) do { _Pragma("unroll") for (int n = 0; n < 2; ++n) _Pragma("unroll") for (int k = 0; k < 2; ++k) dst[n][k] = *(const PG8_LAS bf16x8*)(lds + PG8_SB(b, h) + boff + n * 2048 + k * 1024); } while (0)
; #define PG8_MMA(ai, bj, At, Bt) do { __builtin_amdgcn_s_setprio(1); _Pragma("unroll") for (int m = 0; m < 4; ++m) _Pragma("unroll") for (int n = 0; n < 2; ++n) _Pragma("unroll") for (int k = 0; k < 2; ++k) \
;         acc[ai][bj][m][n] = __builtin_amdgcn_mfma_f32_16x16x32_bf16(Bt[n][k], At[m][k], acc[ai][bj][m][n], 0, 0, 0); __builtin_amdgcn_s_setprio(0); } while (0)
; #define PG8_BAR __builtin_amdgcn_s_barrier()
; template <class Epi, class Sched, bool ALIGN_EPI = false, bool SP2 = false>
; __device__ __forceinline__ void gemm_phase(PG8_LAS unsigned char* lds, const Gemm g, const Sched& S, const Epi& E, const int tid_in) {
;     ...
;             PG8_LDB(B0, 0, 0); PG8_LDB(B1, 0, 1); PG8_SCHED; PG8_LDA(At, 0, 0); PG8_STAGE(PG8_SA(1, 1), a1 + hstepA, voffA);
;             PG8_WAIT_V(8); PG8_WAIT_L(0); PG8_BAR; PG8_MMA(0, 0, At, B0); PG8_MMA(0, 1, At, B1); PG8_BAR; PG8_SCHED;
;             PG8_LDA(At, 0, 1); PG8_STAGE(PG8_SB(0, 0), b2, voffB); PG8_STAGE(PG8_SB(0, 1), b2 + hstepB, voffB); PG8_STAGE(PG8_SA(0, 0), a2, voffA);
;             PG8_WAIT_V(8); PG8_WAIT_L(0); PG8_BAR; PG8_MMA(1, 0, At, B0); PG8_MMA(1, 1, At, B1); PG8_BAR; PG8_SCHED;
;             PG8_LDB(B0, 1, 0); PG8_LDB(B1, 1, 1); PG8_SCHED; PG8_LDA(At, 1, 0); PG8_STAGE(PG8_SA(0, 1), a2 + hstepA, voffA);
;             PG8_WAIT_V(8); PG8_WAIT_L(0); PG8_BAR; PG8_MMA(0, 0, At, B0); PG8_MMA(0, 1, At, B1); PG8_BAR; PG8_SCHED;
;             PG8_LDA(At, 1, 1); PG8_STAGE(PG8_SB(1, 0), b3, voffB); PG8_STAGE(PG8_SB(1, 1), b3 + hstepB, voffB); PG8_STAGE(PG8_SA(1, 0), a3, voffA);
;             PG8_WAIT_V(8); PG8_WAIT_L(0); PG8_BAR; PG8_MMA(1, 0, At, B0); PG8_MMA(1, 1, At, B1); PG8_BAR; PG8_SCHED;
	s_add_i32 s28, s46, s39
	v_lshl_add_u64 v[190:191], v[190:191], 0, s[68:69]
	s_mov_b32 m0, s28
	ds_read_b128 v[178:181], v144 offset:49152
	ds_read_b128 v[182:185], v144 offset:50176
	ds_read_b128 v[186:189], v144 offset:51200
	ds_read_b128 v[202:205], v144 offset:52224
	ds_read_b128 v[206:209], v144 offset:53248
	ds_read_b128 v[210:213], v144 offset:54272
	ds_read_b128 v[214:217], v144 offset:55296
	ds_read_b128 v[218:221], v144 offset:56320
	global_load_lds_dwordx4 v[190:191], off
	s_add_i32 m0, s28, 0x2000
	s_add_u32 s22, s22, 0x40080
	v_lshl_add_u64 v[190:191], v[192:193], 0, s[68:69]
	s_addc_u32 s23, s23, 0
	s_add_i32 s28, s71, s39
	global_load_lds_dwordx4 v[190:191], off
	v_lshl_add_u64 v[190:191], s[22:23], 0, v[132:133]
	s_mov_b32 m0, s28
	s_nop 0
	global_load_lds_dwordx4 v[190:191], off
	v_lshl_add_u64 v[190:191], s[22:23], 0, v[136:137]
	s_add_i32 m0, s28, 0x2000
	s_nop 0
	global_load_lds_dwordx4 v[190:191], off
	v_lshl_add_u64 v[190:191], v[198:199], 0, s[68:69]
	s_mov_b32 m0, s44
	s_nop 0
	global_load_lds_dwordx4 v[190:191], off
	v_lshl_add_u64 v[190:191], v[200:201], 0, s[68:69]
	s_mov_b32 m0, s45
	s_nop 0
	global_load_lds_dwordx4 v[190:191], off
	s_waitcnt vmcnt(8)
	s_waitcnt lgkmcnt(0)
	s_barrier
	s_setprio 1
	s_waitcnt lgkmcnt(0)
	v_mfma_f32_16x16x32_bf16 v[60:63], v[146:149], v[178:181], v[60:63]
	v_mfma_f32_16x16x32_bf16 v[52:55], v[154:157], v[178:181], v[52:55]
	v_mfma_f32_16x16x32_bf16 v[44:47], v[146:149], v[186:189], v[44:47]
	v_mfma_f32_16x16x32_bf16 v[36:39], v[154:157], v[186:189], v[36:39]
	v_mfma_f32_16x16x32_bf16 v[28:31], v[146:149], v[206:209], v[28:31]
	v_mfma_f32_16x16x32_bf16 v[20:23], v[154:157], v[206:209], v[20:23]
	v_mfma_f32_16x16x32_bf16 v[12:15], v[146:149], v[214:217], v[12:15]
	v_mfma_f32_16x16x32_bf16 v[4:7], v[154:157], v[214:217], v[4:7]
	v_mfma_f32_16x16x32_bf16 v[60:63], v[150:153], v[182:185], v[60:63]
	v_mfma_f32_16x16x32_bf16 v[52:55], v[158:161], v[182:185], v[52:55]
	v_mfma_f32_16x16x32_bf16 v[44:47], v[150:153], v[202:205], v[44:47]
	v_mfma_f32_16x16x32_bf16 v[36:39], v[158:161], v[202:205], v[36:39]
	v_mfma_f32_16x16x32_bf16 v[28:31], v[150:153], v[210:213], v[28:31]
	v_mfma_f32_16x16x32_bf16 v[20:23], v[158:161], v[210:213], v[20:23]
	v_mfma_f32_16x16x32_bf16 v[12:15], v[150:153], v[218:221], v[12:15]
	v_mfma_f32_16x16x32_bf16 v[4:7], v[158:161], v[218:221], v[4:7]
	s_setprio 0
	s_setprio 1
	v_mfma_f32_16x16x32_bf16 v[56:59], v[162:165], v[178:181], v[56:59]
	v_mfma_f32_16x16x32_bf16 v[48:51], v[170:173], v[178:181], v[48:51]
	v_mfma_f32_16x16x32_bf16 v[40:43], v[162:165], v[186:189], v[40:43]
	v_mfma_f32_16x16x32_bf16 v[32:35], v[170:173], v[186:189], v[32:35]
	v_mfma_f32_16x16x32_bf16 v[24:27], v[162:165], v[206:209], v[24:27]
	v_mfma_f32_16x16x32_bf16 v[16:19], v[170:173], v[206:209], v[16:19]
	v_mfma_f32_16x16x32_bf16 v[8:11], v[162:165], v[214:217], v[8:11]
	v_mfma_f32_16x16x32_bf16 v[0:3], v[170:173], v[214:217], v[0:3]
	v_mfma_f32_16x16x32_bf16 v[56:59], v[166:169], v[182:185], v[56:59]
	v_mfma_f32_16x16x32_bf16 v[48:51], v[174:177], v[182:185], v[48:51]
	v_mfma_f32_16x16x32_bf16 v[40:43], v[166:169], v[202:205], v[40:43]
	v_mfma_f32_16x16x32_bf16 v[32:35], v[174:177], v[202:205], v[32:35]
	v_mfma_f32_16x16x32_bf16 v[24:27], v[166:169], v[210:213], v[24:27]
	v_mfma_f32_16x16x32_bf16 v[16:19], v[174:177], v[210:213], v[16:19]
	v_mfma_f32_16x16x32_bf16 v[8:11], v[166:169], v[218:221], v[8:11]
	v_mfma_f32_16x16x32_bf16 v[0:3], v[174:177], v[218:221], v[0:3]
	s_setprio 0
	s_barrier
	s_add_i32 s70, s70, 2
	s_add_u32 s20, s20, 0x100
	s_addc_u32 s21, s21, 0
	s_add_u32 s56, s56, 0x100
	s_addc_u32 s60, s60, 0
	s_cmp_gt_u32 s70, 13
	s_cbranch_scc0 .LBB0_213
	s_and_b64 vcc, exec, s[8:9]
	s_mov_b32 s46, 0xe00000
	s_mov_b32 s60, 0x1000000
	s_mov_b32 s70, 0x1200000
	s_cbranch_vccz .LBB0_216
	s_barrier

; #define PG8_STAGE(bufoff, gbase, voff) do { _Pragma("unroll") for (int _i = 0; _i < 2; ++_i) \
;         __builtin_amdgcn_global_load_lds((const unsigned*)((const char*)(gbase) + (voff)[_i]), (PG8_LAS unsigned*)(lds + (bufoff) + ldsw + _i * 8192), 16, 0, 0); } while (0)
; #define PG8_LDA(dst, b, h) do { _Pragma("unroll") for (int m = 0; m < 4; ++m) _Pragma("unroll") for (int k = 0; k < 2; ++k) dst[m][k] = *(const PG8_LAS bf16x8*)(lds + PG8_SA(b, h) + aoff + m * 2048 + k * 1024); } while (0)
; #define PG8_LDB(dst, b, h) do { _Pragma("unroll") for (int n = 0; n < 2; ++n) _Pragma("unroll") for (int k = 0; k < 2; ++k) dst[n][k] = *(const PG8_LAS bf16x8*)(lds + PG8_SB(b, h) + boff + n * 2048 + k * 1024); } while (0)
; #define PG8_MMA(ai, bj, At, Bt) do { __builtin_amdgcn_s_setprio(1); _Pragma("unroll") for (int m = 0; m < 4; ++m) _Pragma("unroll") for (int n = 0; n < 2; ++n) _Pragma("unroll") for (int k = 0; k < 2; ++k) \
;         acc[ai][bj][m][n] = __builtin_amdgcn_mfma_f32_16x16x32_bf16(Bt[n][k], At[m][k], acc[ai][bj][m][n], 0, 0, 0); __builtin_amdgcn_s_setprio(0); } while (0)
; #define PG8_BAR __builtin_amdgcn_s_barrier()
; template <class Epi, class Sched, bool ALIGN_EPI = false, bool SP2 = false>
; __device__ __forceinline__ void gemm_phase(PG8_LAS unsigned char* lds, const Gemm g, const Sched& S, const Epi& E, const int tid_in) {
;     ...
;             PG8_LDB(B0, 0, 0); PG8_LDB(B1, 0, 1); PG8_SCHED; PG8_LDA(At, 0, 0); PG8_STAGE(PG8_SA(1, 1), a1 + hstepA, voffA);
;             PG8_WAIT_V(8); PG8_WAIT_L(0); PG8_BAR; PG8_MMA(0, 0, At, B0); PG8_MMA(0, 1, At, B1); PG8_BAR; PG8_SCHED;
;             PG8_LDA(At, 0, 1); PG8_STAGE(PG8_SB(0, 0), b2, voffB); PG8_STAGE(PG8_SB(0, 1), b2 + hstepB, voffB); PG8_STAGE(PG8_SA(0, 0), a2, voffA);
;             PG8_WAIT_V(8); PG8_WAIT_L(0); PG8_BAR; PG8_MMA(1, 0, At, B0); PG8_MMA(1, 1, At, B1); PG8_BAR; PG8_SCHED;
;             PG8_LDB(B0, 1, 0); PG8_LDB(B1, 1, 1); PG8_SCHED; PG8_LDA(At, 1, 0); PG8_STAGE(PG8_SA(0, 1), a2 + hstepA, voffA);
;             PG8_WAIT_V(8); PG8_WAIT_L(0); PG8_BAR; PG8_MMA(0, 0, At, B0); PG8_MMA(0, 1, At, B1); PG8_BAR; PG8_SCHED;
;             PG8_LDA(At, 1, 1); PG8_STAGE(PG8_SB(1, 0), b3, voffB); PG8_STAGE(PG8_SB(1, 1), b3 + hstepB, voffB); PG8_STAGE(PG8_SA(1, 0), a3, voffA);
;             PG8_WAIT_V(8); PG8_WAIT_L(0); PG8_BAR; PG8_MMA(1, 0, At, B0); PG8_MMA(1, 1, At, B1); PG8_BAR; PG8_SCHED;
.LBB0_249:
	s_add_u32 s20, s18, 0xfffc0080
	s_addc_u32 s21, s19, -1
	s_add_i32 s46, 0, 0x10000
	s_cmp_eq_u32 s72, 12
	s_cselect_b32 s23, s11, s21
	s_cselect_b32 s22, s55, s20
	s_cselect_b32 s21, s9, s71
	s_cselect_b32 s20, s60, s70
	s_add_i32 s73, 0, 0x14000
	v_add_u32_e32 v142, s46, v165
	v_add_u32_e32 v146, s73, v165
	ds_read_b128 v[130:133], v142
	ds_read_b128 v[134:137], v142 offset:1024
	ds_read_b128 v[138:141], v142 offset:2048
	ds_read_b128 v[142:145], v142 offset:3072
	ds_read_b128 v[168:171], v146
	ds_read_b128 v[172:175], v146 offset:1024
	ds_read_b128 v[176:179], v146 offset:2048
	ds_read_b128 v[180:183], v146 offset:3072
	v_lshl_add_u64 v[146:147], s[18:19], 0, v[158:159]
	s_add_i32 m0, s33, 0xc000
	ds_read_b128 v[184:187], v166
	ds_read_b128 v[202:205], v166 offset:1024
	ds_read_b128 v[206:209], v166 offset:2048
	ds_read_b128 v[210:213], v166 offset:3072
	ds_read_b128 v[214:217], v166 offset:4096
	ds_read_b128 v[218:221], v166 offset:5120
	ds_read_b128 v[222:225], v166 offset:6144
	ds_read_b128 v[226:229], v166 offset:7168
	global_load_lds_dwordx4 v[146:147], off
	v_lshl_add_u64 v[146:147], s[18:19], 0, v[160:161]
	s_add_i32 m0, s33, 0xe000
	s_nop 0
	global_load_lds_dwordx4 v[146:147], off
	s_waitcnt vmcnt(8)
	s_waitcnt lgkmcnt(0)
	s_barrier
	s_setprio 1
	s_waitcnt lgkmcnt(0)
	v_mfma_f32_16x16x32_bf16 v[126:129], v[130:133], v[184:187], v[126:129]
	v_mfma_f32_16x16x32_bf16 v[122:125], v[138:141], v[184:187], v[122:125]
	v_mfma_f32_16x16x32_bf16 v[114:117], v[130:133], v[206:209], v[114:117]
	v_mfma_f32_16x16x32_bf16 v[110:113], v[138:141], v[206:209], v[110:113]
	v_mfma_f32_16x16x32_bf16 v[98:101], v[130:133], v[214:217], v[98:101]
	v_mfma_f32_16x16x32_bf16 v[92:95], v[138:141], v[214:217], v[92:95]
	v_mfma_f32_16x16x32_bf16 v[80:83], v[130:133], v[222:225], v[80:83]
	v_mfma_f32_16x16x32_bf16 v[76:79], v[138:141], v[222:225], v[76:79]
	v_mfma_f32_16x16x32_bf16 v[126:129], v[134:137], v[202:205], v[126:129]
	v_mfma_f32_16x16x32_bf16 v[122:125], v[142:145], v[202:205], v[122:125]
	v_mfma_f32_16x16x32_bf16 v[114:117], v[134:137], v[210:213], v[114:117]
	v_mfma_f32_16x16x32_bf16 v[110:113], v[142:145], v[210:213], v[110:113]
	v_mfma_f32_16x16x32_bf16 v[98:101], v[134:137], v[218:221], v[98:101]
	v_mfma_f32_16x16x32_bf16 v[92:95], v[142:145], v[218:221], v[92:95]
	v_mfma_f32_16x16x32_bf16 v[80:83], v[134:137], v[226:229], v[80:83]
	v_mfma_f32_16x16x32_bf16 v[76:79], v[142:145], v[226:229], v[76:79]
	s_setprio 0
	s_setprio 1
	v_mfma_f32_16x16x32_bf16 v[118:121], v[168:171], v[184:187], v[118:121]
	v_mfma_f32_16x16x32_bf16 v[106:109], v[176:179], v[184:187], v[106:109]
	v_mfma_f32_16x16x32_bf16 v[102:105], v[168:171], v[206:209], v[102:105]
	v_mfma_f32_16x16x32_bf16 v[88:91], v[176:179], v[206:209], v[88:91]
	v_mfma_f32_16x16x32_bf16 v[84:87], v[168:171], v[214:217], v[84:87]
	v_mfma_f32_16x16x32_bf16 v[72:75], v[176:179], v[214:217], v[72:75]
	v_mfma_f32_16x16x32_bf16 v[68:71], v[168:171], v[222:225], v[68:71]
	v_mfma_f32_16x16x32_bf16 v[64:67], v[176:179], v[222:225], v[64:67]
	v_mfma_f32_16x16x32_bf16 v[118:121], v[172:175], v[202:205], v[118:121]
	v_mfma_f32_16x16x32_bf16 v[106:109], v[180:183], v[202:205], v[106:109]
	v_mfma_f32_16x16x32_bf16 v[102:105], v[172:175], v[210:213], v[102:105]
	v_mfma_f32_16x16x32_bf16 v[88:91], v[180:183], v[210:213], v[88:91]
	v_mfma_f32_16x16x32_bf16 v[84:87], v[172:175], v[218:221], v[84:87]
	v_mfma_f32_16x16x32_bf16 v[72:75], v[180:183], v[218:221], v[72:75]
	v_mfma_f32_16x16x32_bf16 v[68:71], v[172:175], v[226:229], v[68:71]
	v_mfma_f32_16x16x32_bf16 v[64:67], v[180:183], v[226:229], v[64:67]
	s_setprio 0
	s_barrier
	s_add_i32 s46, s46, s31
	v_lshl_add_u64 v[146:147], s[20:21], 0, v[152:153]
	s_mov_b32 m0, s46
	ds_read_b128 v[184:187], v166 offset:16384
	ds_read_b128 v[202:205], v166 offset:17408
	ds_read_b128 v[206:209], v166 offset:18432
	ds_read_b128 v[210:213], v166 offset:19456
	ds_read_b128 v[214:217], v166 offset:20480
	ds_read_b128 v[218:221], v166 offset:21504
	ds_read_b128 v[222:225], v166 offset:22528
	ds_read_b128 v[226:229], v166 offset:23552
	global_load_lds_dwordx4 v[146:147], off
	s_add_i32 m0, s46, 0x2000
	s_add_u32 s74, s20, 0x40000
	v_lshl_add_u64 v[148:149], s[20:21], 0, v[156:157]
	s_addc_u32 s75, s21, 0
	s_add_i32 s46, s73, s31
	global_load_lds_dwordx4 v[148:149], off
	v_lshl_add_u64 v[162:163], s[74:75], 0, v[152:153]
	s_mov_b32 m0, s46
	global_load_lds_dwordx4 v[162:163], off
	v_lshl_add_u64 v[162:163], s[74:75], 0, v[156:157]
	s_add_i32 m0, s46, 0x2000
	s_nop 0
	global_load_lds_dwordx4 v[162:163], off
	s_waitcnt vmcnt(6)
	s_waitcnt lgkmcnt(0)
	s_barrier
; #define PG8_STAGE(bufoff, gbase, voff) do { _Pragma("unroll") for (int _i = 0; _i < 2; ++_i) \
;         __builtin_amdgcn_global_load_lds((const unsigned*)((const char*)(gbase) + (voff)[_i]), (PG8_LAS unsigned*)(lds + (bufoff) + ldsw + _i * 8192), 16, 0, 0); } while (0)
; #define PG8_LDA(dst, b, h) do { _Pragma("unroll") for (int m = 0; m < 4; ++m) _Pragma("unroll") for (int k = 0; k < 2; ++k) dst[m][k] = *(const PG8_LAS bf16x8*)(lds + PG8_SA(b, h) + aoff + m * 2048 + k * 1024); } while (0)
; #define PG8_LDB(dst, b, h) do { _Pragma("unroll") for (int n = 0; n < 2; ++n) _Pragma("unroll") for (int k = 0; k < 2; ++k) dst[n][k] = *(const PG8_LAS bf16x8*)(lds + PG8_SB(b, h) + boff + n * 2048 + k * 1024); } while (0)
; #define PG8_MMA(ai, bj, At, Bt) do { __builtin_amdgcn_s_setprio(1); _Pragma("unroll") for (int m = 0; m < 4; ++m) _Pragma("unroll") for (int n = 0; n < 2; ++n) _Pragma("unroll") for (int k = 0; k < 2; ++k) \
;         acc[ai][bj][m][n] = __builtin_amdgcn_mfma_f32_16x16x32_bf16(Bt[n][k], At[m][k], acc[ai][bj][m][n], 0, 0, 0); __builtin_amdgcn_s_setprio(0); } while (0)
; #define PG8_BAR __builtin_amdgcn_s_barrier()
; template <class Epi, class Sched, bool ALIGN_EPI = false, bool SP2 = false>
; __device__ __forceinline__ void gemm_phase(PG8_LAS unsigned char* lds, const Gemm g, const Sched& S, const Epi& E, const int tid_in) {
;     ...
;             PG8_LDB(B0, 0, 0); PG8_LDB(B1, 0, 1); PG8_SCHED; PG8_LDA(At, 0, 0); PG8_STAGE(PG8_SA(1, 1), a1 + hstepA, voffA);
;             PG8_WAIT_V(8); PG8_WAIT_L(0); PG8_BAR; PG8_MMA(0, 0, At, B0); PG8_MMA(0, 1, At, B1); PG8_BAR; PG8_SCHED;
;             PG8_LDA(At, 0, 1); PG8_STAGE(PG8_SB(0, 0), b2, voffB); PG8_STAGE(PG8_SB(0, 1), b2 + hstepB, voffB); PG8_STAGE(PG8_SA(0, 0), a2, voffA);
;             PG8_WAIT_V(8); PG8_WAIT_L(0); PG8_BAR; PG8_MMA(1, 0, At, B0); PG8_MMA(1, 1, At, B1); PG8_BAR; PG8_SCHED;
;             PG8_LDB(B0, 1, 0); PG8_LDB(B1, 1, 1); PG8_SCHED; PG8_LDA(At, 1, 0); PG8_STAGE(PG8_SA(0, 1), a2 + hstepA, voffA);
;             PG8_WAIT_V(8); PG8_WAIT_L(0); PG8_BAR; PG8_MMA(0, 0, At, B0); PG8_MMA(0, 1, At, B1); PG8_BAR; PG8_SCHED;
;             PG8_LDA(At, 1, 1); PG8_STAGE(PG8_SB(1, 0), b3, voffB); PG8_STAGE(PG8_SB(1, 1), b3 + hstepB, voffB); PG8_STAGE(PG8_SA(1, 0), a3, voffA);
;             PG8_WAIT_V(8); PG8_WAIT_L(0); PG8_BAR; PG8_MMA(1, 0, At, B0); PG8_MMA(1, 1, At, B1); PG8_BAR; PG8_SCHED;
	s_setprio 1
	s_waitcnt lgkmcnt(0)
	v_mfma_f32_16x16x32_bf16 v[60:63], v[130:133], v[184:187], v[60:63]
	v_mfma_f32_16x16x32_bf16 v[56:59], v[138:141], v[184:187], v[56:59]
	v_mfma_f32_16x16x32_bf16 v[48:51], v[130:133], v[206:209], v[48:51]
	v_mfma_f32_16x16x32_bf16 v[44:47], v[138:141], v[206:209], v[44:47]
	v_mfma_f32_16x16x32_bf16 v[32:35], v[130:133], v[214:217], v[32:35]
	v_mfma_f32_16x16x32_bf16 v[28:31], v[138:141], v[214:217], v[28:31]
	v_mfma_f32_16x16x32_bf16 v[16:19], v[130:133], v[222:225], v[16:19]
	v_mfma_f32_16x16x32_bf16 v[12:15], v[138:141], v[222:225], v[12:15]
	v_mfma_f32_16x16x32_bf16 v[60:63], v[134:137], v[202:205], v[60:63]
	v_mfma_f32_16x16x32_bf16 v[56:59], v[142:145], v[202:205], v[56:59]
	v_mfma_f32_16x16x32_bf16 v[48:51], v[134:137], v[210:213], v[48:51]
	v_mfma_f32_16x16x32_bf16 v[44:47], v[142:145], v[210:213], v[44:47]
	v_mfma_f32_16x16x32_bf16 v[32:35], v[134:137], v[218:221], v[32:35]
	v_mfma_f32_16x16x32_bf16 v[28:31], v[142:145], v[218:221], v[28:31]
	v_mfma_f32_16x16x32_bf16 v[16:19], v[134:137], v[226:229], v[16:19]
	v_mfma_f32_16x16x32_bf16 v[12:15], v[142:145], v[226:229], v[12:15]
	s_setprio 0
	s_setprio 1
	v_mfma_f32_16x16x32_bf16 v[52:55], v[168:171], v[184:187], v[52:55]
	v_mfma_f32_16x16x32_bf16 v[40:43], v[176:179], v[184:187], v[40:43]
	v_mfma_f32_16x16x32_bf16 v[36:39], v[168:171], v[206:209], v[36:39]
	v_mfma_f32_16x16x32_bf16 v[24:27], v[176:179], v[206:209], v[24:27]
	v_mfma_f32_16x16x32_bf16 v[20:23], v[168:171], v[214:217], v[20:23]
	v_mfma_f32_16x16x32_bf16 v[8:11], v[176:179], v[214:217], v[8:11]
	v_mfma_f32_16x16x32_bf16 v[4:7], v[168:171], v[222:225], v[4:7]
	v_mfma_f32_16x16x32_bf16 v[0:3], v[176:179], v[222:225], v[0:3]
	v_mfma_f32_16x16x32_bf16 v[52:55], v[172:175], v[202:205], v[52:55]
	v_mfma_f32_16x16x32_bf16 v[40:43], v[180:183], v[202:205], v[40:43]
	v_mfma_f32_16x16x32_bf16 v[36:39], v[172:175], v[210:213], v[36:39]
	v_mfma_f32_16x16x32_bf16 v[24:27], v[180:183], v[210:213], v[24:27]
	v_mfma_f32_16x16x32_bf16 v[20:23], v[172:175], v[218:221], v[20:23]
	v_mfma_f32_16x16x32_bf16 v[8:11], v[180:183], v[218:221], v[8:11]
	v_mfma_f32_16x16x32_bf16 v[4:7], v[172:175], v[226:229], v[4:7]
	v_mfma_f32_16x16x32_bf16 v[0:3], v[180:183], v[226:229], v[0:3]
	s_setprio 0
	s_barrier
	v_lshl_add_u64 v[162:163], s[22:23], 0, v[150:151]
	v_lshl_add_u64 v[188:189], s[22:23], 0, v[154:155]
	s_mov_b32 m0, s33
	s_nop 0
	global_load_lds_dwordx4 v[162:163], off
	s_mov_b32 m0, s39
	s_nop 0
	global_load_lds_dwordx4 v[188:189], off
	s_add_i32 s46, 0, 0x18000
	s_add_i32 s73, 0, 0x1c000
	v_add_u32_e32 v142, s46, v165
	v_add_u32_e32 v167, s73, v165
	ds_read_b128 v[130:133], v142
	ds_read_b128 v[134:137], v142 offset:1024
	ds_read_b128 v[138:141], v142 offset:2048
	ds_read_b128 v[142:145], v142 offset:3072
	ds_read_b128 v[168:171], v167
	ds_read_b128 v[172:175], v167 offset:1024
	ds_read_b128 v[176:179], v167 offset:2048
	ds_read_b128 v[180:183], v167 offset:3072
	s_add_u32 s22, s22, 0x40000
	s_addc_u32 s23, s23, 0
	s_mov_b32 m0, s40
	v_lshl_add_u64 v[190:191], s[22:23], 0, v[150:151]
	ds_read_b128 v[184:187], v166 offset:32768
	ds_read_b128 v[202:205], v166 offset:33792
	ds_read_b128 v[206:209], v166 offset:34816
	ds_read_b128 v[210:213], v166 offset:35840
	ds_read_b128 v[214:217], v166 offset:36864
	ds_read_b128 v[218:221], v166 offset:37888
	ds_read_b128 v[222:225], v166 offset:38912
	ds_read_b128 v[226:229], v166 offset:39936
	global_load_lds_dwordx4 v[190:191], off
	v_lshl_add_u64 v[190:191], s[22:23], 0, v[154:155]
	s_mov_b32 m0, s41
	s_nop 0
	global_load_lds_dwordx4 v[190:191], off
	s_waitcnt vmcnt(8)
	s_waitcnt lgkmcnt(0)
	s_barrier
	s_setprio 1
	s_waitcnt lgkmcnt(0)
	v_mfma_f32_16x16x32_bf16 v[126:129], v[130:133], v[184:187], v[126:129]
	v_mfma_f32_16x16x32_bf16 v[122:125], v[138:141], v[184:187], v[122:125]
	v_mfma_f32_16x16x32_bf16 v[114:117], v[130:133], v[206:209], v[114:117]
	v_mfma_f32_16x16x32_bf16 v[110:113], v[138:141], v[206:209], v[110:113]
	v_mfma_f32_16x16x32_bf16 v[98:101], v[130:133], v[214:217], v[98:101]
	v_mfma_f32_16x16x32_bf16 v[92:95], v[138:141], v[214:217], v[92:95]
	v_mfma_f32_16x16x32_bf16 v[80:83], v[130:133], v[222:225], v[80:83]
	v_mfma_f32_16x16x32_bf16 v[76:79], v[138:141], v[222:225], v[76:79]
	v_mfma_f32_16x16x32_bf16 v[126:129], v[134:137], v[202:205], v[126:129]
	v_mfma_f32_16x16x32_bf16 v[122:125], v[142:145], v[202:205], v[122:125]
	v_mfma_f32_16x16x32_bf16 v[114:117], v[134:137], v[210:213], v[114:117]
	v_mfma_f32_16x16x32_bf16 v[110:113], v[142:145], v[210:213], v[110:113]
	v_mfma_f32_16x16x32_bf16 v[98:101], v[134:137], v[218:221], v[98:101]
	v_mfma_f32_16x16x32_bf16 v[92:95], v[142:145], v[218:221], v[92:95]
	v_mfma_f32_16x16x32_bf16 v[80:83], v[134:137], v[226:229], v[80:83]
	v_mfma_f32_16x16x32_bf16 v[76:79], v[142:145], v[226:229], v[76:79]
	s_setprio 0
	s_setprio 1
	v_mfma_f32_16x16x32_bf16 v[118:121], v[168:171], v[184:187], v[118:121]
	v_mfma_f32_16x16x32_bf16 v[106:109], v[176:179], v[184:187], v[106:109]
	v_mfma_f32_16x16x32_bf16 v[102:105], v[168:171], v[206:209], v[102:105]
	v_mfma_f32_16x16x32_bf16 v[88:91], v[176:179], v[206:209], v[88:91]
	v_mfma_f32_16x16x32_bf16 v[84:87], v[168:171], v[214:217], v[84:87]
	v_mfma_f32_16x16x32_bf16 v[72:75], v[176:179], v[214:217], v[72:75]
	v_mfma_f32_16x16x32_bf16 v[68:71], v[168:171], v[222:225], v[68:71]
	v_mfma_f32_16x16x32_bf16 v[64:67], v[176:179], v[222:225], v[64:67]
	v_mfma_f32_16x16x32_bf16 v[118:121], v[172:175], v[202:205], v[118:121]
	v_mfma_f32_16x16x32_bf16 v[106:109], v[180:183], v[202:205], v[106:109]
	v_mfma_f32_16x16x32_bf16 v[102:105], v[172:175], v[210:213], v[102:105]
	v_mfma_f32_16x16x32_bf16 v[88:91], v[180:183], v[210:213], v[88:91]
	v_mfma_f32_16x16x32_bf16 v[84:87], v[172:175], v[218:221], v[84:87]
	v_mfma_f32_16x16x32_bf16 v[72:75], v[180:183], v[218:221], v[72:75]
	v_mfma_f32_16x16x32_bf16 v[68:71], v[172:175], v[226:229], v[68:71]
	v_mfma_f32_16x16x32_bf16 v[64:67], v[180:183], v[226:229], v[64:67]
	s_setprio 0
	s_barrier
; #define PG8_STAGE(bufoff, gbase, voff) do { _Pragma("unroll") for (int _i = 0; _i < 2; ++_i) \
;         __builtin_amdgcn_global_load_lds((const unsigned*)((const char*)(gbase) + (voff)[_i]), (PG8_LAS unsigned*)(lds + (bufoff) + ldsw + _i * 8192), 16, 0, 0); } while (0)
; #define PG8_LDA(dst, b, h) do { _Pragma("unroll") for (int m = 0; m < 4; ++m) _Pragma("unroll") for (int k = 0; k < 2; ++k) dst[m][k] = *(const PG8_LAS bf16x8*)(lds + PG8_SA(b, h) + aoff + m * 2048 + k * 1024); } while (0)
; #define PG8_LDB(dst, b, h) do { _Pragma("unroll") for (int n = 0; n < 2; ++n) _Pragma("unroll") for (int k = 0; k < 2; ++k) dst[n][k] = *(const PG8_LAS bf16x8*)(lds + PG8_SB(b, h) + boff + n * 2048 + k * 1024); } while (0)
; #define PG8_MMA(ai, bj, At, Bt) do { __builtin_amdgcn_s_setprio(1); _Pragma("unroll") for (int m = 0; m < 4; ++m) _Pragma("unroll") for (int n = 0; n < 2; ++n) _Pragma("unroll") for (int k = 0; k < 2; ++k) \
;         acc[ai][bj][m][n] = __builtin_amdgcn_mfma_f32_16x16x32_bf16(Bt[n][k], At[m][k], acc[ai][bj][m][n], 0, 0, 0); __builtin_amdgcn_s_setprio(0); } while (0)
; #define PG8_BAR __builtin_amdgcn_s_barrier()
; template <class Epi, class Sched, bool ALIGN_EPI = false, bool SP2 = false>
; __device__ __forceinline__ void gemm_phase(PG8_LAS unsigned char* lds, const Gemm g, const Sched& S, const Epi& E, const int tid_in) {
;     ...
;             PG8_LDB(B0, 0, 0); PG8_LDB(B1, 0, 1); PG8_SCHED; PG8_LDA(At, 0, 0); PG8_STAGE(PG8_SA(1, 1), a1 + hstepA, voffA);
;             PG8_WAIT_V(8); PG8_WAIT_L(0); PG8_BAR; PG8_MMA(0, 0, At, B0); PG8_MMA(0, 1, At, B1); PG8_BAR; PG8_SCHED;
;             PG8_LDA(At, 0, 1); PG8_STAGE(PG8_SB(0, 0), b2, voffB); PG8_STAGE(PG8_SB(0, 1), b2 + hstepB, voffB); PG8_STAGE(PG8_SA(0, 0), a2, voffA);
;             PG8_WAIT_V(8); PG8_WAIT_L(0); PG8_BAR; PG8_MMA(1, 0, At, B0); PG8_MMA(1, 1, At, B1); PG8_BAR; PG8_SCHED;
;             PG8_LDB(B0, 1, 0); PG8_LDB(B1, 1, 1); PG8_SCHED; PG8_LDA(At, 1, 0); PG8_STAGE(PG8_SA(0, 1), a2 + hstepA, voffA);
;             PG8_WAIT_V(8); PG8_WAIT_L(0); PG8_BAR; PG8_MMA(0, 0, At, B0); PG8_MMA(0, 1, At, B1); PG8_BAR; PG8_SCHED;
;             PG8_LDA(At, 1, 1); PG8_STAGE(PG8_SB(1, 0), b3, voffB); PG8_STAGE(PG8_SB(1, 1), b3 + hstepB, voffB); PG8_STAGE(PG8_SA(1, 0), a3, voffA);
;             PG8_WAIT_V(8); PG8_WAIT_L(0); PG8_BAR; PG8_MMA(1, 0, At, B0); PG8_MMA(1, 1, At, B1); PG8_BAR; PG8_SCHED;
	s_add_i32 s22, s46, s31
	v_lshl_add_u64 v[146:147], v[146:147], 0, s[68:69]
	s_mov_b32 m0, s22
	ds_read_b128 v[184:187], v166 offset:49152
	ds_read_b128 v[202:205], v166 offset:50176
	ds_read_b128 v[206:209], v166 offset:51200
	ds_read_b128 v[210:213], v166 offset:52224
	ds_read_b128 v[214:217], v166 offset:53248
	ds_read_b128 v[218:221], v166 offset:54272
	ds_read_b128 v[222:225], v166 offset:55296
	ds_read_b128 v[226:229], v166 offset:56320
	global_load_lds_dwordx4 v[146:147], off
	s_add_i32 m0, s22, 0x2000
	s_add_u32 s20, s20, 0x40080
	v_lshl_add_u64 v[146:147], v[148:149], 0, s[68:69]
	s_addc_u32 s21, s21, 0
	s_add_i32 s22, s73, s31
	global_load_lds_dwordx4 v[146:147], off
	v_lshl_add_u64 v[146:147], s[20:21], 0, v[152:153]
	s_mov_b32 m0, s22
	s_nop 0
	global_load_lds_dwordx4 v[146:147], off
	v_lshl_add_u64 v[146:147], s[20:21], 0, v[156:157]
	s_add_i32 m0, s22, 0x2000
	s_nop 0
	global_load_lds_dwordx4 v[146:147], off
	v_lshl_add_u64 v[146:147], v[162:163], 0, s[68:69]
	s_mov_b32 m0, s44
	s_nop 0
	global_load_lds_dwordx4 v[146:147], off
	v_lshl_add_u64 v[146:147], v[188:189], 0, s[68:69]
	s_mov_b32 m0, s45
	s_nop 0
	global_load_lds_dwordx4 v[146:147], off
	s_waitcnt vmcnt(8)
	s_waitcnt lgkmcnt(0)
	s_barrier
	s_setprio 1
	s_waitcnt lgkmcnt(0)
	v_mfma_f32_16x16x32_bf16 v[60:63], v[130:133], v[184:187], v[60:63]
	v_mfma_f32_16x16x32_bf16 v[56:59], v[138:141], v[184:187], v[56:59]
	v_mfma_f32_16x16x32_bf16 v[48:51], v[130:133], v[206:209], v[48:51]
	v_mfma_f32_16x16x32_bf16 v[44:47], v[138:141], v[206:209], v[44:47]
	v_mfma_f32_16x16x32_bf16 v[32:35], v[130:133], v[214:217], v[32:35]
	v_mfma_f32_16x16x32_bf16 v[28:31], v[138:141], v[214:217], v[28:31]
	v_mfma_f32_16x16x32_bf16 v[16:19], v[130:133], v[222:225], v[16:19]
	v_mfma_f32_16x16x32_bf16 v[12:15], v[138:141], v[222:225], v[12:15]
	v_mfma_f32_16x16x32_bf16 v[60:63], v[134:137], v[202:205], v[60:63]
	v_mfma_f32_16x16x32_bf16 v[56:59], v[142:145], v[202:205], v[56:59]
	v_mfma_f32_16x16x32_bf16 v[48:51], v[134:137], v[210:213], v[48:51]
	v_mfma_f32_16x16x32_bf16 v[44:47], v[142:145], v[210:213], v[44:47]
	v_mfma_f32_16x16x32_bf16 v[32:35], v[134:137], v[218:221], v[32:35]
	v_mfma_f32_16x16x32_bf16 v[28:31], v[142:145], v[218:221], v[28:31]
	v_mfma_f32_16x16x32_bf16 v[16:19], v[134:137], v[226:229], v[16:19]
	v_mfma_f32_16x16x32_bf16 v[12:15], v[142:145], v[226:229], v[12:15]
	s_setprio 0
	s_setprio 1
	v_mfma_f32_16x16x32_bf16 v[52:55], v[168:171], v[184:187], v[52:55]
	v_mfma_f32_16x16x32_bf16 v[40:43], v[176:179], v[184:187], v[40:43]
	v_mfma_f32_16x16x32_bf16 v[36:39], v[168:171], v[206:209], v[36:39]
	v_mfma_f32_16x16x32_bf16 v[24:27], v[176:179], v[206:209], v[24:27]
	v_mfma_f32_16x16x32_bf16 v[20:23], v[168:171], v[214:217], v[20:23]
	v_mfma_f32_16x16x32_bf16 v[8:11], v[176:179], v[214:217], v[8:11]
	v_mfma_f32_16x16x32_bf16 v[4:7], v[168:171], v[222:225], v[4:7]
	v_mfma_f32_16x16x32_bf16 v[0:3], v[176:179], v[222:225], v[0:3]
	v_mfma_f32_16x16x32_bf16 v[52:55], v[172:175], v[202:205], v[52:55]
	v_mfma_f32_16x16x32_bf16 v[40:43], v[180:183], v[202:205], v[40:43]
	v_mfma_f32_16x16x32_bf16 v[36:39], v[172:175], v[210:213], v[36:39]
	v_mfma_f32_16x16x32_bf16 v[24:27], v[180:183], v[210:213], v[24:27]
	v_mfma_f32_16x16x32_bf16 v[20:23], v[172:175], v[218:221], v[20:23]
	v_mfma_f32_16x16x32_bf16 v[8:11], v[180:183], v[218:221], v[8:11]
	v_mfma_f32_16x16x32_bf16 v[4:7], v[172:175], v[226:229], v[4:7]
	v_mfma_f32_16x16x32_bf16 v[0:3], v[180:183], v[226:229], v[0:3]
	s_setprio 0
	s_barrier
	s_add_i32 s72, s72, 2
	s_add_u32 s18, s18, 0x100
	s_addc_u32 s19, s19, 0
	s_add_u32 s70, s70, 0x100
	s_addc_u32 s71, s71, 0
	s_cmp_gt_u32 s72, 13
	s_cbranch_scc0 .LBB0_249
	s_and_b64 vcc, exec, s[4:5]
	s_mov_b32 s72, 0xa00000
	s_mov_b32 s46, 0xe00000
	s_mov_b32 s60, 0x1000000
	s_mov_b32 s70, 0x1200000
	s_mov_b32 s71, 0x1400000
	s_cbranch_vccz .LBB0_252
	s_barrier

; __device__ __forceinline__ int lane_id_v() { int l; asm volatile("v_mbcnt_lo_u32_b32 %0, -1, 0\n\tv_mbcnt_hi_u32_b32 %0, -1, %0" : "=v"(l)); return l; }
; #define PG8_STAGE(bufoff, gbase, voff) do { _Pragma("unroll") for (int _i = 0; _i < 2; ++_i) \
;         __builtin_amdgcn_global_load_lds((const unsigned*)((const char*)(gbase) + (voff)[_i]), (PG8_LAS unsigned*)(lds + (bufoff) + ldsw + _i * 8192), 16, 0, 0); } while (0)
; #define PG8_LDA(dst, b, h) do { _Pragma("unroll") for (int m = 0; m < 4; ++m) _Pragma("unroll") for (int k = 0; k < 2; ++k) dst[m][k] = *(const PG8_LAS bf16x8*)(lds + PG8_SA(b, h) + aoff + m * 2048 + k * 1024); } while (0)
; #define PG8_BAR __builtin_amdgcn_s_barrier()
; template <class Epi, class Sched, bool ALIGN_EPI = false, bool SP2 = false>
; __device__ __forceinline__ void gemm_phase(PG8_LAS unsigned char* lds, const Gemm g, const Sched& S, const Epi& E, const int tid_in) {
;     ...
;             PG8_LDB(B0, 0, 0); PG8_LDB(B1, 0, 1); PG8_SCHED; PG8_LDA(At, 0, 0); PG8_STAGE(PG8_SA(1, 1), a1 + hstepA, voffA);
;             PG8_WAIT_V(8); PG8_WAIT_L(0); PG8_BAR; PG8_MMA(0, 0, At, B0); PG8_MMA(0, 1, At, B1); PG8_BAR; PG8_SCHED;
;             PG8_LDA(At, 0, 1); PG8_STAGE(PG8_SB(0, 0), b2, voffB); PG8_STAGE(PG8_SB(0, 1), b2 + hstepB, voffB); PG8_STAGE(PG8_SA(0, 0), a2, voffA);
;             PG8_WAIT_V(8); PG8_WAIT_L(0); PG8_BAR; PG8_MMA(1, 0, At, B0); PG8_MMA(1, 1, At, B1); PG8_BAR; PG8_SCHED;
;             PG8_LDB(B0, 1, 0); PG8_LDB(B1, 1, 1); PG8_SCHED; PG8_LDA(At, 1, 0); PG8_STAGE(PG8_SA(0, 1), a2 + hstepA, voffA);
;             PG8_WAIT_V(8); PG8_WAIT_L(0); PG8_BAR; PG8_MMA(0, 0, At, B0); PG8_MMA(0, 1, At, B1); PG8_BAR; PG8_SCHED;
;             PG8_LDA(At, 1, 1); PG8_STAGE(PG8_SB(1, 0), b3, voffB); PG8_STAGE(PG8_SB(1, 1), b3 + hstepB, voffB); PG8_STAGE(PG8_SA(1, 0), a3, voffA);
;             PG8_WAIT_V(8); PG8_WAIT_L(0); PG8_BAR; PG8_MMA(1, 0, At, B0); PG8_MMA(1, 1, At, B1); PG8_BAR; PG8_SCHED;
; __global__ void __launch_bounds__(512, 2) mega(Args a_unused) {
;     ...
;                 { pg8::Gemm g{(const bf16_t*)(ws + WS_DYY), (const bf16_t*)(ws + WS_WBR) + (size_t)l * 3072 * 512, 3 * M, 3072, 512, 0, 0}; pg8::BranchOrder S{G, c};
;                   pg8::EpiMerge E{(const bf16_t*)(ws + WS_GT), (float*)(ws + WS_XA), H};
;                   pg8::gemm_phase<pg8::EpiMerge, pg8::BranchOrder, true, true>(lds, g, S, E, wave_s * 64 + lane_id_v()); }
.Lmz_keep:
.LBB0_293:
	s_add_u32 s22, s20, 0xfffe0080
	s_addc_u32 s23, s21, -1
	s_add_i32 s46, 0, 0x10000
	s_cmp_eq_u32 s71, 4
	s_cselect_b32 s29, s7, s23
	s_cselect_b32 s28, s11, s22
	v_add_u32_e32 v96, s46, v159
	s_cselect_b32 s23, s13, s70
	s_cselect_b32 s22, s56, s60
	s_add_i32 s74, 0, 0x14000
	ds_read_b128 v[142:145], v96
	ds_read_b128 v[150:153], v96 offset:1024
	ds_read_b128 v[154:157], v96 offset:2048
	ds_read_b128 v[162:165], v96 offset:3072
	v_add_u32_e32 v96, s74, v159
	ds_read_b128 v[166:169], v96
	ds_read_b128 v[170:173], v96 offset:1024
	ds_read_b128 v[174:177], v96 offset:2048
	ds_read_b128 v[178:181], v96 offset:3072
	v_lshl_add_u64 v[146:147], s[20:21], 0, v[138:139]
	s_add_i32 m0, s31, 0xc000
	ds_read_b128 v[182:185], v161
	ds_read_b128 v[186:189], v161 offset:1024
	ds_read_b128 v[202:205], v161 offset:2048
	ds_read_b128 v[206:209], v161 offset:3072
	ds_read_b128 v[210:213], v161 offset:4096
	ds_read_b128 v[214:217], v161 offset:5120
	ds_read_b128 v[218:221], v161 offset:6144
	ds_read_b128 v[222:225], v161 offset:7168
	global_load_lds_dwordx4 v[146:147], off
	v_lshl_add_u64 v[146:147], s[20:21], 0, v[140:141]
	s_add_i32 m0, s31, 0xe000
	s_nop 0
	global_load_lds_dwordx4 v[146:147], off
	s_waitcnt vmcnt(8)
	s_waitcnt lgkmcnt(0)
	s_barrier
	s_setprio 1
	s_waitcnt lgkmcnt(0)
	v_mfma_f32_16x16x32_bf16 v[126:129], v[142:145], v[182:185], v[126:129]
	v_mfma_f32_16x16x32_bf16 v[122:125], v[154:157], v[182:185], v[122:125]
	v_mfma_f32_16x16x32_bf16 v[110:113], v[142:145], v[202:205], v[110:113]
	v_mfma_f32_16x16x32_bf16 v[106:109], v[154:157], v[202:205], v[106:109]
	v_mfma_f32_16x16x32_bf16 v[92:95], v[142:145], v[210:213], v[92:95]
	v_mfma_f32_16x16x32_bf16 v[88:91], v[154:157], v[210:213], v[88:91]
	v_mfma_f32_16x16x32_bf16 v[76:79], v[142:145], v[218:221], v[76:79]
	v_mfma_f32_16x16x32_bf16 v[72:75], v[154:157], v[218:221], v[72:75]
	v_mfma_f32_16x16x32_bf16 v[126:129], v[150:153], v[186:189], v[126:129]
	v_mfma_f32_16x16x32_bf16 v[122:125], v[162:165], v[186:189], v[122:125]
	v_mfma_f32_16x16x32_bf16 v[110:113], v[150:153], v[206:209], v[110:113]
	v_mfma_f32_16x16x32_bf16 v[106:109], v[162:165], v[206:209], v[106:109]
	v_mfma_f32_16x16x32_bf16 v[92:95], v[150:153], v[214:217], v[92:95]
	v_mfma_f32_16x16x32_bf16 v[88:91], v[162:165], v[214:217], v[88:91]
	v_mfma_f32_16x16x32_bf16 v[76:79], v[150:153], v[222:225], v[76:79]
	v_mfma_f32_16x16x32_bf16 v[72:75], v[162:165], v[222:225], v[72:75]
	s_setprio 0
	s_setprio 1
	v_mfma_f32_16x16x32_bf16 v[118:121], v[166:169], v[182:185], v[118:121]
	v_mfma_f32_16x16x32_bf16 v[114:117], v[174:177], v[182:185], v[114:117]
	v_mfma_f32_16x16x32_bf16 v[102:105], v[166:169], v[202:205], v[102:105]
	v_mfma_f32_16x16x32_bf16 v[98:101], v[174:177], v[202:205], v[98:101]
	v_mfma_f32_16x16x32_bf16 v[84:87], v[166:169], v[210:213], v[84:87]
	v_mfma_f32_16x16x32_bf16 v[80:83], v[174:177], v[210:213], v[80:83]
	v_mfma_f32_16x16x32_bf16 v[68:71], v[166:169], v[218:221], v[68:71]
	v_mfma_f32_16x16x32_bf16 v[64:67], v[174:177], v[218:221], v[64:67]
	v_mfma_f32_16x16x32_bf16 v[118:121], v[170:173], v[186:189], v[118:121]
	v_mfma_f32_16x16x32_bf16 v[114:117], v[178:181], v[186:189], v[114:117]
	v_mfma_f32_16x16x32_bf16 v[102:105], v[170:173], v[206:209], v[102:105]
	v_mfma_f32_16x16x32_bf16 v[98:101], v[178:181], v[206:209], v[98:101]
	v_mfma_f32_16x16x32_bf16 v[84:87], v[170:173], v[214:217], v[84:87]
	v_mfma_f32_16x16x32_bf16 v[80:83], v[178:181], v[214:217], v[80:83]
	v_mfma_f32_16x16x32_bf16 v[68:71], v[170:173], v[222:225], v[68:71]
	v_mfma_f32_16x16x32_bf16 v[64:67], v[178:181], v[222:225], v[64:67]
	s_setprio 0
	s_barrier
	s_add_i32 s46, s46, s30
	v_lshl_add_u64 v[146:147], s[22:23], 0, v[132:133]
	s_mov_b32 m0, s46
	ds_read_b128 v[182:185], v161 offset:16384
	ds_read_b128 v[186:189], v161 offset:17408
	ds_read_b128 v[202:205], v161 offset:18432
	ds_read_b128 v[206:209], v161 offset:19456
	ds_read_b128 v[210:213], v161 offset:20480
	ds_read_b128 v[214:217], v161 offset:21504
	ds_read_b128 v[218:221], v161 offset:22528
	ds_read_b128 v[222:225], v161 offset:23552
	global_load_lds_dwordx4 v[146:147], off
	s_add_i32 m0, s46, 0x2000
	s_add_u32 s72, s22, 0x20000
	v_lshl_add_u64 v[148:149], s[22:23], 0, v[136:137]
	s_addc_u32 s73, s23, 0
	s_add_i32 s46, s74, s30
	global_load_lds_dwordx4 v[148:149], off
	v_lshl_add_u64 v[226:227], s[72:73], 0, v[132:133]
	s_mov_b32 m0, s46
	global_load_lds_dwordx4 v[226:227], off
	v_lshl_add_u64 v[226:227], s[72:73], 0, v[136:137]
	s_add_i32 m0, s46, 0x2000
	s_nop 0
	global_load_lds_dwordx4 v[226:227], off
	s_waitcnt vmcnt(6)
	s_waitcnt lgkmcnt(0)
	s_barrier
; __device__ __forceinline__ int lane_id_v() { int l; asm volatile("v_mbcnt_lo_u32_b32 %0, -1, 0\n\tv_mbcnt_hi_u32_b32 %0, -1, %0" : "=v"(l)); return l; }
; #define PG8_STAGE(bufoff, gbase, voff) do { _Pragma("unroll") for (int _i = 0; _i < 2; ++_i) \
;         __builtin_amdgcn_global_load_lds((const unsigned*)((const char*)(gbase) + (voff)[_i]), (PG8_LAS unsigned*)(lds + (bufoff) + ldsw + _i * 8192), 16, 0, 0); } while (0)
; #define PG8_LDA(dst, b, h) do { _Pragma("unroll") for (int m = 0; m < 4; ++m) _Pragma("unroll") for (int k = 0; k < 2; ++k) dst[m][k] = *(const PG8_LAS bf16x8*)(lds + PG8_SA(b, h) + aoff + m * 2048 + k * 1024); } while (0)
; #define PG8_BAR __builtin_amdgcn_s_barrier()
; template <class Epi, class Sched, bool ALIGN_EPI = false, bool SP2 = false>
; __device__ __forceinline__ void gemm_phase(PG8_LAS unsigned char* lds, const Gemm g, const Sched& S, const Epi& E, const int tid_in) {
;     ...
;             PG8_LDB(B0, 0, 0); PG8_LDB(B1, 0, 1); PG8_SCHED; PG8_LDA(At, 0, 0); PG8_STAGE(PG8_SA(1, 1), a1 + hstepA, voffA);
;             PG8_WAIT_V(8); PG8_WAIT_L(0); PG8_BAR; PG8_MMA(0, 0, At, B0); PG8_MMA(0, 1, At, B1); PG8_BAR; PG8_SCHED;
;             PG8_LDA(At, 0, 1); PG8_STAGE(PG8_SB(0, 0), b2, voffB); PG8_STAGE(PG8_SB(0, 1), b2 + hstepB, voffB); PG8_STAGE(PG8_SA(0, 0), a2, voffA);
;             PG8_WAIT_V(8); PG8_WAIT_L(0); PG8_BAR; PG8_MMA(1, 0, At, B0); PG8_MMA(1, 1, At, B1); PG8_BAR; PG8_SCHED;
;             PG8_LDB(B0, 1, 0); PG8_LDB(B1, 1, 1); PG8_SCHED; PG8_LDA(At, 1, 0); PG8_STAGE(PG8_SA(0, 1), a2 + hstepA, voffA);
;             PG8_WAIT_V(8); PG8_WAIT_L(0); PG8_BAR; PG8_MMA(0, 0, At, B0); PG8_MMA(0, 1, At, B1); PG8_BAR; PG8_SCHED;
;             PG8_LDA(At, 1, 1); PG8_STAGE(PG8_SB(1, 0), b3, voffB); PG8_STAGE(PG8_SB(1, 1), b3 + hstepB, voffB); PG8_STAGE(PG8_SA(1, 0), a3, voffA);
;             PG8_WAIT_V(8); PG8_WAIT_L(0); PG8_BAR; PG8_MMA(1, 0, At, B0); PG8_MMA(1, 1, At, B1); PG8_BAR; PG8_SCHED;
; __global__ void __launch_bounds__(512, 2) mega(Args a_unused) {
;     ...
;                 { pg8::Gemm g{(const bf16_t*)(ws + WS_DYY), (const bf16_t*)(ws + WS_WBR) + (size_t)l * 3072 * 512, 3 * M, 3072, 512, 0, 0}; pg8::BranchOrder S{G, c};
;                   pg8::EpiMerge E{(const bf16_t*)(ws + WS_GT), (float*)(ws + WS_XA), H};
;                   pg8::gemm_phase<pg8::EpiMerge, pg8::BranchOrder, true, true>(lds, g, S, E, wave_s * 64 + lane_id_v()); }
	s_setprio 1
	s_waitcnt lgkmcnt(0)
	v_mfma_f32_16x16x32_bf16 v[60:63], v[142:145], v[182:185], v[60:63]
	v_mfma_f32_16x16x32_bf16 v[56:59], v[154:157], v[182:185], v[56:59]
	v_mfma_f32_16x16x32_bf16 v[44:47], v[142:145], v[202:205], v[44:47]
	v_mfma_f32_16x16x32_bf16 v[40:43], v[154:157], v[202:205], v[40:43]
	v_mfma_f32_16x16x32_bf16 v[28:31], v[142:145], v[210:213], v[28:31]
	v_mfma_f32_16x16x32_bf16 v[24:27], v[154:157], v[210:213], v[24:27]
	v_mfma_f32_16x16x32_bf16 v[12:15], v[142:145], v[218:221], v[12:15]
	v_mfma_f32_16x16x32_bf16 v[8:11], v[154:157], v[218:221], v[8:11]
	v_mfma_f32_16x16x32_bf16 v[60:63], v[150:153], v[186:189], v[60:63]
	v_mfma_f32_16x16x32_bf16 v[56:59], v[162:165], v[186:189], v[56:59]
	v_mfma_f32_16x16x32_bf16 v[44:47], v[150:153], v[206:209], v[44:47]
	v_mfma_f32_16x16x32_bf16 v[40:43], v[162:165], v[206:209], v[40:43]
	v_mfma_f32_16x16x32_bf16 v[28:31], v[150:153], v[214:217], v[28:31]
	v_mfma_f32_16x16x32_bf16 v[24:27], v[162:165], v[214:217], v[24:27]
	v_mfma_f32_16x16x32_bf16 v[12:15], v[150:153], v[222:225], v[12:15]
	v_mfma_f32_16x16x32_bf16 v[8:11], v[162:165], v[222:225], v[8:11]
	s_setprio 0
	s_setprio 1
	v_mfma_f32_16x16x32_bf16 v[52:55], v[166:169], v[182:185], v[52:55]
	v_mfma_f32_16x16x32_bf16 v[48:51], v[174:177], v[182:185], v[48:51]
	v_mfma_f32_16x16x32_bf16 v[36:39], v[166:169], v[202:205], v[36:39]
	v_mfma_f32_16x16x32_bf16 v[32:35], v[174:177], v[202:205], v[32:35]
	v_mfma_f32_16x16x32_bf16 v[20:23], v[166:169], v[210:213], v[20:23]
	v_mfma_f32_16x16x32_bf16 v[16:19], v[174:177], v[210:213], v[16:19]
	v_mfma_f32_16x16x32_bf16 v[4:7], v[166:169], v[218:221], v[4:7]
	v_mfma_f32_16x16x32_bf16 v[0:3], v[174:177], v[218:221], v[0:3]
	v_mfma_f32_16x16x32_bf16 v[52:55], v[170:173], v[186:189], v[52:55]
	v_mfma_f32_16x16x32_bf16 v[48:51], v[178:181], v[186:189], v[48:51]
	v_mfma_f32_16x16x32_bf16 v[36:39], v[170:173], v[206:209], v[36:39]
	v_mfma_f32_16x16x32_bf16 v[32:35], v[178:181], v[206:209], v[32:35]
	v_mfma_f32_16x16x32_bf16 v[20:23], v[170:173], v[214:217], v[20:23]
	v_mfma_f32_16x16x32_bf16 v[16:19], v[178:181], v[214:217], v[16:19]
	v_mfma_f32_16x16x32_bf16 v[4:7], v[170:173], v[222:225], v[4:7]
	v_mfma_f32_16x16x32_bf16 v[0:3], v[178:181], v[222:225], v[0:3]
	s_setprio 0
	s_barrier
	v_lshl_add_u64 v[226:227], s[28:29], 0, v[130:131]
	v_lshl_add_u64 v[228:229], s[28:29], 0, v[134:135]
	s_mov_b32 m0, s31
	s_nop 0
	global_load_lds_dwordx4 v[226:227], off
	s_mov_b32 m0, s42
	s_nop 0
	global_load_lds_dwordx4 v[228:229], off
	s_add_i32 s46, 0, 0x18000
	v_add_u32_e32 v96, s46, v159
	s_add_i32 s72, 0, 0x1c000
	ds_read_b128 v[142:145], v96
	ds_read_b128 v[150:153], v96 offset:1024
	ds_read_b128 v[154:157], v96 offset:2048
	ds_read_b128 v[162:165], v96 offset:3072
	v_add_u32_e32 v96, s72, v159
	ds_read_b128 v[166:169], v96
	ds_read_b128 v[170:173], v96 offset:1024
	ds_read_b128 v[174:177], v96 offset:2048
	ds_read_b128 v[178:181], v96 offset:3072
	s_add_u32 s28, s28, 0x20000
	s_addc_u32 s29, s29, 0
	s_mov_b32 m0, s43
	v_lshl_add_u64 v[230:231], s[28:29], 0, v[130:131]
	ds_read_b128 v[182:185], v161 offset:32768
	ds_read_b128 v[186:189], v161 offset:33792
	ds_read_b128 v[202:205], v161 offset:34816
	ds_read_b128 v[206:209], v161 offset:35840
	ds_read_b128 v[210:213], v161 offset:36864
	ds_read_b128 v[214:217], v161 offset:37888
	ds_read_b128 v[218:221], v161 offset:38912
	ds_read_b128 v[222:225], v161 offset:39936
	global_load_lds_dwordx4 v[230:231], off
	v_lshl_add_u64 v[230:231], s[28:29], 0, v[134:135]
	s_mov_b32 m0, s44
	s_nop 0
	global_load_lds_dwordx4 v[230:231], off
	s_waitcnt vmcnt(8)
	s_waitcnt lgkmcnt(0)
	s_barrier
	s_setprio 1
	s_waitcnt lgkmcnt(0)
	v_mfma_f32_16x16x32_bf16 v[126:129], v[142:145], v[182:185], v[126:129]
	v_mfma_f32_16x16x32_bf16 v[122:125], v[154:157], v[182:185], v[122:125]
	v_mfma_f32_16x16x32_bf16 v[110:113], v[142:145], v[202:205], v[110:113]
	v_mfma_f32_16x16x32_bf16 v[106:109], v[154:157], v[202:205], v[106:109]
	v_mfma_f32_16x16x32_bf16 v[92:95], v[142:145], v[210:213], v[92:95]
	v_mfma_f32_16x16x32_bf16 v[88:91], v[154:157], v[210:213], v[88:91]
	v_mfma_f32_16x16x32_bf16 v[76:79], v[142:145], v[218:221], v[76:79]
	v_mfma_f32_16x16x32_bf16 v[72:75], v[154:157], v[218:221], v[72:75]
	v_mfma_f32_16x16x32_bf16 v[126:129], v[150:153], v[186:189], v[126:129]
	v_mfma_f32_16x16x32_bf16 v[122:125], v[162:165], v[186:189], v[122:125]
	v_mfma_f32_16x16x32_bf16 v[110:113], v[150:153], v[206:209], v[110:113]
	v_mfma_f32_16x16x32_bf16 v[106:109], v[162:165], v[206:209], v[106:109]
	v_mfma_f32_16x16x32_bf16 v[92:95], v[150:153], v[214:217], v[92:95]
	v_mfma_f32_16x16x32_bf16 v[88:91], v[162:165], v[214:217], v[88:91]
	v_mfma_f32_16x16x32_bf16 v[76:79], v[150:153], v[222:225], v[76:79]
	v_mfma_f32_16x16x32_bf16 v[72:75], v[162:165], v[222:225], v[72:75]
	s_setprio 0
	s_setprio 1
	v_mfma_f32_16x16x32_bf16 v[118:121], v[166:169], v[182:185], v[118:121]
	v_mfma_f32_16x16x32_bf16 v[114:117], v[174:177], v[182:185], v[114:117]
	v_mfma_f32_16x16x32_bf16 v[102:105], v[166:169], v[202:205], v[102:105]
	v_mfma_f32_16x16x32_bf16 v[98:101], v[174:177], v[202:205], v[98:101]
	v_mfma_f32_16x16x32_bf16 v[84:87], v[166:169], v[210:213], v[84:87]
	v_mfma_f32_16x16x32_bf16 v[80:83], v[174:177], v[210:213], v[80:83]
	v_mfma_f32_16x16x32_bf16 v[68:71], v[166:169], v[218:221], v[68:71]
	v_mfma_f32_16x16x32_bf16 v[64:67], v[174:177], v[218:221], v[64:67]
	v_mfma_f32_16x16x32_bf16 v[118:121], v[170:173], v[186:189], v[118:121]
	v_mfma_f32_16x16x32_bf16 v[114:117], v[178:181], v[186:189], v[114:117]
	v_mfma_f32_16x16x32_bf16 v[102:105], v[170:173], v[206:209], v[102:105]
	v_mfma_f32_16x16x32_bf16 v[98:101], v[178:181], v[206:209], v[98:101]
	v_mfma_f32_16x16x32_bf16 v[84:87], v[170:173], v[214:217], v[84:87]
	v_mfma_f32_16x16x32_bf16 v[80:83], v[178:181], v[214:217], v[80:83]
	v_mfma_f32_16x16x32_bf16 v[68:71], v[170:173], v[222:225], v[68:71]
	v_mfma_f32_16x16x32_bf16 v[64:67], v[178:181], v[222:225], v[64:67]
	s_setprio 0
	s_barrier
; __device__ __forceinline__ int lane_id_v() { int l; asm volatile("v_mbcnt_lo_u32_b32 %0, -1, 0\n\tv_mbcnt_hi_u32_b32 %0, -1, %0" : "=v"(l)); return l; }
; #define PG8_STAGE(bufoff, gbase, voff) do { _Pragma("unroll") for (int _i = 0; _i < 2; ++_i) \
;         __builtin_amdgcn_global_load_lds((const unsigned*)((const char*)(gbase) + (voff)[_i]), (PG8_LAS unsigned*)(lds + (bufoff) + ldsw + _i * 8192), 16, 0, 0); } while (0)
; #define PG8_LDA(dst, b, h) do { _Pragma("unroll") for (int m = 0; m < 4; ++m) _Pragma("unroll") for (int k = 0; k < 2; ++k) dst[m][k] = *(const PG8_LAS bf16x8*)(lds + PG8_SA(b, h) + aoff + m * 2048 + k * 1024); } while (0)
; #define PG8_BAR __builtin_amdgcn_s_barrier()
; template <class Epi, class Sched, bool ALIGN_EPI = false, bool SP2 = false>
; __device__ __forceinline__ void gemm_phase(PG8_LAS unsigned char* lds, const Gemm g, const Sched& S, const Epi& E, const int tid_in) {
;     ...
;             PG8_LDB(B0, 0, 0); PG8_LDB(B1, 0, 1); PG8_SCHED; PG8_LDA(At, 0, 0); PG8_STAGE(PG8_SA(1, 1), a1 + hstepA, voffA);
;             PG8_WAIT_V(8); PG8_WAIT_L(0); PG8_BAR; PG8_MMA(0, 0, At, B0); PG8_MMA(0, 1, At, B1); PG8_BAR; PG8_SCHED;
;             PG8_LDA(At, 0, 1); PG8_STAGE(PG8_SB(0, 0), b2, voffB); PG8_STAGE(PG8_SB(0, 1), b2 + hstepB, voffB); PG8_STAGE(PG8_SA(0, 0), a2, voffA);
;             PG8_WAIT_V(8); PG8_WAIT_L(0); PG8_BAR; PG8_MMA(1, 0, At, B0); PG8_MMA(1, 1, At, B1); PG8_BAR; PG8_SCHED;
;             PG8_LDB(B0, 1, 0); PG8_LDB(B1, 1, 1); PG8_SCHED; PG8_LDA(At, 1, 0); PG8_STAGE(PG8_SA(0, 1), a2 + hstepA, voffA);
;             PG8_WAIT_V(8); PG8_WAIT_L(0); PG8_BAR; PG8_MMA(0, 0, At, B0); PG8_MMA(0, 1, At, B1); PG8_BAR; PG8_SCHED;
;             PG8_LDA(At, 1, 1); PG8_STAGE(PG8_SB(1, 0), b3, voffB); PG8_STAGE(PG8_SB(1, 1), b3 + hstepB, voffB); PG8_STAGE(PG8_SA(1, 0), a3, voffA);
;             PG8_WAIT_V(8); PG8_WAIT_L(0); PG8_BAR; PG8_MMA(1, 0, At, B0); PG8_MMA(1, 1, At, B1); PG8_BAR; PG8_SCHED;
; __global__ void __launch_bounds__(512, 2) mega(Args a_unused) {
;     ...
;                 { pg8::Gemm g{(const bf16_t*)(ws + WS_DYY), (const bf16_t*)(ws + WS_WBR) + (size_t)l * 3072 * 512, 3 * M, 3072, 512, 0, 0}; pg8::BranchOrder S{G, c};
;                   pg8::EpiMerge E{(const bf16_t*)(ws + WS_GT), (float*)(ws + WS_XA), H};
;                   pg8::gemm_phase<pg8::EpiMerge, pg8::BranchOrder, true, true>(lds, g, S, E, wave_s * 64 + lane_id_v()); }
	s_add_i32 s28, s46, s30
	v_lshl_add_u64 v[146:147], v[146:147], 0, s[68:69]
	s_mov_b32 m0, s28
	ds_read_b128 v[182:185], v161 offset:49152
	ds_read_b128 v[186:189], v161 offset:50176
	ds_read_b128 v[202:205], v161 offset:51200
	ds_read_b128 v[206:209], v161 offset:52224
	ds_read_b128 v[210:213], v161 offset:53248
	ds_read_b128 v[214:217], v161 offset:54272
	ds_read_b128 v[218:221], v161 offset:55296
	ds_read_b128 v[222:225], v161 offset:56320
	global_load_lds_dwordx4 v[146:147], off
	s_add_i32 m0, s28, 0x2000
	s_add_u32 s22, s22, 0x20080
	v_lshl_add_u64 v[146:147], v[148:149], 0, s[68:69]
	s_addc_u32 s23, s23, 0
	s_add_i32 s28, s72, s30
	global_load_lds_dwordx4 v[146:147], off
	v_lshl_add_u64 v[146:147], s[22:23], 0, v[132:133]
	s_mov_b32 m0, s28
	s_nop 0
	global_load_lds_dwordx4 v[146:147], off
	v_lshl_add_u64 v[146:147], s[22:23], 0, v[136:137]
	s_add_i32 m0, s28, 0x2000
	s_nop 0
	global_load_lds_dwordx4 v[146:147], off
	v_lshl_add_u64 v[146:147], v[226:227], 0, s[68:69]
	s_mov_b32 m0, s45
	s_nop 0
	global_load_lds_dwordx4 v[146:147], off
	v_lshl_add_u64 v[146:147], v[228:229], 0, s[68:69]
	s_mov_b32 m0, s52
	s_nop 0
	global_load_lds_dwordx4 v[146:147], off
	s_waitcnt vmcnt(8)
	s_waitcnt lgkmcnt(0)
	s_barrier
	s_setprio 1
	s_waitcnt lgkmcnt(0)
	v_mfma_f32_16x16x32_bf16 v[60:63], v[142:145], v[182:185], v[60:63]
	v_mfma_f32_16x16x32_bf16 v[56:59], v[154:157], v[182:185], v[56:59]
	v_mfma_f32_16x16x32_bf16 v[44:47], v[142:145], v[202:205], v[44:47]
	v_mfma_f32_16x16x32_bf16 v[40:43], v[154:157], v[202:205], v[40:43]
	v_mfma_f32_16x16x32_bf16 v[28:31], v[142:145], v[210:213], v[28:31]
	v_mfma_f32_16x16x32_bf16 v[24:27], v[154:157], v[210:213], v[24:27]
	v_mfma_f32_16x16x32_bf16 v[12:15], v[142:145], v[218:221], v[12:15]
	v_mfma_f32_16x16x32_bf16 v[8:11], v[154:157], v[218:221], v[8:11]
	v_mfma_f32_16x16x32_bf16 v[60:63], v[150:153], v[186:189], v[60:63]
	v_mfma_f32_16x16x32_bf16 v[56:59], v[162:165], v[186:189], v[56:59]
	v_mfma_f32_16x16x32_bf16 v[44:47], v[150:153], v[206:209], v[44:47]
	v_mfma_f32_16x16x32_bf16 v[40:43], v[162:165], v[206:209], v[40:43]
	v_mfma_f32_16x16x32_bf16 v[28:31], v[150:153], v[214:217], v[28:31]
	v_mfma_f32_16x16x32_bf16 v[24:27], v[162:165], v[214:217], v[24:27]
	v_mfma_f32_16x16x32_bf16 v[12:15], v[150:153], v[222:225], v[12:15]
	v_mfma_f32_16x16x32_bf16 v[8:11], v[162:165], v[222:225], v[8:11]
	s_setprio 0
	s_setprio 1
	v_mfma_f32_16x16x32_bf16 v[52:55], v[166:169], v[182:185], v[52:55]
	v_mfma_f32_16x16x32_bf16 v[48:51], v[174:177], v[182:185], v[48:51]
	v_mfma_f32_16x16x32_bf16 v[36:39], v[166:169], v[202:205], v[36:39]
	v_mfma_f32_16x16x32_bf16 v[32:35], v[174:177], v[202:205], v[32:35]
	v_mfma_f32_16x16x32_bf16 v[20:23], v[166:169], v[210:213], v[20:23]
	v_mfma_f32_16x16x32_bf16 v[16:19], v[174:177], v[210:213], v[16:19]
	v_mfma_f32_16x16x32_bf16 v[4:7], v[166:169], v[218:221], v[4:7]
	v_mfma_f32_16x16x32_bf16 v[0:3], v[174:177], v[218:221], v[0:3]
	v_mfma_f32_16x16x32_bf16 v[52:55], v[170:173], v[186:189], v[52:55]
	v_mfma_f32_16x16x32_bf16 v[48:51], v[178:181], v[186:189], v[48:51]
	v_mfma_f32_16x16x32_bf16 v[36:39], v[170:173], v[206:209], v[36:39]
	v_mfma_f32_16x16x32_bf16 v[32:35], v[178:181], v[206:209], v[32:35]
	v_mfma_f32_16x16x32_bf16 v[20:23], v[170:173], v[214:217], v[20:23]
	v_mfma_f32_16x16x32_bf16 v[16:19], v[178:181], v[214:217], v[16:19]
	v_mfma_f32_16x16x32_bf16 v[4:7], v[170:173], v[222:225], v[4:7]
	v_mfma_f32_16x16x32_bf16 v[0:3], v[178:181], v[222:225], v[0:3]
	s_setprio 0
	s_barrier
	s_add_i32 s71, s71, 2
	s_add_u32 s20, s20, 0x100
	s_addc_u32 s21, s21, 0
	s_add_u32 s60, s60, 0x100
	s_addc_u32 s70, s70, 0
	s_cmp_gt_u32 s71, 5
	s_cbranch_scc0 .LBB0_293
	s_and_b64 vcc, exec, s[8:9]
	s_cbranch_vccz .LBB0_296
	s_barrier

; __device__ __forceinline__ int lane_id_v() { int l; asm volatile("v_mbcnt_lo_u32_b32 %0, -1, 0\n\tv_mbcnt_hi_u32_b32 %0, -1, %0" : "=v"(l)); return l; }
; #define PG8_STAGE(bufoff, gbase, voff) do { _Pragma("unroll") for (int _i = 0; _i < 2; ++_i) \
;         __builtin_amdgcn_global_load_lds((const unsigned*)((const char*)(gbase) + (voff)[_i]), (PG8_LAS unsigned*)(lds + (bufoff) + ldsw + _i * 8192), 16, 0, 0); } while (0)
; #define PG8_LDA(dst, b, h) do { _Pragma("unroll") for (int m = 0; m < 4; ++m) _Pragma("unroll") for (int k = 0; k < 2; ++k) dst[m][k] = *(const PG8_LAS bf16x8*)(lds + PG8_SA(b, h) + aoff + m * 2048 + k * 1024); } while (0)
; template <class Epi, class Sched, bool ALIGN_EPI = false, bool SP2 = false>
; __device__ __forceinline__ void gemm_phase(PG8_LAS unsigned char* lds, const Gemm g, const Sched& S, const Epi& E, const int tid_in) {
;     ...
;             PG8_LDB(B0, 0, 0); PG8_LDB(B1, 0, 1); PG8_SCHED; PG8_LDA(At, 0, 0); PG8_STAGE(PG8_SA(1, 1), a1 + hstepA, voffA);
;             PG8_WAIT_V(8); PG8_WAIT_L(0); PG8_BAR; PG8_MMA(0, 0, At, B0); PG8_MMA(0, 1, At, B1); PG8_BAR; PG8_SCHED;
;             PG8_LDA(At, 0, 1); PG8_STAGE(PG8_SB(0, 0), b2, voffB); PG8_STAGE(PG8_SB(0, 1), b2 + hstepB, voffB); PG8_STAGE(PG8_SA(0, 0), a2, voffA);
;             PG8_WAIT_V(8); PG8_WAIT_L(0); PG8_BAR; PG8_MMA(1, 0, At, B0); PG8_MMA(1, 1, At, B1); PG8_BAR; PG8_SCHED;
;             PG8_LDB(B0, 1, 0); PG8_LDB(B1, 1, 1); PG8_SCHED; PG8_LDA(At, 1, 0); PG8_STAGE(PG8_SA(0, 1), a2 + hstepA, voffA);
;             PG8_WAIT_V(8); PG8_WAIT_L(0); PG8_BAR; PG8_MMA(0, 0, At, B0); PG8_MMA(0, 1, At, B1); PG8_BAR; PG8_SCHED;
;             PG8_LDA(At, 1, 1); PG8_STAGE(PG8_SB(1, 0), b3, voffB); PG8_STAGE(PG8_SB(1, 1), b3 + hstepB, voffB); PG8_STAGE(PG8_SA(1, 0), a3, voffA);
;             PG8_WAIT_V(8); PG8_WAIT_L(0); PG8_BAR; PG8_MMA(1, 0, At, B0); PG8_MMA(1, 1, At, B1); PG8_BAR; PG8_SCHED;
; __global__ void __launch_bounds__(512, 2) mega(Args a_unused) {
;     ...
;                 pg8::Gemm g{(const bf16_t*)(ws + WS_YC0), (const bf16_t*)(ws + WS_WGLU) + (size_t)l * 512 * 512, M, 512, 512}; pg8::StaticOrder S; S.init(M, 512, G, c);
;                 pg8::EpiGlu E{(const bf16_t*)(ws + WS_YC0), (bf16_t*)(ws + WS_DYY) + (size_t)2 * M * 512};
;                 pg8::gemm_phase<pg8::EpiGlu, pg8::StaticOrder, true, true>(lds, g, S, E, wave_s * 64 + lane_id_v());
.LBB0_468:
	s_add_u32 s22, s20, 0xfffe0080
	s_addc_u32 s23, s21, -1
	s_add_i32 s46, 0, 0x10000
	s_cmp_eq_u32 s70, 4
	s_cselect_b32 s29, s13, s23
	s_cselect_b32 s28, s54, s22
	v_add_u32_e32 v146, s46, v150
	s_cselect_b32 s23, s11, s60
	s_cselect_b32 s22, s55, s56
	s_add_i32 s71, 0, 0x14000
	ds_read_b128 v[142:145], v146
	ds_read_b128 v[154:157], v146 offset:1024
	ds_read_b128 v[158:161], v146 offset:2048
	ds_read_b128 v[162:165], v146 offset:3072
	v_add_u32_e32 v146, s71, v150
	ds_read_b128 v[166:169], v146
	ds_read_b128 v[170:173], v146 offset:1024
	ds_read_b128 v[174:177], v146 offset:2048
	ds_read_b128 v[178:181], v146 offset:3072
	v_lshl_add_u64 v[146:147], s[20:21], 0, v[138:139]
	s_add_i32 m0, s19, 0xc000
	ds_read_b128 v[182:185], v152
	ds_read_b128 v[186:189], v152 offset:1024
	ds_read_b128 v[202:205], v152 offset:2048
	ds_read_b128 v[206:209], v152 offset:3072
	ds_read_b128 v[210:213], v152 offset:4096
	ds_read_b128 v[214:217], v152 offset:5120
	ds_read_b128 v[218:221], v152 offset:6144
	ds_read_b128 v[222:225], v152 offset:7168
	global_load_lds_dwordx4 v[146:147], off
	v_lshl_add_u64 v[146:147], s[20:21], 0, v[140:141]
	s_add_i32 m0, s19, 0xe000
	s_nop 0
	global_load_lds_dwordx4 v[146:147], off
	s_waitcnt vmcnt(8)
	s_waitcnt lgkmcnt(0)
	s_barrier
	s_setprio 1
	s_waitcnt lgkmcnt(0)
	v_mfma_f32_16x16x32_bf16 v[126:129], v[142:145], v[182:185], v[126:129]
	v_mfma_f32_16x16x32_bf16 v[122:125], v[158:161], v[182:185], v[122:125]
	v_mfma_f32_16x16x32_bf16 v[110:113], v[142:145], v[202:205], v[110:113]
	v_mfma_f32_16x16x32_bf16 v[106:109], v[158:161], v[202:205], v[106:109]
	v_mfma_f32_16x16x32_bf16 v[92:95], v[142:145], v[210:213], v[92:95]
	v_mfma_f32_16x16x32_bf16 v[88:91], v[158:161], v[210:213], v[88:91]
	v_mfma_f32_16x16x32_bf16 v[76:79], v[142:145], v[218:221], v[76:79]
	v_mfma_f32_16x16x32_bf16 v[72:75], v[158:161], v[218:221], v[72:75]
	v_mfma_f32_16x16x32_bf16 v[126:129], v[154:157], v[186:189], v[126:129]
	v_mfma_f32_16x16x32_bf16 v[122:125], v[162:165], v[186:189], v[122:125]
	v_mfma_f32_16x16x32_bf16 v[110:113], v[154:157], v[206:209], v[110:113]
	v_mfma_f32_16x16x32_bf16 v[106:109], v[162:165], v[206:209], v[106:109]
	v_mfma_f32_16x16x32_bf16 v[92:95], v[154:157], v[214:217], v[92:95]
	v_mfma_f32_16x16x32_bf16 v[88:91], v[162:165], v[214:217], v[88:91]
	v_mfma_f32_16x16x32_bf16 v[76:79], v[154:157], v[222:225], v[76:79]
	v_mfma_f32_16x16x32_bf16 v[72:75], v[162:165], v[222:225], v[72:75]
	s_setprio 0
	s_setprio 1
	v_mfma_f32_16x16x32_bf16 v[118:121], v[166:169], v[182:185], v[118:121]
	v_mfma_f32_16x16x32_bf16 v[114:117], v[174:177], v[182:185], v[114:117]
	v_mfma_f32_16x16x32_bf16 v[102:105], v[166:169], v[202:205], v[102:105]
	v_mfma_f32_16x16x32_bf16 v[98:101], v[174:177], v[202:205], v[98:101]
	v_mfma_f32_16x16x32_bf16 v[84:87], v[166:169], v[210:213], v[84:87]
	v_mfma_f32_16x16x32_bf16 v[80:83], v[174:177], v[210:213], v[80:83]
	v_mfma_f32_16x16x32_bf16 v[68:71], v[166:169], v[218:221], v[68:71]
	v_mfma_f32_16x16x32_bf16 v[64:67], v[174:177], v[218:221], v[64:67]
	v_mfma_f32_16x16x32_bf16 v[118:121], v[170:173], v[186:189], v[118:121]
	v_mfma_f32_16x16x32_bf16 v[114:117], v[178:181], v[186:189], v[114:117]
	v_mfma_f32_16x16x32_bf16 v[102:105], v[170:173], v[206:209], v[102:105]
	v_mfma_f32_16x16x32_bf16 v[98:101], v[178:181], v[206:209], v[98:101]
	v_mfma_f32_16x16x32_bf16 v[84:87], v[170:173], v[214:217], v[84:87]
	v_mfma_f32_16x16x32_bf16 v[80:83], v[178:181], v[214:217], v[80:83]
	v_mfma_f32_16x16x32_bf16 v[68:71], v[170:173], v[222:225], v[68:71]
	v_mfma_f32_16x16x32_bf16 v[64:67], v[178:181], v[222:225], v[64:67]
	s_setprio 0
	s_barrier
	s_add_i32 s46, s46, s39
	v_lshl_add_u64 v[146:147], s[22:23], 0, v[132:133]
	s_mov_b32 m0, s46
	ds_read_b128 v[182:185], v152 offset:16384
	ds_read_b128 v[186:189], v152 offset:17408
	ds_read_b128 v[202:205], v152 offset:18432
	ds_read_b128 v[206:209], v152 offset:19456
	ds_read_b128 v[210:213], v152 offset:20480
	ds_read_b128 v[214:217], v152 offset:21504
	ds_read_b128 v[218:221], v152 offset:22528
	ds_read_b128 v[222:225], v152 offset:23552
	global_load_lds_dwordx4 v[146:147], off
	s_add_i32 m0, s46, 0x2000
	s_add_u32 s72, s22, 0x20000
	v_lshl_add_u64 v[148:149], s[22:23], 0, v[136:137]
	s_addc_u32 s73, s23, 0
	s_add_i32 s46, s71, s39
	global_load_lds_dwordx4 v[148:149], off
	v_lshl_add_u64 v[226:227], s[72:73], 0, v[132:133]
	s_mov_b32 m0, s46
	global_load_lds_dwordx4 v[226:227], off
	v_lshl_add_u64 v[226:227], s[72:73], 0, v[136:137]
	s_add_i32 m0, s46, 0x2000
	s_nop 0
	global_load_lds_dwordx4 v[226:227], off
	s_waitcnt vmcnt(6)
	s_waitcnt lgkmcnt(0)
	s_barrier
; __device__ __forceinline__ int lane_id_v() { int l; asm volatile("v_mbcnt_lo_u32_b32 %0, -1, 0\n\tv_mbcnt_hi_u32_b32 %0, -1, %0" : "=v"(l)); return l; }
; #define PG8_STAGE(bufoff, gbase, voff) do { _Pragma("unroll") for (int _i = 0; _i < 2; ++_i) \
;         __builtin_amdgcn_global_load_lds((const unsigned*)((const char*)(gbase) + (voff)[_i]), (PG8_LAS unsigned*)(lds + (bufoff) + ldsw + _i * 8192), 16, 0, 0); } while (0)
; #define PG8_LDA(dst, b, h) do { _Pragma("unroll") for (int m = 0; m < 4; ++m) _Pragma("unroll") for (int k = 0; k < 2; ++k) dst[m][k] = *(const PG8_LAS bf16x8*)(lds + PG8_SA(b, h) + aoff + m * 2048 + k * 1024); } while (0)
; template <class Epi, class Sched, bool ALIGN_EPI = false, bool SP2 = false>
; __device__ __forceinline__ void gemm_phase(PG8_LAS unsigned char* lds, const Gemm g, const Sched& S, const Epi& E, const int tid_in) {
;     ...
;             PG8_LDB(B0, 0, 0); PG8_LDB(B1, 0, 1); PG8_SCHED; PG8_LDA(At, 0, 0); PG8_STAGE(PG8_SA(1, 1), a1 + hstepA, voffA);
;             PG8_WAIT_V(8); PG8_WAIT_L(0); PG8_BAR; PG8_MMA(0, 0, At, B0); PG8_MMA(0, 1, At, B1); PG8_BAR; PG8_SCHED;
;             PG8_LDA(At, 0, 1); PG8_STAGE(PG8_SB(0, 0), b2, voffB); PG8_STAGE(PG8_SB(0, 1), b2 + hstepB, voffB); PG8_STAGE(PG8_SA(0, 0), a2, voffA);
;             PG8_WAIT_V(8); PG8_WAIT_L(0); PG8_BAR; PG8_MMA(1, 0, At, B0); PG8_MMA(1, 1, At, B1); PG8_BAR; PG8_SCHED;
;             PG8_LDB(B0, 1, 0); PG8_LDB(B1, 1, 1); PG8_SCHED; PG8_LDA(At, 1, 0); PG8_STAGE(PG8_SA(0, 1), a2 + hstepA, voffA);
;             PG8_WAIT_V(8); PG8_WAIT_L(0); PG8_BAR; PG8_MMA(0, 0, At, B0); PG8_MMA(0, 1, At, B1); PG8_BAR; PG8_SCHED;
;             PG8_LDA(At, 1, 1); PG8_STAGE(PG8_SB(1, 0), b3, voffB); PG8_STAGE(PG8_SB(1, 1), b3 + hstepB, voffB); PG8_STAGE(PG8_SA(1, 0), a3, voffA);
;             PG8_WAIT_V(8); PG8_WAIT_L(0); PG8_BAR; PG8_MMA(1, 0, At, B0); PG8_MMA(1, 1, At, B1); PG8_BAR; PG8_SCHED;
; __global__ void __launch_bounds__(512, 2) mega(Args a_unused) {
;     ...
;                 pg8::Gemm g{(const bf16_t*)(ws + WS_YC0), (const bf16_t*)(ws + WS_WGLU) + (size_t)l * 512 * 512, M, 512, 512}; pg8::StaticOrder S; S.init(M, 512, G, c);
;                 pg8::EpiGlu E{(const bf16_t*)(ws + WS_YC0), (bf16_t*)(ws + WS_DYY) + (size_t)2 * M * 512};
;                 pg8::gemm_phase<pg8::EpiGlu, pg8::StaticOrder, true, true>(lds, g, S, E, wave_s * 64 + lane_id_v());
	s_setprio 1
	s_waitcnt lgkmcnt(0)
	v_mfma_f32_16x16x32_bf16 v[60:63], v[142:145], v[182:185], v[60:63]
	v_mfma_f32_16x16x32_bf16 v[56:59], v[158:161], v[182:185], v[56:59]
	v_mfma_f32_16x16x32_bf16 v[44:47], v[142:145], v[202:205], v[44:47]
	v_mfma_f32_16x16x32_bf16 v[40:43], v[158:161], v[202:205], v[40:43]
	v_mfma_f32_16x16x32_bf16 v[28:31], v[142:145], v[210:213], v[28:31]
	v_mfma_f32_16x16x32_bf16 v[24:27], v[158:161], v[210:213], v[24:27]
	v_mfma_f32_16x16x32_bf16 v[12:15], v[142:145], v[218:221], v[12:15]
	v_mfma_f32_16x16x32_bf16 v[8:11], v[158:161], v[218:221], v[8:11]
	v_mfma_f32_16x16x32_bf16 v[60:63], v[154:157], v[186:189], v[60:63]
	v_mfma_f32_16x16x32_bf16 v[56:59], v[162:165], v[186:189], v[56:59]
	v_mfma_f32_16x16x32_bf16 v[44:47], v[154:157], v[206:209], v[44:47]
	v_mfma_f32_16x16x32_bf16 v[40:43], v[162:165], v[206:209], v[40:43]
	v_mfma_f32_16x16x32_bf16 v[28:31], v[154:157], v[214:217], v[28:31]
	v_mfma_f32_16x16x32_bf16 v[24:27], v[162:165], v[214:217], v[24:27]
	v_mfma_f32_16x16x32_bf16 v[12:15], v[154:157], v[222:225], v[12:15]
	v_mfma_f32_16x16x32_bf16 v[8:11], v[162:165], v[222:225], v[8:11]
	s_setprio 0
	s_setprio 1
	v_mfma_f32_16x16x32_bf16 v[52:55], v[166:169], v[182:185], v[52:55]
	v_mfma_f32_16x16x32_bf16 v[48:51], v[174:177], v[182:185], v[48:51]
	v_mfma_f32_16x16x32_bf16 v[36:39], v[166:169], v[202:205], v[36:39]
	v_mfma_f32_16x16x32_bf16 v[32:35], v[174:177], v[202:205], v[32:35]
	v_mfma_f32_16x16x32_bf16 v[20:23], v[166:169], v[210:213], v[20:23]
	v_mfma_f32_16x16x32_bf16 v[16:19], v[174:177], v[210:213], v[16:19]
	v_mfma_f32_16x16x32_bf16 v[4:7], v[166:169], v[218:221], v[4:7]
	v_mfma_f32_16x16x32_bf16 v[0:3], v[174:177], v[218:221], v[0:3]
	v_mfma_f32_16x16x32_bf16 v[52:55], v[170:173], v[186:189], v[52:55]
	v_mfma_f32_16x16x32_bf16 v[48:51], v[178:181], v[186:189], v[48:51]
	v_mfma_f32_16x16x32_bf16 v[36:39], v[170:173], v[206:209], v[36:39]
	v_mfma_f32_16x16x32_bf16 v[32:35], v[178:181], v[206:209], v[32:35]
	v_mfma_f32_16x16x32_bf16 v[20:23], v[170:173], v[214:217], v[20:23]
	v_mfma_f32_16x16x32_bf16 v[16:19], v[178:181], v[214:217], v[16:19]
	v_mfma_f32_16x16x32_bf16 v[4:7], v[170:173], v[222:225], v[4:7]
	v_mfma_f32_16x16x32_bf16 v[0:3], v[178:181], v[222:225], v[0:3]
	s_setprio 0
	s_barrier
	v_lshl_add_u64 v[226:227], s[28:29], 0, v[130:131]
	v_lshl_add_u64 v[228:229], s[28:29], 0, v[134:135]
	s_mov_b32 m0, s19
	s_nop 0
	global_load_lds_dwordx4 v[226:227], off
	s_mov_b32 m0, s40
	s_nop 0
	global_load_lds_dwordx4 v[228:229], off
	s_add_i32 s46, 0, 0x18000
	v_add_u32_e32 v153, s46, v150
	s_add_i32 s71, 0, 0x1c000
	ds_read_b128 v[142:145], v153
	ds_read_b128 v[154:157], v153 offset:1024
	ds_read_b128 v[158:161], v153 offset:2048
	ds_read_b128 v[162:165], v153 offset:3072
	v_add_u32_e32 v153, s71, v150
	ds_read_b128 v[166:169], v153
	ds_read_b128 v[170:173], v153 offset:1024
	ds_read_b128 v[174:177], v153 offset:2048
	ds_read_b128 v[178:181], v153 offset:3072
	s_add_u32 s28, s28, 0x20000
	s_addc_u32 s29, s29, 0
	s_mov_b32 m0, s41
	v_lshl_add_u64 v[230:231], s[28:29], 0, v[130:131]
	ds_read_b128 v[182:185], v152 offset:32768
	ds_read_b128 v[186:189], v152 offset:33792
	ds_read_b128 v[202:205], v152 offset:34816
	ds_read_b128 v[206:209], v152 offset:35840
	ds_read_b128 v[210:213], v152 offset:36864
	ds_read_b128 v[214:217], v152 offset:37888
	ds_read_b128 v[218:221], v152 offset:38912
	ds_read_b128 v[222:225], v152 offset:39936
	global_load_lds_dwordx4 v[230:231], off
	v_lshl_add_u64 v[230:231], s[28:29], 0, v[134:135]
	s_mov_b32 m0, s42
	s_nop 0
	global_load_lds_dwordx4 v[230:231], off
	s_waitcnt vmcnt(8)
	s_waitcnt lgkmcnt(0)
	s_barrier
	s_setprio 1
	s_waitcnt lgkmcnt(0)
	v_mfma_f32_16x16x32_bf16 v[126:129], v[142:145], v[182:185], v[126:129]
	v_mfma_f32_16x16x32_bf16 v[122:125], v[158:161], v[182:185], v[122:125]
	v_mfma_f32_16x16x32_bf16 v[110:113], v[142:145], v[202:205], v[110:113]
	v_mfma_f32_16x16x32_bf16 v[106:109], v[158:161], v[202:205], v[106:109]
	v_mfma_f32_16x16x32_bf16 v[92:95], v[142:145], v[210:213], v[92:95]
	v_mfma_f32_16x16x32_bf16 v[88:91], v[158:161], v[210:213], v[88:91]
	v_mfma_f32_16x16x32_bf16 v[76:79], v[142:145], v[218:221], v[76:79]
	v_mfma_f32_16x16x32_bf16 v[72:75], v[158:161], v[218:221], v[72:75]
	v_mfma_f32_16x16x32_bf16 v[126:129], v[154:157], v[186:189], v[126:129]
	v_mfma_f32_16x16x32_bf16 v[122:125], v[162:165], v[186:189], v[122:125]
	v_mfma_f32_16x16x32_bf16 v[110:113], v[154:157], v[206:209], v[110:113]
	v_mfma_f32_16x16x32_bf16 v[106:109], v[162:165], v[206:209], v[106:109]
	v_mfma_f32_16x16x32_bf16 v[92:95], v[154:157], v[214:217], v[92:95]
	v_mfma_f32_16x16x32_bf16 v[88:91], v[162:165], v[214:217], v[88:91]
	v_mfma_f32_16x16x32_bf16 v[76:79], v[154:157], v[222:225], v[76:79]
	v_mfma_f32_16x16x32_bf16 v[72:75], v[162:165], v[222:225], v[72:75]
	s_setprio 0
	s_setprio 1
	v_mfma_f32_16x16x32_bf16 v[118:121], v[166:169], v[182:185], v[118:121]
	v_mfma_f32_16x16x32_bf16 v[114:117], v[174:177], v[182:185], v[114:117]
	v_mfma_f32_16x16x32_bf16 v[102:105], v[166:169], v[202:205], v[102:105]
	v_mfma_f32_16x16x32_bf16 v[98:101], v[174:177], v[202:205], v[98:101]
	v_mfma_f32_16x16x32_bf16 v[84:87], v[166:169], v[210:213], v[84:87]
	v_mfma_f32_16x16x32_bf16 v[80:83], v[174:177], v[210:213], v[80:83]
	v_mfma_f32_16x16x32_bf16 v[68:71], v[166:169], v[218:221], v[68:71]
	v_mfma_f32_16x16x32_bf16 v[64:67], v[174:177], v[218:221], v[64:67]
	v_mfma_f32_16x16x32_bf16 v[118:121], v[170:173], v[186:189], v[118:121]
	v_mfma_f32_16x16x32_bf16 v[114:117], v[178:181], v[186:189], v[114:117]
	v_mfma_f32_16x16x32_bf16 v[102:105], v[170:173], v[206:209], v[102:105]
	v_mfma_f32_16x16x32_bf16 v[98:101], v[178:181], v[206:209], v[98:101]
	v_mfma_f32_16x16x32_bf16 v[84:87], v[170:173], v[214:217], v[84:87]
	v_mfma_f32_16x16x32_bf16 v[80:83], v[178:181], v[214:217], v[80:83]
	v_mfma_f32_16x16x32_bf16 v[68:71], v[170:173], v[222:225], v[68:71]
	v_mfma_f32_16x16x32_bf16 v[64:67], v[178:181], v[222:225], v[64:67]
	s_setprio 0
	s_barrier
; __device__ __forceinline__ int lane_id_v() { int l; asm volatile("v_mbcnt_lo_u32_b32 %0, -1, 0\n\tv_mbcnt_hi_u32_b32 %0, -1, %0" : "=v"(l)); return l; }
; #define PG8_STAGE(bufoff, gbase, voff) do { _Pragma("unroll") for (int _i = 0; _i < 2; ++_i) \
;         __builtin_amdgcn_global_load_lds((const unsigned*)((const char*)(gbase) + (voff)[_i]), (PG8_LAS unsigned*)(lds + (bufoff) + ldsw + _i * 8192), 16, 0, 0); } while (0)
; #define PG8_LDA(dst, b, h) do { _Pragma("unroll") for (int m = 0; m < 4; ++m) _Pragma("unroll") for (int k = 0; k < 2; ++k) dst[m][k] = *(const PG8_LAS bf16x8*)(lds + PG8_SA(b, h) + aoff + m * 2048 + k * 1024); } while (0)
; template <class Epi, class Sched, bool ALIGN_EPI = false, bool SP2 = false>
; __device__ __forceinline__ void gemm_phase(PG8_LAS unsigned char* lds, const Gemm g, const Sched& S, const Epi& E, const int tid_in) {
;     ...
;             PG8_LDB(B0, 0, 0); PG8_LDB(B1, 0, 1); PG8_SCHED; PG8_LDA(At, 0, 0); PG8_STAGE(PG8_SA(1, 1), a1 + hstepA, voffA);
;             PG8_WAIT_V(8); PG8_WAIT_L(0); PG8_BAR; PG8_MMA(0, 0, At, B0); PG8_MMA(0, 1, At, B1); PG8_BAR; PG8_SCHED;
;             PG8_LDA(At, 0, 1); PG8_STAGE(PG8_SB(0, 0), b2, voffB); PG8_STAGE(PG8_SB(0, 1), b2 + hstepB, voffB); PG8_STAGE(PG8_SA(0, 0), a2, voffA);
;             PG8_WAIT_V(8); PG8_WAIT_L(0); PG8_BAR; PG8_MMA(1, 0, At, B0); PG8_MMA(1, 1, At, B1); PG8_BAR; PG8_SCHED;
;             PG8_LDB(B0, 1, 0); PG8_LDB(B1, 1, 1); PG8_SCHED; PG8_LDA(At, 1, 0); PG8_STAGE(PG8_SA(0, 1), a2 + hstepA, voffA);
;             PG8_WAIT_V(8); PG8_WAIT_L(0); PG8_BAR; PG8_MMA(0, 0, At, B0); PG8_MMA(0, 1, At, B1); PG8_BAR; PG8_SCHED;
;             PG8_LDA(At, 1, 1); PG8_STAGE(PG8_SB(1, 0), b3, voffB); PG8_STAGE(PG8_SB(1, 1), b3 + hstepB, voffB); PG8_STAGE(PG8_SA(1, 0), a3, voffA);
;             PG8_WAIT_V(8); PG8_WAIT_L(0); PG8_BAR; PG8_MMA(1, 0, At, B0); PG8_MMA(1, 1, At, B1); PG8_BAR; PG8_SCHED;
; __global__ void __launch_bounds__(512, 2) mega(Args a_unused) {
;     ...
;                 pg8::Gemm g{(const bf16_t*)(ws + WS_YC0), (const bf16_t*)(ws + WS_WGLU) + (size_t)l * 512 * 512, M, 512, 512}; pg8::StaticOrder S; S.init(M, 512, G, c);
;                 pg8::EpiGlu E{(const bf16_t*)(ws + WS_YC0), (bf16_t*)(ws + WS_DYY) + (size_t)2 * M * 512};
;                 pg8::gemm_phase<pg8::EpiGlu, pg8::StaticOrder, true, true>(lds, g, S, E, wave_s * 64 + lane_id_v());
	s_add_i32 s28, s46, s39
	v_lshl_add_u64 v[146:147], v[146:147], 0, s[68:69]
	s_mov_b32 m0, s28
	ds_read_b128 v[182:185], v152 offset:49152
	ds_read_b128 v[186:189], v152 offset:50176
	ds_read_b128 v[202:205], v152 offset:51200
	ds_read_b128 v[206:209], v152 offset:52224
	ds_read_b128 v[210:213], v152 offset:53248
	ds_read_b128 v[214:217], v152 offset:54272
	ds_read_b128 v[218:221], v152 offset:55296
	ds_read_b128 v[222:225], v152 offset:56320
	global_load_lds_dwordx4 v[146:147], off
	s_add_i32 m0, s28, 0x2000
	s_add_u32 s22, s22, 0x20080
	v_lshl_add_u64 v[146:147], v[148:149], 0, s[68:69]
	s_addc_u32 s23, s23, 0
	s_add_i32 s28, s71, s39
	global_load_lds_dwordx4 v[146:147], off
	v_lshl_add_u64 v[146:147], s[22:23], 0, v[132:133]
	s_mov_b32 m0, s28
	s_nop 0
	global_load_lds_dwordx4 v[146:147], off
	v_lshl_add_u64 v[146:147], s[22:23], 0, v[136:137]
	s_add_i32 m0, s28, 0x2000
	s_nop 0
	global_load_lds_dwordx4 v[146:147], off
	v_lshl_add_u64 v[146:147], v[226:227], 0, s[68:69]
	s_mov_b32 m0, s43
	s_nop 0
	global_load_lds_dwordx4 v[146:147], off
	v_lshl_add_u64 v[146:147], v[228:229], 0, s[68:69]
	s_mov_b32 m0, s44
	s_nop 0
	global_load_lds_dwordx4 v[146:147], off
	s_waitcnt vmcnt(8)
	s_waitcnt lgkmcnt(0)
	s_barrier
	s_setprio 1
	s_waitcnt lgkmcnt(0)
	v_mfma_f32_16x16x32_bf16 v[60:63], v[142:145], v[182:185], v[60:63]
	v_mfma_f32_16x16x32_bf16 v[56:59], v[158:161], v[182:185], v[56:59]
	v_mfma_f32_16x16x32_bf16 v[44:47], v[142:145], v[202:205], v[44:47]
	v_mfma_f32_16x16x32_bf16 v[40:43], v[158:161], v[202:205], v[40:43]
	v_mfma_f32_16x16x32_bf16 v[28:31], v[142:145], v[210:213], v[28:31]
	v_mfma_f32_16x16x32_bf16 v[24:27], v[158:161], v[210:213], v[24:27]
	v_mfma_f32_16x16x32_bf16 v[12:15], v[142:145], v[218:221], v[12:15]
	v_mfma_f32_16x16x32_bf16 v[8:11], v[158:161], v[218:221], v[8:11]
	v_mfma_f32_16x16x32_bf16 v[60:63], v[154:157], v[186:189], v[60:63]
	v_mfma_f32_16x16x32_bf16 v[56:59], v[162:165], v[186:189], v[56:59]
	v_mfma_f32_16x16x32_bf16 v[44:47], v[154:157], v[206:209], v[44:47]
	v_mfma_f32_16x16x32_bf16 v[40:43], v[162:165], v[206:209], v[40:43]
	v_mfma_f32_16x16x32_bf16 v[28:31], v[154:157], v[214:217], v[28:31]
	v_mfma_f32_16x16x32_bf16 v[24:27], v[162:165], v[214:217], v[24:27]
	v_mfma_f32_16x16x32_bf16 v[12:15], v[154:157], v[222:225], v[12:15]
	v_mfma_f32_16x16x32_bf16 v[8:11], v[162:165], v[222:225], v[8:11]
	s_setprio 0
	s_setprio 1
	v_mfma_f32_16x16x32_bf16 v[52:55], v[166:169], v[182:185], v[52:55]
	v_mfma_f32_16x16x32_bf16 v[48:51], v[174:177], v[182:185], v[48:51]
	v_mfma_f32_16x16x32_bf16 v[36:39], v[166:169], v[202:205], v[36:39]
	v_mfma_f32_16x16x32_bf16 v[32:35], v[174:177], v[202:205], v[32:35]
	v_mfma_f32_16x16x32_bf16 v[20:23], v[166:169], v[210:213], v[20:23]
	v_mfma_f32_16x16x32_bf16 v[16:19], v[174:177], v[210:213], v[16:19]
	v_mfma_f32_16x16x32_bf16 v[4:7], v[166:169], v[218:221], v[4:7]
	v_mfma_f32_16x16x32_bf16 v[0:3], v[174:177], v[218:221], v[0:3]
	v_mfma_f32_16x16x32_bf16 v[52:55], v[170:173], v[186:189], v[52:55]
	v_mfma_f32_16x16x32_bf16 v[48:51], v[178:181], v[186:189], v[48:51]
	v_mfma_f32_16x16x32_bf16 v[36:39], v[170:173], v[206:209], v[36:39]
	v_mfma_f32_16x16x32_bf16 v[32:35], v[178:181], v[206:209], v[32:35]
	v_mfma_f32_16x16x32_bf16 v[20:23], v[170:173], v[214:217], v[20:23]
	v_mfma_f32_16x16x32_bf16 v[16:19], v[178:181], v[214:217], v[16:19]
	v_mfma_f32_16x16x32_bf16 v[4:7], v[170:173], v[222:225], v[4:7]
	v_mfma_f32_16x16x32_bf16 v[0:3], v[178:181], v[222:225], v[0:3]
	s_setprio 0
	s_barrier
	s_add_i32 s70, s70, 2
	s_add_u32 s20, s20, 0x100
	s_addc_u32 s21, s21, 0
	s_add_u32 s56, s56, 0x100
	s_addc_u32 s60, s60, 0
	s_cmp_gt_u32 s70, 5
	s_cbranch_scc0 .LBB0_468
	s_and_b64 vcc, exec, s[8:9]
	s_mov_b32 s46, 0xe00000
	s_mov_b32 s60, 0x1000000
	s_mov_b32 s70, 0x1200000
	s_cbranch_vccz .LBB0_471
	s_barrier

; #define PG8_STAGE(bufoff, gbase, voff) do { _Pragma("unroll") for (int _i = 0; _i < 2; ++_i) \
;         __builtin_amdgcn_global_load_lds((const unsigned*)((const char*)(gbase) + (voff)[_i]), (PG8_LAS unsigned*)(lds + (bufoff) + ldsw + _i * 8192), 16, 0, 0); } while (0)
; #define PG8_LDA(dst, b, h) do { _Pragma("unroll") for (int m = 0; m < 4; ++m) _Pragma("unroll") for (int k = 0; k < 2; ++k) dst[m][k] = *(const PG8_LAS bf16x8*)(lds + PG8_SA(b, h) + aoff + m * 2048 + k * 1024); } while (0)
; #define PG8_LDB(dst, b, h) do { _Pragma("unroll") for (int n = 0; n < 2; ++n) _Pragma("unroll") for (int k = 0; k < 2; ++k) dst[n][k] = *(const PG8_LAS bf16x8*)(lds + PG8_SB(b, h) + boff + n * 2048 + k * 1024); } while (0)
; #define PG8_MMA(ai, bj, At, Bt) do { __builtin_amdgcn_s_setprio(1); _Pragma("unroll") for (int m = 0; m < 4; ++m) _Pragma("unroll") for (int n = 0; n < 2; ++n) _Pragma("unroll") for (int k = 0; k < 2; ++k) \
;         acc[ai][bj][m][n] = __builtin_amdgcn_mfma_f32_16x16x32_bf16(Bt[n][k], At[m][k], acc[ai][bj][m][n], 0, 0, 0); __builtin_amdgcn_s_setprio(0); } while (0)
; #define PG8_BAR __builtin_amdgcn_s_barrier()
; template <class Epi, class Sched, bool ALIGN_EPI = false, bool SP2 = false>
; __device__ __forceinline__ void gemm_phase(PG8_LAS unsigned char* lds, const Gemm g, const Sched& S, const Epi& E, const int tid_in) {
;     ...
;             PG8_LDB(B0, 0, 0); PG8_LDB(B1, 0, 1); PG8_SCHED; PG8_LDA(At, 0, 0); PG8_STAGE(PG8_SA(1, 1), a1 + hstepA, voffA);
;             PG8_WAIT_V(8); PG8_WAIT_L(0); PG8_BAR; PG8_MMA(0, 0, At, B0); PG8_MMA(0, 1, At, B1); PG8_BAR; PG8_SCHED;
;             PG8_LDA(At, 0, 1); PG8_STAGE(PG8_SB(0, 0), b2, voffB); PG8_STAGE(PG8_SB(0, 1), b2 + hstepB, voffB); PG8_STAGE(PG8_SA(0, 0), a2, voffA);
;             PG8_WAIT_V(8); PG8_WAIT_L(0); PG8_BAR; PG8_MMA(1, 0, At, B0); PG8_MMA(1, 1, At, B1); PG8_BAR; PG8_SCHED;
;             PG8_LDB(B0, 1, 0); PG8_LDB(B1, 1, 1); PG8_SCHED; PG8_LDA(At, 1, 0); PG8_STAGE(PG8_SA(0, 1), a2 + hstepA, voffA);
;             PG8_WAIT_V(8); PG8_WAIT_L(0); PG8_BAR; PG8_MMA(0, 0, At, B0); PG8_MMA(0, 1, At, B1); PG8_BAR; PG8_SCHED;
;             PG8_LDA(At, 1, 1); PG8_STAGE(PG8_SB(1, 0), b3, voffB); PG8_STAGE(PG8_SB(1, 1), b3 + hstepB, voffB); PG8_STAGE(PG8_SA(1, 0), a3, voffA);
;             PG8_WAIT_V(8); PG8_WAIT_L(0); PG8_BAR; PG8_MMA(1, 0, At, B0); PG8_MMA(1, 1, At, B1); PG8_BAR; PG8_SCHED;
.LBB0_1027:
	s_add_u32 s18, s16, 0xfffc0080
	s_addc_u32 s19, s17, -1
	s_add_i32 s46, 0, 0x10000
	s_cmp_eq_u32 s70, 12
	s_cselect_b32 s21, s1, s19
	s_cselect_b32 s20, s15, s18
	v_add_u32_e32 v96, s46, v145
	s_cselect_b32 s19, s28, s56
	s_cselect_b32 s18, s29, s53
	s_add_i32 s71, 0, 0x14000
	ds_read_b128 v[130:133], v96
	ds_read_b128 v[172:175], v96 offset:1024
	ds_read_b128 v[176:179], v96 offset:2048
	ds_read_b128 v[180:183], v96 offset:3072
	v_add_u32_e32 v96, s71, v145
	ds_read_b128 v[184:187], v96
	ds_read_b128 v[202:205], v96 offset:1024
	ds_read_b128 v[206:209], v96 offset:2048
	ds_read_b128 v[210:213], v96 offset:3072
	v_lshl_add_u64 v[146:147], s[16:17], 0, v[168:169]
	s_add_i32 m0, s23, 0xc000
	ds_read_b128 v[214:217], v153
	ds_read_b128 v[218:221], v153 offset:1024
	ds_read_b128 v[222:225], v153 offset:2048
	ds_read_b128 v[226:229], v153 offset:3072
	ds_read_b128 v[230:233], v153 offset:4096
	ds_read_b128 v[234:237], v153 offset:5120
	ds_read_b128 v[238:241], v153 offset:6144
	ds_read_b128 v[242:245], v153 offset:7168
	global_load_lds_dwordx4 v[146:147], off
	v_lshl_add_u64 v[146:147], s[16:17], 0, v[170:171]
	s_add_i32 m0, s23, 0xe000
	s_nop 0
	global_load_lds_dwordx4 v[146:147], off
	s_waitcnt vmcnt(8)
	s_waitcnt lgkmcnt(0)
	s_barrier
	s_setprio 1
	s_waitcnt lgkmcnt(0)
	v_mfma_f32_16x16x32_bf16 v[126:129], v[130:133], v[214:217], v[126:129]
	v_mfma_f32_16x16x32_bf16 v[122:125], v[176:179], v[214:217], v[122:125]
	v_mfma_f32_16x16x32_bf16 v[110:113], v[130:133], v[222:225], v[110:113]
	v_mfma_f32_16x16x32_bf16 v[106:109], v[176:179], v[222:225], v[106:109]
	v_mfma_f32_16x16x32_bf16 v[92:95], v[130:133], v[230:233], v[92:95]
	v_mfma_f32_16x16x32_bf16 v[88:91], v[176:179], v[230:233], v[88:91]
	v_mfma_f32_16x16x32_bf16 v[76:79], v[130:133], v[238:241], v[76:79]
	v_mfma_f32_16x16x32_bf16 v[72:75], v[176:179], v[238:241], v[72:75]
	v_mfma_f32_16x16x32_bf16 v[126:129], v[172:175], v[218:221], v[126:129]
	v_mfma_f32_16x16x32_bf16 v[122:125], v[180:183], v[218:221], v[122:125]
	v_mfma_f32_16x16x32_bf16 v[110:113], v[172:175], v[226:229], v[110:113]
	v_mfma_f32_16x16x32_bf16 v[106:109], v[180:183], v[226:229], v[106:109]
	v_mfma_f32_16x16x32_bf16 v[92:95], v[172:175], v[234:237], v[92:95]
	v_mfma_f32_16x16x32_bf16 v[88:91], v[180:183], v[234:237], v[88:91]
	v_mfma_f32_16x16x32_bf16 v[76:79], v[172:175], v[242:245], v[76:79]
	v_mfma_f32_16x16x32_bf16 v[72:75], v[180:183], v[242:245], v[72:75]
	s_setprio 0
	s_setprio 1
	v_mfma_f32_16x16x32_bf16 v[118:121], v[184:187], v[214:217], v[118:121]
	v_mfma_f32_16x16x32_bf16 v[114:117], v[206:209], v[214:217], v[114:117]
	v_mfma_f32_16x16x32_bf16 v[102:105], v[184:187], v[222:225], v[102:105]
	v_mfma_f32_16x16x32_bf16 v[98:101], v[206:209], v[222:225], v[98:101]
	v_mfma_f32_16x16x32_bf16 v[84:87], v[184:187], v[230:233], v[84:87]
	v_mfma_f32_16x16x32_bf16 v[80:83], v[206:209], v[230:233], v[80:83]
	v_mfma_f32_16x16x32_bf16 v[68:71], v[184:187], v[238:241], v[68:71]
	v_mfma_f32_16x16x32_bf16 v[64:67], v[206:209], v[238:241], v[64:67]
	v_mfma_f32_16x16x32_bf16 v[118:121], v[202:205], v[218:221], v[118:121]
	v_mfma_f32_16x16x32_bf16 v[114:117], v[210:213], v[218:221], v[114:117]
	v_mfma_f32_16x16x32_bf16 v[102:105], v[202:205], v[226:229], v[102:105]
	v_mfma_f32_16x16x32_bf16 v[98:101], v[210:213], v[226:229], v[98:101]
	v_mfma_f32_16x16x32_bf16 v[84:87], v[202:205], v[234:237], v[84:87]
	v_mfma_f32_16x16x32_bf16 v[80:83], v[210:213], v[234:237], v[80:83]
	v_mfma_f32_16x16x32_bf16 v[68:71], v[202:205], v[242:245], v[68:71]
	v_mfma_f32_16x16x32_bf16 v[64:67], v[210:213], v[242:245], v[64:67]
	s_setprio 0
	s_barrier
	s_add_i32 s46, s46, s22
	v_lshl_add_u64 v[146:147], s[18:19], 0, v[136:137]
	s_mov_b32 m0, s46
	ds_read_b128 v[214:217], v153 offset:16384
	ds_read_b128 v[218:221], v153 offset:17408
	ds_read_b128 v[222:225], v153 offset:18432
	ds_read_b128 v[226:229], v153 offset:19456
	ds_read_b128 v[230:233], v153 offset:20480
	ds_read_b128 v[234:237], v153 offset:21504
	ds_read_b128 v[238:241], v153 offset:22528
	ds_read_b128 v[242:245], v153 offset:23552
	global_load_lds_dwordx4 v[146:147], off
	s_add_i32 m0, s46, 0x2000
	s_add_u32 s78, s18, 0x40000
	v_lshl_add_u64 v[148:149], s[18:19], 0, v[140:141]
	s_addc_u32 s79, s19, 0
	s_add_i32 s46, s71, s22
	global_load_lds_dwordx4 v[148:149], off
	v_lshl_add_u64 v[188:189], s[78:79], 0, v[136:137]
	s_mov_b32 m0, s46
	global_load_lds_dwordx4 v[188:189], off
	v_lshl_add_u64 v[188:189], s[78:79], 0, v[140:141]
	s_add_i32 m0, s46, 0x2000
	s_nop 0
	global_load_lds_dwordx4 v[188:189], off
	s_waitcnt vmcnt(6)
	s_waitcnt lgkmcnt(0)
	s_barrier
; #define PG8_STAGE(bufoff, gbase, voff) do { _Pragma("unroll") for (int _i = 0; _i < 2; ++_i) \
;         __builtin_amdgcn_global_load_lds((const unsigned*)((const char*)(gbase) + (voff)[_i]), (PG8_LAS unsigned*)(lds + (bufoff) + ldsw + _i * 8192), 16, 0, 0); } while (0)
; #define PG8_LDA(dst, b, h) do { _Pragma("unroll") for (int m = 0; m < 4; ++m) _Pragma("unroll") for (int k = 0; k < 2; ++k) dst[m][k] = *(const PG8_LAS bf16x8*)(lds + PG8_SA(b, h) + aoff + m * 2048 + k * 1024); } while (0)
; #define PG8_LDB(dst, b, h) do { _Pragma("unroll") for (int n = 0; n < 2; ++n) _Pragma("unroll") for (int k = 0; k < 2; ++k) dst[n][k] = *(const PG8_LAS bf16x8*)(lds + PG8_SB(b, h) + boff + n * 2048 + k * 1024); } while (0)
; #define PG8_MMA(ai, bj, At, Bt) do { __builtin_amdgcn_s_setprio(1); _Pragma("unroll") for (int m = 0; m < 4; ++m) _Pragma("unroll") for (int n = 0; n < 2; ++n) _Pragma("unroll") for (int k = 0; k < 2; ++k) \
;         acc[ai][bj][m][n] = __builtin_amdgcn_mfma_f32_16x16x32_bf16(Bt[n][k], At[m][k], acc[ai][bj][m][n], 0, 0, 0); __builtin_amdgcn_s_setprio(0); } while (0)
; #define PG8_BAR __builtin_amdgcn_s_barrier()
; template <class Epi, class Sched, bool ALIGN_EPI = false, bool SP2 = false>
; __device__ __forceinline__ void gemm_phase(PG8_LAS unsigned char* lds, const Gemm g, const Sched& S, const Epi& E, const int tid_in) {
;     ...
;             PG8_LDB(B0, 0, 0); PG8_LDB(B1, 0, 1); PG8_SCHED; PG8_LDA(At, 0, 0); PG8_STAGE(PG8_SA(1, 1), a1 + hstepA, voffA);
;             PG8_WAIT_V(8); PG8_WAIT_L(0); PG8_BAR; PG8_MMA(0, 0, At, B0); PG8_MMA(0, 1, At, B1); PG8_BAR; PG8_SCHED;
;             PG8_LDA(At, 0, 1); PG8_STAGE(PG8_SB(0, 0), b2, voffB); PG8_STAGE(PG8_SB(0, 1), b2 + hstepB, voffB); PG8_STAGE(PG8_SA(0, 0), a2, voffA);
;             PG8_WAIT_V(8); PG8_WAIT_L(0); PG8_BAR; PG8_MMA(1, 0, At, B0); PG8_MMA(1, 1, At, B1); PG8_BAR; PG8_SCHED;
;             PG8_LDB(B0, 1, 0); PG8_LDB(B1, 1, 1); PG8_SCHED; PG8_LDA(At, 1, 0); PG8_STAGE(PG8_SA(0, 1), a2 + hstepA, voffA);
;             PG8_WAIT_V(8); PG8_WAIT_L(0); PG8_BAR; PG8_MMA(0, 0, At, B0); PG8_MMA(0, 1, At, B1); PG8_BAR; PG8_SCHED;
;             PG8_LDA(At, 1, 1); PG8_STAGE(PG8_SB(1, 0), b3, voffB); PG8_STAGE(PG8_SB(1, 1), b3 + hstepB, voffB); PG8_STAGE(PG8_SA(1, 0), a3, voffA);
;             PG8_WAIT_V(8); PG8_WAIT_L(0); PG8_BAR; PG8_MMA(1, 0, At, B0); PG8_MMA(1, 1, At, B1); PG8_BAR; PG8_SCHED;
	s_setprio 1
	s_waitcnt lgkmcnt(0)
	v_mfma_f32_16x16x32_bf16 v[60:63], v[130:133], v[214:217], v[60:63]
	v_mfma_f32_16x16x32_bf16 v[56:59], v[176:179], v[214:217], v[56:59]
	v_mfma_f32_16x16x32_bf16 v[44:47], v[130:133], v[222:225], v[44:47]
	v_mfma_f32_16x16x32_bf16 v[40:43], v[176:179], v[222:225], v[40:43]
	v_mfma_f32_16x16x32_bf16 v[28:31], v[130:133], v[230:233], v[28:31]
	v_mfma_f32_16x16x32_bf16 v[24:27], v[176:179], v[230:233], v[24:27]
	v_mfma_f32_16x16x32_bf16 v[12:15], v[130:133], v[238:241], v[12:15]
	v_mfma_f32_16x16x32_bf16 v[8:11], v[176:179], v[238:241], v[8:11]
	v_mfma_f32_16x16x32_bf16 v[60:63], v[172:175], v[218:221], v[60:63]
	v_mfma_f32_16x16x32_bf16 v[56:59], v[180:183], v[218:221], v[56:59]
	v_mfma_f32_16x16x32_bf16 v[44:47], v[172:175], v[226:229], v[44:47]
	v_mfma_f32_16x16x32_bf16 v[40:43], v[180:183], v[226:229], v[40:43]
	v_mfma_f32_16x16x32_bf16 v[28:31], v[172:175], v[234:237], v[28:31]
	v_mfma_f32_16x16x32_bf16 v[24:27], v[180:183], v[234:237], v[24:27]
	v_mfma_f32_16x16x32_bf16 v[12:15], v[172:175], v[242:245], v[12:15]
	v_mfma_f32_16x16x32_bf16 v[8:11], v[180:183], v[242:245], v[8:11]
	s_setprio 0
	s_setprio 1
	v_mfma_f32_16x16x32_bf16 v[52:55], v[184:187], v[214:217], v[52:55]
	v_mfma_f32_16x16x32_bf16 v[48:51], v[206:209], v[214:217], v[48:51]
	v_mfma_f32_16x16x32_bf16 v[36:39], v[184:187], v[222:225], v[36:39]
	v_mfma_f32_16x16x32_bf16 v[32:35], v[206:209], v[222:225], v[32:35]
	v_mfma_f32_16x16x32_bf16 v[20:23], v[184:187], v[230:233], v[20:23]
	v_mfma_f32_16x16x32_bf16 v[16:19], v[206:209], v[230:233], v[16:19]
	v_mfma_f32_16x16x32_bf16 v[4:7], v[184:187], v[238:241], v[4:7]
	v_mfma_f32_16x16x32_bf16 v[0:3], v[206:209], v[238:241], v[0:3]
	v_mfma_f32_16x16x32_bf16 v[52:55], v[202:205], v[218:221], v[52:55]
	v_mfma_f32_16x16x32_bf16 v[48:51], v[210:213], v[218:221], v[48:51]
	v_mfma_f32_16x16x32_bf16 v[36:39], v[202:205], v[226:229], v[36:39]
	v_mfma_f32_16x16x32_bf16 v[32:35], v[210:213], v[226:229], v[32:35]
	v_mfma_f32_16x16x32_bf16 v[20:23], v[202:205], v[234:237], v[20:23]
	v_mfma_f32_16x16x32_bf16 v[16:19], v[210:213], v[234:237], v[16:19]
	v_mfma_f32_16x16x32_bf16 v[4:7], v[202:205], v[242:245], v[4:7]
	v_mfma_f32_16x16x32_bf16 v[0:3], v[210:213], v[242:245], v[0:3]
	s_setprio 0
	s_barrier
	v_lshl_add_u64 v[188:189], s[20:21], 0, v[134:135]
	v_lshl_add_u64 v[246:247], s[20:21], 0, v[138:139]
	s_mov_b32 m0, s23
	s_nop 0
	global_load_lds_dwordx4 v[188:189], off
	s_mov_b32 m0, s40
	s_nop 0
	global_load_lds_dwordx4 v[246:247], off
	s_add_i32 s46, 0, 0x18000
	v_add_u32_e32 v96, s46, v145
	s_add_i32 s71, 0, 0x1c000
	ds_read_b128 v[130:133], v96
	ds_read_b128 v[172:175], v96 offset:1024
	ds_read_b128 v[176:179], v96 offset:2048
	ds_read_b128 v[180:183], v96 offset:3072
	v_add_u32_e32 v96, s71, v145
	ds_read_b128 v[184:187], v96
	ds_read_b128 v[202:205], v96 offset:1024
	ds_read_b128 v[206:209], v96 offset:2048
	ds_read_b128 v[210:213], v96 offset:3072
	s_add_u32 s20, s20, 0x40000
	s_addc_u32 s21, s21, 0
	s_mov_b32 m0, s41
	v_lshl_add_u64 v[248:249], s[20:21], 0, v[134:135]
	ds_read_b128 v[214:217], v153 offset:32768
	ds_read_b128 v[218:221], v153 offset:33792
	ds_read_b128 v[222:225], v153 offset:34816
	ds_read_b128 v[226:229], v153 offset:35840
	ds_read_b128 v[230:233], v153 offset:36864
	ds_read_b128 v[234:237], v153 offset:37888
	ds_read_b128 v[238:241], v153 offset:38912
	ds_read_b128 v[242:245], v153 offset:39936
	global_load_lds_dwordx4 v[248:249], off
	v_lshl_add_u64 v[248:249], s[20:21], 0, v[138:139]
	s_mov_b32 m0, s39
	s_nop 0
	global_load_lds_dwordx4 v[248:249], off
	s_waitcnt vmcnt(8)
	s_waitcnt lgkmcnt(0)
	s_barrier
	s_setprio 1
	s_waitcnt lgkmcnt(0)
	v_mfma_f32_16x16x32_bf16 v[126:129], v[130:133], v[214:217], v[126:129]
	v_mfma_f32_16x16x32_bf16 v[122:125], v[176:179], v[214:217], v[122:125]
	v_mfma_f32_16x16x32_bf16 v[110:113], v[130:133], v[222:225], v[110:113]
	v_mfma_f32_16x16x32_bf16 v[106:109], v[176:179], v[222:225], v[106:109]
	v_mfma_f32_16x16x32_bf16 v[92:95], v[130:133], v[230:233], v[92:95]
	v_mfma_f32_16x16x32_bf16 v[88:91], v[176:179], v[230:233], v[88:91]
	v_mfma_f32_16x16x32_bf16 v[76:79], v[130:133], v[238:241], v[76:79]
	v_mfma_f32_16x16x32_bf16 v[72:75], v[176:179], v[238:241], v[72:75]
	v_mfma_f32_16x16x32_bf16 v[126:129], v[172:175], v[218:221], v[126:129]
	v_mfma_f32_16x16x32_bf16 v[122:125], v[180:183], v[218:221], v[122:125]
	v_mfma_f32_16x16x32_bf16 v[110:113], v[172:175], v[226:229], v[110:113]
	v_mfma_f32_16x16x32_bf16 v[106:109], v[180:183], v[226:229], v[106:109]
	v_mfma_f32_16x16x32_bf16 v[92:95], v[172:175], v[234:237], v[92:95]
	v_mfma_f32_16x16x32_bf16 v[88:91], v[180:183], v[234:237], v[88:91]
	v_mfma_f32_16x16x32_bf16 v[76:79], v[172:175], v[242:245], v[76:79]
	v_mfma_f32_16x16x32_bf16 v[72:75], v[180:183], v[242:245], v[72:75]
	s_setprio 0
	s_setprio 1
	v_mfma_f32_16x16x32_bf16 v[118:121], v[184:187], v[214:217], v[118:121]
	v_mfma_f32_16x16x32_bf16 v[114:117], v[206:209], v[214:217], v[114:117]
	v_mfma_f32_16x16x32_bf16 v[102:105], v[184:187], v[222:225], v[102:105]
	v_mfma_f32_16x16x32_bf16 v[98:101], v[206:209], v[222:225], v[98:101]
	v_mfma_f32_16x16x32_bf16 v[84:87], v[184:187], v[230:233], v[84:87]
	v_mfma_f32_16x16x32_bf16 v[80:83], v[206:209], v[230:233], v[80:83]
	v_mfma_f32_16x16x32_bf16 v[68:71], v[184:187], v[238:241], v[68:71]
	v_mfma_f32_16x16x32_bf16 v[64:67], v[206:209], v[238:241], v[64:67]
	v_mfma_f32_16x16x32_bf16 v[118:121], v[202:205], v[218:221], v[118:121]
	v_mfma_f32_16x16x32_bf16 v[114:117], v[210:213], v[218:221], v[114:117]
	v_mfma_f32_16x16x32_bf16 v[102:105], v[202:205], v[226:229], v[102:105]
	v_mfma_f32_16x16x32_bf16 v[98:101], v[210:213], v[226:229], v[98:101]
	v_mfma_f32_16x16x32_bf16 v[84:87], v[202:205], v[234:237], v[84:87]
	v_mfma_f32_16x16x32_bf16 v[80:83], v[210:213], v[234:237], v[80:83]
	v_mfma_f32_16x16x32_bf16 v[68:71], v[202:205], v[242:245], v[68:71]
	v_mfma_f32_16x16x32_bf16 v[64:67], v[210:213], v[242:245], v[64:67]
	s_setprio 0
	s_barrier
; #define PG8_STAGE(bufoff, gbase, voff) do { _Pragma("unroll") for (int _i = 0; _i < 2; ++_i) \
;         __builtin_amdgcn_global_load_lds((const unsigned*)((const char*)(gbase) + (voff)[_i]), (PG8_LAS unsigned*)(lds + (bufoff) + ldsw + _i * 8192), 16, 0, 0); } while (0)
; #define PG8_LDA(dst, b, h) do { _Pragma("unroll") for (int m = 0; m < 4; ++m) _Pragma("unroll") for (int k = 0; k < 2; ++k) dst[m][k] = *(const PG8_LAS bf16x8*)(lds + PG8_SA(b, h) + aoff + m * 2048 + k * 1024); } while (0)
; #define PG8_LDB(dst, b, h) do { _Pragma("unroll") for (int n = 0; n < 2; ++n) _Pragma("unroll") for (int k = 0; k < 2; ++k) dst[n][k] = *(const PG8_LAS bf16x8*)(lds + PG8_SB(b, h) + boff + n * 2048 + k * 1024); } while (0)
; #define PG8_MMA(ai, bj, At, Bt) do { __builtin_amdgcn_s_setprio(1); _Pragma("unroll") for (int m = 0; m < 4; ++m) _Pragma("unroll") for (int n = 0; n < 2; ++n) _Pragma("unroll") for (int k = 0; k < 2; ++k) \
;         acc[ai][bj][m][n] = __builtin_amdgcn_mfma_f32_16x16x32_bf16(Bt[n][k], At[m][k], acc[ai][bj][m][n], 0, 0, 0); __builtin_amdgcn_s_setprio(0); } while (0)
; #define PG8_BAR __builtin_amdgcn_s_barrier()
; template <class Epi, class Sched, bool ALIGN_EPI = false, bool SP2 = false>
; __device__ __forceinline__ void gemm_phase(PG8_LAS unsigned char* lds, const Gemm g, const Sched& S, const Epi& E, const int tid_in) {
;     ...
;             PG8_LDB(B0, 0, 0); PG8_LDB(B1, 0, 1); PG8_SCHED; PG8_LDA(At, 0, 0); PG8_STAGE(PG8_SA(1, 1), a1 + hstepA, voffA);
;             PG8_WAIT_V(8); PG8_WAIT_L(0); PG8_BAR; PG8_MMA(0, 0, At, B0); PG8_MMA(0, 1, At, B1); PG8_BAR; PG8_SCHED;
;             PG8_LDA(At, 0, 1); PG8_STAGE(PG8_SB(0, 0), b2, voffB); PG8_STAGE(PG8_SB(0, 1), b2 + hstepB, voffB); PG8_STAGE(PG8_SA(0, 0), a2, voffA);
;             PG8_WAIT_V(8); PG8_WAIT_L(0); PG8_BAR; PG8_MMA(1, 0, At, B0); PG8_MMA(1, 1, At, B1); PG8_BAR; PG8_SCHED;
;             PG8_LDB(B0, 1, 0); PG8_LDB(B1, 1, 1); PG8_SCHED; PG8_LDA(At, 1, 0); PG8_STAGE(PG8_SA(0, 1), a2 + hstepA, voffA);
;             PG8_WAIT_V(8); PG8_WAIT_L(0); PG8_BAR; PG8_MMA(0, 0, At, B0); PG8_MMA(0, 1, At, B1); PG8_BAR; PG8_SCHED;
;             PG8_LDA(At, 1, 1); PG8_STAGE(PG8_SB(1, 0), b3, voffB); PG8_STAGE(PG8_SB(1, 1), b3 + hstepB, voffB); PG8_STAGE(PG8_SA(1, 0), a3, voffA);
;             PG8_WAIT_V(8); PG8_WAIT_L(0); PG8_BAR; PG8_MMA(1, 0, At, B0); PG8_MMA(1, 1, At, B1); PG8_BAR; PG8_SCHED;
	s_add_i32 s20, s46, s22
	v_lshl_add_u64 v[146:147], v[146:147], 0, s[68:69]
	s_mov_b32 m0, s20
	ds_read_b128 v[214:217], v153 offset:49152
	ds_read_b128 v[218:221], v153 offset:50176
	ds_read_b128 v[222:225], v153 offset:51200
	ds_read_b128 v[226:229], v153 offset:52224
	ds_read_b128 v[230:233], v153 offset:53248
	ds_read_b128 v[234:237], v153 offset:54272
	ds_read_b128 v[238:241], v153 offset:55296
	ds_read_b128 v[242:245], v153 offset:56320
	global_load_lds_dwordx4 v[146:147], off
	s_add_i32 m0, s20, 0x2000
	s_add_u32 s18, s18, 0x40080
	v_lshl_add_u64 v[146:147], v[148:149], 0, s[68:69]
	s_addc_u32 s19, s19, 0
	s_add_i32 s20, s71, s22
	global_load_lds_dwordx4 v[146:147], off
	v_lshl_add_u64 v[146:147], s[18:19], 0, v[136:137]
	s_mov_b32 m0, s20
	s_nop 0
	global_load_lds_dwordx4 v[146:147], off
	v_lshl_add_u64 v[146:147], s[18:19], 0, v[140:141]
	s_add_i32 m0, s20, 0x2000
	s_nop 0
	global_load_lds_dwordx4 v[146:147], off
	v_lshl_add_u64 v[146:147], v[188:189], 0, s[68:69]
	s_mov_b32 m0, s95
	s_nop 0
	global_load_lds_dwordx4 v[146:147], off
	v_lshl_add_u64 v[146:147], v[246:247], 0, s[68:69]
	s_mov_b32 m0, s33
	s_nop 0
	global_load_lds_dwordx4 v[146:147], off
	s_waitcnt vmcnt(8)
	s_waitcnt lgkmcnt(0)
	s_barrier
	s_setprio 1
	s_waitcnt lgkmcnt(0)
	v_mfma_f32_16x16x32_bf16 v[60:63], v[130:133], v[214:217], v[60:63]
	v_mfma_f32_16x16x32_bf16 v[56:59], v[176:179], v[214:217], v[56:59]
	v_mfma_f32_16x16x32_bf16 v[44:47], v[130:133], v[222:225], v[44:47]
	v_mfma_f32_16x16x32_bf16 v[40:43], v[176:179], v[222:225], v[40:43]
	v_mfma_f32_16x16x32_bf16 v[28:31], v[130:133], v[230:233], v[28:31]
	v_mfma_f32_16x16x32_bf16 v[24:27], v[176:179], v[230:233], v[24:27]
	v_mfma_f32_16x16x32_bf16 v[12:15], v[130:133], v[238:241], v[12:15]
	v_mfma_f32_16x16x32_bf16 v[8:11], v[176:179], v[238:241], v[8:11]
	v_mfma_f32_16x16x32_bf16 v[60:63], v[172:175], v[218:221], v[60:63]
	v_mfma_f32_16x16x32_bf16 v[56:59], v[180:183], v[218:221], v[56:59]
	v_mfma_f32_16x16x32_bf16 v[44:47], v[172:175], v[226:229], v[44:47]
	v_mfma_f32_16x16x32_bf16 v[40:43], v[180:183], v[226:229], v[40:43]
	v_mfma_f32_16x16x32_bf16 v[28:31], v[172:175], v[234:237], v[28:31]
	v_mfma_f32_16x16x32_bf16 v[24:27], v[180:183], v[234:237], v[24:27]
	v_mfma_f32_16x16x32_bf16 v[12:15], v[172:175], v[242:245], v[12:15]
	v_mfma_f32_16x16x32_bf16 v[8:11], v[180:183], v[242:245], v[8:11]
	s_setprio 0
	s_setprio 1
	v_mfma_f32_16x16x32_bf16 v[52:55], v[184:187], v[214:217], v[52:55]
	v_mfma_f32_16x16x32_bf16 v[48:51], v[206:209], v[214:217], v[48:51]
	v_mfma_f32_16x16x32_bf16 v[36:39], v[184:187], v[222:225], v[36:39]
	v_mfma_f32_16x16x32_bf16 v[32:35], v[206:209], v[222:225], v[32:35]
	v_mfma_f32_16x16x32_bf16 v[20:23], v[184:187], v[230:233], v[20:23]
	v_mfma_f32_16x16x32_bf16 v[16:19], v[206:209], v[230:233], v[16:19]
	v_mfma_f32_16x16x32_bf16 v[4:7], v[184:187], v[238:241], v[4:7]
	v_mfma_f32_16x16x32_bf16 v[0:3], v[206:209], v[238:241], v[0:3]
	v_mfma_f32_16x16x32_bf16 v[52:55], v[202:205], v[218:221], v[52:55]
	v_mfma_f32_16x16x32_bf16 v[48:51], v[210:213], v[218:221], v[48:51]
	v_mfma_f32_16x16x32_bf16 v[36:39], v[202:205], v[226:229], v[36:39]
	v_mfma_f32_16x16x32_bf16 v[32:35], v[210:213], v[226:229], v[32:35]
	v_mfma_f32_16x16x32_bf16 v[20:23], v[202:205], v[234:237], v[20:23]
	v_mfma_f32_16x16x32_bf16 v[16:19], v[210:213], v[234:237], v[16:19]
	v_mfma_f32_16x16x32_bf16 v[4:7], v[202:205], v[242:245], v[4:7]
	v_mfma_f32_16x16x32_bf16 v[0:3], v[210:213], v[242:245], v[0:3]
	s_setprio 0
	s_barrier
	s_add_i32 s70, s70, 2
	s_add_u32 s16, s16, 0x100
	s_addc_u32 s17, s17, 0
	s_add_u32 s53, s53, 0x100
	s_addc_u32 s56, s56, 0
	s_cmp_gt_u32 s70, 13
	s_cbranch_scc0 .LBB0_1027
	v_readlane_b32 s16, v254, 57
	v_readlane_b32 s17, v254, 58
	s_and_b64 vcc, exec, s[16:17]
	s_cbranch_vccz .LBB0_1030
	s_barrier

; #define PG8_STAGE(bufoff, gbase, voff) do { _Pragma("unroll") for (int _i = 0; _i < 2; ++_i) \
;         __builtin_amdgcn_global_load_lds((const unsigned*)((const char*)(gbase) + (voff)[_i]), (PG8_LAS unsigned*)(lds + (bufoff) + ldsw + _i * 8192), 16, 0, 0); } while (0)
; #define PG8_LDA(dst, b, h) do { _Pragma("unroll") for (int m = 0; m < 4; ++m) _Pragma("unroll") for (int k = 0; k < 2; ++k) dst[m][k] = *(const PG8_LAS bf16x8*)(lds + PG8_SA(b, h) + aoff + m * 2048 + k * 1024); } while (0)
; #define PG8_LDB(dst, b, h) do { _Pragma("unroll") for (int n = 0; n < 2; ++n) _Pragma("unroll") for (int k = 0; k < 2; ++k) dst[n][k] = *(const PG8_LAS bf16x8*)(lds + PG8_SB(b, h) + boff + n * 2048 + k * 1024); } while (0)
; #define PG8_MMA(ai, bj, At, Bt) do { __builtin_amdgcn_s_setprio(1); _Pragma("unroll") for (int m = 0; m < 4; ++m) _Pragma("unroll") for (int n = 0; n < 2; ++n) _Pragma("unroll") for (int k = 0; k < 2; ++k) \
;         acc[ai][bj][m][n] = __builtin_amdgcn_mfma_f32_16x16x32_bf16(Bt[n][k], At[m][k], acc[ai][bj][m][n], 0, 0, 0); __builtin_amdgcn_s_setprio(0); } while (0)
; #define PG8_WAIT_V(n) asm volatile("s_waitcnt vmcnt(" #n ")" ::: "memory")
; #define PG8_BAR __builtin_amdgcn_s_barrier()
; template <class Epi, class Sched, bool ALIGN_EPI = false, bool SP2 = false>
; __device__ __forceinline__ void gemm_phase(PG8_LAS unsigned char* lds, const Gemm g, const Sched& S, const Epi& E, const int tid_in) {
;     ...
;         for (int t = 0; t < nt; t += 2) {
;             const bool last = (t == nt - 2);
;             const char* a1 = cA + (size_t)(t + 1) * kstep;
;             const char* a2 = last ? nA : cA + (size_t)(t + 2) * kstep; const char* b2 = last ? nB : cB + (size_t)(t + 2) * kstep;
;             const char* a3 = a2 + kstep; const char* b3 = b2 + kstep;
;             if (last && has_next) S.a_ready(nxt);
;             if constexpr (SP2) {
;             PG8_LDB(B0, 0, 0); PG8_LDB(B1, 0, 1); PG8_SCHED; PG8_LDA(At, 0, 0); PG8_STAGE(PG8_SA(1, 1), a1 + hstepA, voffA);
;             PG8_WAIT_V(8); PG8_WAIT_L(0); PG8_BAR; PG8_MMA(0, 0, At, B0); PG8_MMA(0, 1, At, B1); PG8_BAR; PG8_SCHED;
;             PG8_LDA(At, 0, 1); PG8_STAGE(PG8_SB(0, 0), b2, voffB); PG8_STAGE(PG8_SB(0, 1), b2 + hstepB, voffB); PG8_STAGE(PG8_SA(0, 0), a2, voffA);
;             PG8_WAIT_V(8); PG8_WAIT_L(0); PG8_BAR; PG8_MMA(1, 0, At, B0); PG8_MMA(1, 1, At, B1); PG8_BAR; PG8_SCHED;
.LBB0_1923:
	s_add_u32 s12, s10, 0x100
	s_addc_u32 s13, s11, 0
	s_add_i32 s46, 0, 0x10000
	s_cmp_eq_u32 s70, 40
	s_cselect_b32 s17, s5, s13
	s_cselect_b32 s16, s4, s12
	s_cselect_b32 s15, s9, s60
	s_cselect_b32 s14, s8, s55
	s_add_i32 s71, 0, 0x14000
	v_add_u32_e32 v92, s46, v165
	v_add_u32_e32 v162, s71, v165
	ds_read_b128 v[40:43], v92
	ds_read_b128 v[44:47], v92 offset:1024
	ds_read_b128 v[84:87], v92 offset:2048
	ds_read_b128 v[92:95], v92 offset:3072
	ds_read_b128 v[146:149], v162
	ds_read_b128 v[168:171], v162 offset:1024
	ds_read_b128 v[172:175], v162 offset:2048
	ds_read_b128 v[176:179], v162 offset:3072
	v_lshl_add_u64 v[162:163], s[10:11], 0, v[158:159]
	s_add_i32 m0, s28, 0xc000
	ds_read_b128 v[180:183], v166
	ds_read_b128 v[184:187], v166 offset:1024
	ds_read_b128 v[202:205], v166 offset:2048
	ds_read_b128 v[206:209], v166 offset:3072
	ds_read_b128 v[210:213], v166 offset:4096
	ds_read_b128 v[214:217], v166 offset:5120
	ds_read_b128 v[218:221], v166 offset:6144
	ds_read_b128 v[222:225], v166 offset:7168
	global_load_lds_dwordx4 v[162:163], off
	v_lshl_add_u64 v[162:163], s[10:11], 0, v[160:161]
	s_add_i32 m0, s28, 0xe000
	s_nop 0
	global_load_lds_dwordx4 v[162:163], off
	s_waitcnt vmcnt(8)
	s_waitcnt lgkmcnt(0)
	s_barrier
	s_setprio 1
	s_waitcnt lgkmcnt(0)
	v_mfma_f32_16x16x32_bf16 v[142:145], v[40:43], v[180:183], v[142:145]
	v_mfma_f32_16x16x32_bf16 v[138:141], v[84:87], v[180:183], v[138:141]
	v_mfma_f32_16x16x32_bf16 v[126:129], v[40:43], v[202:205], v[126:129]
	v_mfma_f32_16x16x32_bf16 v[122:125], v[84:87], v[202:205], v[122:125]
	v_mfma_f32_16x16x32_bf16 v[110:113], v[40:43], v[210:213], v[110:113]
	v_mfma_f32_16x16x32_bf16 v[106:109], v[84:87], v[210:213], v[106:109]
	v_mfma_f32_16x16x32_bf16 v[88:91], v[40:43], v[218:221], v[88:91]
	v_mfma_f32_16x16x32_bf16 v[80:83], v[84:87], v[218:221], v[80:83]
	v_mfma_f32_16x16x32_bf16 v[142:145], v[44:47], v[184:187], v[142:145]
	v_mfma_f32_16x16x32_bf16 v[138:141], v[92:95], v[184:187], v[138:141]
	v_mfma_f32_16x16x32_bf16 v[126:129], v[44:47], v[206:209], v[126:129]
	v_mfma_f32_16x16x32_bf16 v[122:125], v[92:95], v[206:209], v[122:125]
	v_mfma_f32_16x16x32_bf16 v[110:113], v[44:47], v[214:217], v[110:113]
	v_mfma_f32_16x16x32_bf16 v[106:109], v[92:95], v[214:217], v[106:109]
	v_mfma_f32_16x16x32_bf16 v[88:91], v[44:47], v[222:225], v[88:91]
	v_mfma_f32_16x16x32_bf16 v[80:83], v[92:95], v[222:225], v[80:83]
	s_setprio 0
	s_setprio 1
	v_mfma_f32_16x16x32_bf16 v[134:137], v[146:149], v[180:183], v[134:137]
	v_mfma_f32_16x16x32_bf16 v[130:133], v[172:175], v[180:183], v[130:133]
	v_mfma_f32_16x16x32_bf16 v[118:121], v[146:149], v[202:205], v[118:121]
	v_mfma_f32_16x16x32_bf16 v[114:117], v[172:175], v[202:205], v[114:117]
	v_mfma_f32_16x16x32_bf16 v[102:105], v[146:149], v[210:213], v[102:105]
	v_mfma_f32_16x16x32_bf16 v[98:101], v[172:175], v[210:213], v[98:101]
	v_mfma_f32_16x16x32_bf16 v[76:79], v[146:149], v[218:221], v[76:79]
	v_mfma_f32_16x16x32_bf16 v[72:75], v[172:175], v[218:221], v[72:75]
	v_mfma_f32_16x16x32_bf16 v[134:137], v[168:171], v[184:187], v[134:137]
	v_mfma_f32_16x16x32_bf16 v[130:133], v[176:179], v[184:187], v[130:133]
	v_mfma_f32_16x16x32_bf16 v[118:121], v[168:171], v[206:209], v[118:121]
	v_mfma_f32_16x16x32_bf16 v[114:117], v[176:179], v[206:209], v[114:117]
	v_mfma_f32_16x16x32_bf16 v[102:105], v[168:171], v[214:217], v[102:105]
	v_mfma_f32_16x16x32_bf16 v[98:101], v[176:179], v[214:217], v[98:101]
	v_mfma_f32_16x16x32_bf16 v[76:79], v[168:171], v[222:225], v[76:79]
	v_mfma_f32_16x16x32_bf16 v[72:75], v[176:179], v[222:225], v[72:75]
	s_setprio 0
	s_barrier
	s_add_i32 s10, s46, s23
	v_lshl_add_u64 v[162:163], s[14:15], 0, v[152:153]
	s_mov_b32 m0, s10
	ds_read_b128 v[180:183], v166 offset:16384
	ds_read_b128 v[184:187], v166 offset:17408
	ds_read_b128 v[202:205], v166 offset:18432
	ds_read_b128 v[206:209], v166 offset:19456
	ds_read_b128 v[210:213], v166 offset:20480
	ds_read_b128 v[214:217], v166 offset:21504
	ds_read_b128 v[218:221], v166 offset:22528
	ds_read_b128 v[222:225], v166 offset:23552
	global_load_lds_dwordx4 v[162:163], off
	s_add_i32 m0, s10, 0x2000
	s_add_u32 s10, s14, 0xb0000
	v_lshl_add_u64 v[188:189], s[14:15], 0, v[156:157]
	s_addc_u32 s11, s15, 0
	s_add_i32 s46, s71, s23
	global_load_lds_dwordx4 v[188:189], off
	v_lshl_add_u64 v[190:191], s[10:11], 0, v[152:153]
	s_mov_b32 m0, s46
	global_load_lds_dwordx4 v[190:191], off
	v_lshl_add_u64 v[190:191], s[10:11], 0, v[156:157]
	s_add_i32 m0, s46, 0x2000
	s_nop 0
	global_load_lds_dwordx4 v[190:191], off
	s_waitcnt vmcnt(6)
	s_waitcnt lgkmcnt(0)
	s_barrier
; #define PG8_STAGE(bufoff, gbase, voff) do { _Pragma("unroll") for (int _i = 0; _i < 2; ++_i) \
;         __builtin_amdgcn_global_load_lds((const unsigned*)((const char*)(gbase) + (voff)[_i]), (PG8_LAS unsigned*)(lds + (bufoff) + ldsw + _i * 8192), 16, 0, 0); } while (0)
; #define PG8_LDA(dst, b, h) do { _Pragma("unroll") for (int m = 0; m < 4; ++m) _Pragma("unroll") for (int k = 0; k < 2; ++k) dst[m][k] = *(const PG8_LAS bf16x8*)(lds + PG8_SA(b, h) + aoff + m * 2048 + k * 1024); } while (0)
; #define PG8_LDB(dst, b, h) do { _Pragma("unroll") for (int n = 0; n < 2; ++n) _Pragma("unroll") for (int k = 0; k < 2; ++k) dst[n][k] = *(const PG8_LAS bf16x8*)(lds + PG8_SB(b, h) + boff + n * 2048 + k * 1024); } while (0)
; #define PG8_MMA(ai, bj, At, Bt) do { __builtin_amdgcn_s_setprio(1); _Pragma("unroll") for (int m = 0; m < 4; ++m) _Pragma("unroll") for (int n = 0; n < 2; ++n) _Pragma("unroll") for (int k = 0; k < 2; ++k) \
;         acc[ai][bj][m][n] = __builtin_amdgcn_mfma_f32_16x16x32_bf16(Bt[n][k], At[m][k], acc[ai][bj][m][n], 0, 0, 0); __builtin_amdgcn_s_setprio(0); } while (0)
; #define PG8_WAIT_V(n) asm volatile("s_waitcnt vmcnt(" #n ")" ::: "memory")
; #define PG8_WAIT_L(n) asm volatile("s_waitcnt lgkmcnt(" #n ")" ::: "memory")
; #define PG8_BAR __builtin_amdgcn_s_barrier()
; #define PG8_SCHED __builtin_amdgcn_sched_barrier(0)
; template <class Epi, class Sched, bool ALIGN_EPI = false, bool SP2 = false>
; __device__ __forceinline__ void gemm_phase(PG8_LAS unsigned char* lds, const Gemm g, const Sched& S, const Epi& E, const int tid_in) {
;     ...
;             PG8_WAIT_V(8); PG8_WAIT_L(0); PG8_BAR; PG8_MMA(1, 0, At, B0); PG8_MMA(1, 1, At, B1); PG8_BAR; PG8_SCHED;
;             PG8_LDB(B0, 1, 0); PG8_LDB(B1, 1, 1); PG8_SCHED; PG8_LDA(At, 1, 0); PG8_STAGE(PG8_SA(0, 1), a2 + hstepA, voffA);
;             PG8_WAIT_V(8); PG8_WAIT_L(0); PG8_BAR; PG8_MMA(0, 0, At, B0); PG8_MMA(0, 1, At, B1); PG8_BAR; PG8_SCHED;
	s_setprio 1
	s_waitcnt lgkmcnt(0)
	v_mfma_f32_16x16x32_bf16 v[68:71], v[40:43], v[180:183], v[68:71]
	v_mfma_f32_16x16x32_bf16 v[64:67], v[84:87], v[180:183], v[64:67]
	v_mfma_f32_16x16x32_bf16 v[52:55], v[40:43], v[202:205], v[52:55]
	v_mfma_f32_16x16x32_bf16 v[48:51], v[84:87], v[202:205], v[48:51]
	v_mfma_f32_16x16x32_bf16 v[28:31], v[40:43], v[210:213], v[28:31]
	v_mfma_f32_16x16x32_bf16 v[24:27], v[84:87], v[210:213], v[24:27]
	v_mfma_f32_16x16x32_bf16 v[12:15], v[40:43], v[218:221], v[12:15]
	v_mfma_f32_16x16x32_bf16 v[8:11], v[84:87], v[218:221], v[8:11]
	v_mfma_f32_16x16x32_bf16 v[68:71], v[44:47], v[184:187], v[68:71]
	v_mfma_f32_16x16x32_bf16 v[64:67], v[92:95], v[184:187], v[64:67]
	v_mfma_f32_16x16x32_bf16 v[52:55], v[44:47], v[206:209], v[52:55]
	v_mfma_f32_16x16x32_bf16 v[48:51], v[92:95], v[206:209], v[48:51]
	v_mfma_f32_16x16x32_bf16 v[28:31], v[44:47], v[214:217], v[28:31]
	v_mfma_f32_16x16x32_bf16 v[24:27], v[92:95], v[214:217], v[24:27]
	v_mfma_f32_16x16x32_bf16 v[12:15], v[44:47], v[222:225], v[12:15]
	v_mfma_f32_16x16x32_bf16 v[8:11], v[92:95], v[222:225], v[8:11]
	s_setprio 0
	s_setprio 1
	v_mfma_f32_16x16x32_bf16 v[36:39], v[146:149], v[202:205], v[36:39]
	v_mfma_f32_16x16x32_bf16 v[32:35], v[172:175], v[202:205], v[32:35]
	v_mfma_f32_16x16x32_bf16 v[20:23], v[146:149], v[210:213], v[20:23]
	v_mfma_f32_16x16x32_bf16 v[16:19], v[172:175], v[210:213], v[16:19]
	v_mfma_f32_16x16x32_bf16 v[4:7], v[146:149], v[218:221], v[4:7]
	v_mfma_f32_16x16x32_bf16 v[0:3], v[172:175], v[218:221], v[0:3]
	v_mfma_f32_16x16x32_bf16 v[40:43], v[146:149], v[180:183], v[60:63]
	v_mfma_f32_16x16x32_bf16 v[44:47], v[172:175], v[180:183], v[56:59]
	v_mfma_f32_16x16x32_bf16 v[36:39], v[168:171], v[206:209], v[36:39]
	v_mfma_f32_16x16x32_bf16 v[32:35], v[176:179], v[206:209], v[32:35]
	v_mfma_f32_16x16x32_bf16 v[20:23], v[168:171], v[214:217], v[20:23]
	v_mfma_f32_16x16x32_bf16 v[16:19], v[176:179], v[214:217], v[16:19]
	v_mfma_f32_16x16x32_bf16 v[4:7], v[168:171], v[222:225], v[4:7]
	v_mfma_f32_16x16x32_bf16 v[0:3], v[176:179], v[222:225], v[0:3]
	v_mfma_f32_16x16x32_bf16 v[40:43], v[168:171], v[184:187], v[40:43]
	v_mfma_f32_16x16x32_bf16 v[44:47], v[176:179], v[184:187], v[44:47]
	s_setprio 0
	s_barrier
	v_lshl_add_u64 v[190:191], s[16:17], 0, v[150:151]
	v_lshl_add_u64 v[192:193], s[16:17], 0, v[154:155]
	s_mov_b32 m0, s28
	s_nop 0
	global_load_lds_dwordx4 v[190:191], off
	s_mov_b32 m0, s29
	s_nop 0
	global_load_lds_dwordx4 v[192:193], off
	s_add_i32 s46, 0, 0x18000
	s_add_i32 s71, 0, 0x1c000
	v_add_u32_e32 v92, s46, v165
	v_add_u32_e32 v167, s71, v165
	ds_read_b128 v[56:59], v92
	ds_read_b128 v[60:63], v92 offset:1024
	ds_read_b128 v[84:87], v92 offset:2048
	ds_read_b128 v[92:95], v92 offset:3072
	ds_read_b128 v[146:149], v167
	ds_read_b128 v[168:171], v167 offset:1024
	ds_read_b128 v[172:175], v167 offset:2048
	ds_read_b128 v[176:179], v167 offset:3072
	s_add_u32 s10, s16, 0xb0000
	s_addc_u32 s11, s17, 0
	s_mov_b32 m0, s30
	v_lshl_add_u64 v[198:199], s[10:11], 0, v[150:151]
	ds_read_b128 v[180:183], v166 offset:32768
	ds_read_b128 v[184:187], v166 offset:33792
	ds_read_b128 v[202:205], v166 offset:34816
	ds_read_b128 v[206:209], v166 offset:35840
	ds_read_b128 v[210:213], v166 offset:36864
	ds_read_b128 v[214:217], v166 offset:37888
	ds_read_b128 v[218:221], v166 offset:38912
	ds_read_b128 v[222:225], v166 offset:39936
	global_load_lds_dwordx4 v[198:199], off
	v_lshl_add_u64 v[198:199], s[10:11], 0, v[154:155]
	s_mov_b32 m0, s31
	s_nop 0
	global_load_lds_dwordx4 v[198:199], off
	s_waitcnt vmcnt(8)
	s_waitcnt lgkmcnt(0)
	s_barrier
	s_setprio 1
	s_waitcnt lgkmcnt(0)
	v_mfma_f32_16x16x32_bf16 v[142:145], v[56:59], v[180:183], v[142:145]
	v_mfma_f32_16x16x32_bf16 v[138:141], v[84:87], v[180:183], v[138:141]
	v_mfma_f32_16x16x32_bf16 v[126:129], v[56:59], v[202:205], v[126:129]
	v_mfma_f32_16x16x32_bf16 v[122:125], v[84:87], v[202:205], v[122:125]
	v_mfma_f32_16x16x32_bf16 v[110:113], v[56:59], v[210:213], v[110:113]
	v_mfma_f32_16x16x32_bf16 v[106:109], v[84:87], v[210:213], v[106:109]
	v_mfma_f32_16x16x32_bf16 v[88:91], v[56:59], v[218:221], v[88:91]
	v_mfma_f32_16x16x32_bf16 v[80:83], v[84:87], v[218:221], v[80:83]
	v_mfma_f32_16x16x32_bf16 v[142:145], v[60:63], v[184:187], v[142:145]
	v_mfma_f32_16x16x32_bf16 v[138:141], v[92:95], v[184:187], v[138:141]
	v_mfma_f32_16x16x32_bf16 v[126:129], v[60:63], v[206:209], v[126:129]
	v_mfma_f32_16x16x32_bf16 v[122:125], v[92:95], v[206:209], v[122:125]
	v_mfma_f32_16x16x32_bf16 v[110:113], v[60:63], v[214:217], v[110:113]
	v_mfma_f32_16x16x32_bf16 v[106:109], v[92:95], v[214:217], v[106:109]
	v_mfma_f32_16x16x32_bf16 v[88:91], v[60:63], v[222:225], v[88:91]
	v_mfma_f32_16x16x32_bf16 v[80:83], v[92:95], v[222:225], v[80:83]
	s_setprio 0
	s_setprio 1
	v_mfma_f32_16x16x32_bf16 v[134:137], v[146:149], v[180:183], v[134:137]
	v_mfma_f32_16x16x32_bf16 v[130:133], v[172:175], v[180:183], v[130:133]
	v_mfma_f32_16x16x32_bf16 v[118:121], v[146:149], v[202:205], v[118:121]
	v_mfma_f32_16x16x32_bf16 v[114:117], v[172:175], v[202:205], v[114:117]
	v_mfma_f32_16x16x32_bf16 v[102:105], v[146:149], v[210:213], v[102:105]
	v_mfma_f32_16x16x32_bf16 v[98:101], v[172:175], v[210:213], v[98:101]
	v_mfma_f32_16x16x32_bf16 v[76:79], v[146:149], v[218:221], v[76:79]
	v_mfma_f32_16x16x32_bf16 v[72:75], v[172:175], v[218:221], v[72:75]
	v_mfma_f32_16x16x32_bf16 v[134:137], v[168:171], v[184:187], v[134:137]
	v_mfma_f32_16x16x32_bf16 v[130:133], v[176:179], v[184:187], v[130:133]
	v_mfma_f32_16x16x32_bf16 v[118:121], v[168:171], v[206:209], v[118:121]
	v_mfma_f32_16x16x32_bf16 v[114:117], v[176:179], v[206:209], v[114:117]
	v_mfma_f32_16x16x32_bf16 v[102:105], v[168:171], v[214:217], v[102:105]
	v_mfma_f32_16x16x32_bf16 v[98:101], v[176:179], v[214:217], v[98:101]
	v_mfma_f32_16x16x32_bf16 v[76:79], v[168:171], v[222:225], v[76:79]
	v_mfma_f32_16x16x32_bf16 v[72:75], v[176:179], v[222:225], v[72:75]
	s_setprio 0
	s_barrier
; #define PG8_STAGE(bufoff, gbase, voff) do { _Pragma("unroll") for (int _i = 0; _i < 2; ++_i) \
;         __builtin_amdgcn_global_load_lds((const unsigned*)((const char*)(gbase) + (voff)[_i]), (PG8_LAS unsigned*)(lds + (bufoff) + ldsw + _i * 8192), 16, 0, 0); } while (0)
; #define PG8_LDA(dst, b, h) do { _Pragma("unroll") for (int m = 0; m < 4; ++m) _Pragma("unroll") for (int k = 0; k < 2; ++k) dst[m][k] = *(const PG8_LAS bf16x8*)(lds + PG8_SA(b, h) + aoff + m * 2048 + k * 1024); } while (0)
; #define PG8_LDB(dst, b, h) do { _Pragma("unroll") for (int n = 0; n < 2; ++n) _Pragma("unroll") for (int k = 0; k < 2; ++k) dst[n][k] = *(const PG8_LAS bf16x8*)(lds + PG8_SB(b, h) + boff + n * 2048 + k * 1024); } while (0)
; #define PG8_MMA(ai, bj, At, Bt) do { __builtin_amdgcn_s_setprio(1); _Pragma("unroll") for (int m = 0; m < 4; ++m) _Pragma("unroll") for (int n = 0; n < 2; ++n) _Pragma("unroll") for (int k = 0; k < 2; ++k) \
;         acc[ai][bj][m][n] = __builtin_amdgcn_mfma_f32_16x16x32_bf16(Bt[n][k], At[m][k], acc[ai][bj][m][n], 0, 0, 0); __builtin_amdgcn_s_setprio(0); } while (0)
; #define PG8_WAIT_V(n) asm volatile("s_waitcnt vmcnt(" #n ")" ::: "memory")
; #define PG8_WAIT_L(n) asm volatile("s_waitcnt lgkmcnt(" #n ")" ::: "memory")
; #define PG8_BAR __builtin_amdgcn_s_barrier()
; #define PG8_SCHED __builtin_amdgcn_sched_barrier(0)
; template <class Epi, class Sched, bool ALIGN_EPI = false, bool SP2 = false>
; __device__ __forceinline__ void gemm_phase(PG8_LAS unsigned char* lds, const Gemm g, const Sched& S, const Epi& E, const int tid_in) {
;     ...
;             PG8_LDB(B0, 1, 0); PG8_LDB(B1, 1, 1); PG8_SCHED; PG8_LDA(At, 1, 0); PG8_STAGE(PG8_SA(0, 1), a2 + hstepA, voffA);
;             PG8_WAIT_V(8); PG8_WAIT_L(0); PG8_BAR; PG8_MMA(0, 0, At, B0); PG8_MMA(0, 1, At, B1); PG8_BAR; PG8_SCHED;
;             PG8_LDA(At, 1, 1); PG8_STAGE(PG8_SB(1, 0), b3, voffB); PG8_STAGE(PG8_SB(1, 1), b3 + hstepB, voffB); PG8_STAGE(PG8_SA(1, 0), a3, voffA);
;             PG8_WAIT_V(8); PG8_WAIT_L(0); PG8_BAR; PG8_MMA(1, 0, At, B0); PG8_MMA(1, 1, At, B1); PG8_BAR; PG8_SCHED;
	s_add_i32 s10, s46, s23
	v_lshl_add_u64 v[162:163], v[162:163], 0, s[68:69]
	s_mov_b32 m0, s10
	ds_read_b128 v[180:183], v166 offset:49152
	ds_read_b128 v[184:187], v166 offset:50176
	ds_read_b128 v[202:205], v166 offset:51200
	ds_read_b128 v[206:209], v166 offset:52224
	ds_read_b128 v[210:213], v166 offset:53248
	ds_read_b128 v[214:217], v166 offset:54272
	ds_read_b128 v[218:221], v166 offset:55296
	ds_read_b128 v[222:225], v166 offset:56320
	global_load_lds_dwordx4 v[162:163], off
	s_add_i32 m0, s10, 0x2000
	s_add_u32 s10, s14, 0xb0080
	v_lshl_add_u64 v[162:163], v[188:189], 0, s[68:69]
	s_addc_u32 s11, s15, 0
	s_add_i32 s14, s71, s23
	global_load_lds_dwordx4 v[162:163], off
	v_lshl_add_u64 v[162:163], s[10:11], 0, v[152:153]
	s_mov_b32 m0, s14
	s_nop 0
	global_load_lds_dwordx4 v[162:163], off
	v_lshl_add_u64 v[162:163], s[10:11], 0, v[156:157]
	s_add_i32 m0, s14, 0x2000
	s_nop 0
	global_load_lds_dwordx4 v[162:163], off
	v_lshl_add_u64 v[162:163], v[190:191], 0, s[68:69]
	s_mov_b32 m0, s40
	s_nop 0
	global_load_lds_dwordx4 v[162:163], off
	v_lshl_add_u64 v[162:163], v[192:193], 0, s[68:69]
	s_mov_b32 m0, s41
	s_nop 0
	global_load_lds_dwordx4 v[162:163], off
	s_waitcnt vmcnt(8)
	s_waitcnt lgkmcnt(0)
	s_barrier
	s_setprio 1
	s_waitcnt lgkmcnt(0)
	v_mfma_f32_16x16x32_bf16 v[68:71], v[56:59], v[180:183], v[68:71]
	v_mfma_f32_16x16x32_bf16 v[64:67], v[84:87], v[180:183], v[64:67]
	v_mfma_f32_16x16x32_bf16 v[52:55], v[56:59], v[202:205], v[52:55]
	v_mfma_f32_16x16x32_bf16 v[48:51], v[84:87], v[202:205], v[48:51]
	v_mfma_f32_16x16x32_bf16 v[28:31], v[56:59], v[210:213], v[28:31]
	v_mfma_f32_16x16x32_bf16 v[24:27], v[84:87], v[210:213], v[24:27]
	v_mfma_f32_16x16x32_bf16 v[12:15], v[56:59], v[218:221], v[12:15]
	v_mfma_f32_16x16x32_bf16 v[8:11], v[84:87], v[218:221], v[8:11]
	v_mfma_f32_16x16x32_bf16 v[68:71], v[60:63], v[184:187], v[68:71]
	v_mfma_f32_16x16x32_bf16 v[64:67], v[92:95], v[184:187], v[64:67]
	v_mfma_f32_16x16x32_bf16 v[52:55], v[60:63], v[206:209], v[52:55]
	v_mfma_f32_16x16x32_bf16 v[48:51], v[92:95], v[206:209], v[48:51]
	v_mfma_f32_16x16x32_bf16 v[28:31], v[60:63], v[214:217], v[28:31]
	v_mfma_f32_16x16x32_bf16 v[24:27], v[92:95], v[214:217], v[24:27]
	v_mfma_f32_16x16x32_bf16 v[12:15], v[60:63], v[222:225], v[12:15]
	v_mfma_f32_16x16x32_bf16 v[8:11], v[92:95], v[222:225], v[8:11]
	s_setprio 0
	s_setprio 1
	v_mfma_f32_16x16x32_bf16 v[40:43], v[146:149], v[180:183], v[40:43]
	v_mfma_f32_16x16x32_bf16 v[60:63], v[168:171], v[184:187], v[40:43]
	v_mfma_f32_16x16x32_bf16 v[40:43], v[172:175], v[180:183], v[44:47]
	v_mfma_f32_16x16x32_bf16 v[36:39], v[146:149], v[202:205], v[36:39]
	v_mfma_f32_16x16x32_bf16 v[32:35], v[172:175], v[202:205], v[32:35]
	v_mfma_f32_16x16x32_bf16 v[20:23], v[146:149], v[210:213], v[20:23]
	v_mfma_f32_16x16x32_bf16 v[16:19], v[172:175], v[210:213], v[16:19]
	v_mfma_f32_16x16x32_bf16 v[4:7], v[146:149], v[218:221], v[4:7]
	v_mfma_f32_16x16x32_bf16 v[0:3], v[172:175], v[218:221], v[0:3]
	v_mfma_f32_16x16x32_bf16 v[56:59], v[176:179], v[184:187], v[40:43]
	v_mfma_f32_16x16x32_bf16 v[36:39], v[168:171], v[206:209], v[36:39]
	v_mfma_f32_16x16x32_bf16 v[32:35], v[176:179], v[206:209], v[32:35]
	v_mfma_f32_16x16x32_bf16 v[20:23], v[168:171], v[214:217], v[20:23]
	v_mfma_f32_16x16x32_bf16 v[16:19], v[176:179], v[214:217], v[16:19]
	v_mfma_f32_16x16x32_bf16 v[4:7], v[168:171], v[222:225], v[4:7]
	v_mfma_f32_16x16x32_bf16 v[0:3], v[176:179], v[222:225], v[0:3]
	s_setprio 0
	s_barrier
	s_add_i32 s70, s70, 2
	s_add_u32 s55, s55, 0x100
	s_addc_u32 s60, s60, 0
	s_cmp_gt_u32 s70, 41
	s_mov_b64 s[10:11], s[12:13]
	s_cbranch_scc0 .LBB0_1923
	s_and_b64 vcc, exec, s[2:3]
	s_cbranch_vccz .LBB0_1926
	s_barrier
